# v12: v9 + all 32 value-row loads issued at the end of the score section (before the softmax barrier)
# baseline (speedup 1.0000x reference)
; DI void attn_sample_item(const Params& p, int item, ldsp lds, int tid_) {
;     ...
;   for (int t = 0; t < 4; ++t) { f32x4 a = {0.f, 0.f, 0.f, 0.f}; const float* pp = (const float*)(p.ws + B_PART) + (size_t)(b * 4 + t) * 1024 + h * 256 + lane * 4;
; #pragma unroll
;     for (int kp = 0; kp < 4; ++kp) a += *(const f32x4*)(pp + (size_t)kp * 512 * 1024);
;     q[t][0] = a[0] * 0.0625f; q[t][1] = a[1] * 0.0625f; q[t][2] = a[2] * 0.0625f; q[t][3] = a[3] * 0.0625f; }
;   const bool b0 = lane & 1, b1 = lane & 2;
;   f32x4 kvA[16], kvB[16];
; #pragma unroll
;   for (int j = 0; j < 16; ++j) kvA[j] = __builtin_nontemporal_load((const f32x4*)(ck + (size_t)(wid * 32 + j) * 1024 + lane * 4));
; #pragma unroll
;   for (int j = 0; j < 16; ++j) kvB[j] = __builtin_nontemporal_load((const f32x4*)(ck + (size_t)(wid * 32 + 16 + j) * 1024 + lane * 4));
.LBB0_1604:
	s_ashr_i32 s4, s40, 2
	s_ashr_i32 s5, s4, 31
	s_lshl_b64 s[4:5], s[4:5], 18
	s_and_b32 s26, s0, 0x300
	v_mov_b32_e32 v222, v212
	s_or_b32 s4, s4, s26
	s_and_b32 s28, s40, -4
	s_lshl_b32 s6, s26, 2
	s_add_u32 s6, s36, s6
	v_and_b32_e32 v223, 63, v222
	s_addc_u32 s7, s37, 0
	v_lshlrev_b32_e32 v144, 4, v223
	s_ashr_i32 s29, s28, 31
	v_lshl_add_u64 v[48:49], s[6:7], 0, v[144:145]
	s_lshl_b64 s[6:7], s[28:29], 12
	v_lshl_add_u64 v[8:9], v[48:49], 0, s[6:7]
	v_add_co_u32_e32 v4, vcc, s3, v8
	s_or_b32 s6, s28, 1
	s_nop 0
	v_addc_co_u32_e32 v5, vcc, 0, v9, vcc
	v_add_co_u32_e32 v10, vcc, s33, v8
	s_ashr_i32 s7, s6, 31
	s_nop 0
	v_addc_co_u32_e32 v11, vcc, 0, v9, vcc
	v_add_co_u32_e32 v12, vcc, s38, v8
	s_lshl_b64 s[6:7], s[6:7], 12
	s_nop 0
	v_addc_co_u32_e32 v13, vcc, 0, v9, vcc
	v_lshl_add_u64 v[24:25], v[48:49], 0, s[6:7]
	v_add_co_u32_e32 v20, vcc, s3, v24
	s_or_b32 s6, s28, 2
	s_nop 0
	v_addc_co_u32_e32 v21, vcc, 0, v25, vcc
	v_add_co_u32_e32 v26, vcc, s33, v24
	s_ashr_i32 s7, s6, 31
	s_nop 0
	v_addc_co_u32_e32 v27, vcc, 0, v25, vcc
	v_add_co_u32_e32 v28, vcc, s38, v24
	s_lshl_b64 s[6:7], s[6:7], 12
	global_load_dwordx4 v[0:3], v[8:9], off
	s_nop 0
	global_load_dwordx4 v[4:7], v[4:5], off
	v_addc_co_u32_e32 v29, vcc, 0, v25, vcc
	v_lshl_add_u64 v[44:45], v[48:49], 0, s[6:7]
	global_load_dwordx4 v[8:11], v[10:11], off
	s_nop 0
	global_load_dwordx4 v[12:15], v[12:13], off
	s_nop 0
	global_load_dwordx4 v[16:19], v[24:25], off
	s_nop 0
	global_load_dwordx4 v[20:23], v[20:21], off
	v_add_co_u32_e32 v36, vcc, s3, v44
	global_load_dwordx4 v[24:27], v[26:27], off
	s_nop 0
	global_load_dwordx4 v[28:31], v[28:29], off
	v_addc_co_u32_e32 v37, vcc, 0, v45, vcc
	v_add_co_u32_e32 v40, vcc, s33, v44
	global_load_dwordx4 v[32:35], v[44:45], off
	s_nop 0
	global_load_dwordx4 v[36:39], v[36:37], off
	v_addc_co_u32_e32 v41, vcc, 0, v45, vcc
	v_add_co_u32_e32 v44, vcc, s38, v44
	global_load_dwordx4 v[40:43], v[40:41], off
	s_nop 0
	v_addc_co_u32_e32 v45, vcc, 0, v45, vcc
	global_load_dwordx4 v[44:47], v[44:45], off
	s_or_b32 s6, s40, 3
	s_ashr_i32 s7, s6, 31
	s_lshl_b64 s[6:7], s[6:7], 12
	s_lshl_b64 s[30:31], s[4:5], 2
	s_add_u32 s4, s12, s30
	s_addc_u32 s5, s13, s31
	s_waitcnt vmcnt(11)
	v_pk_add_f32 v[2:3], v[2:3], 0 op_sel_hi:[1,0]
	v_pk_add_f32 v[0:1], v[0:1], 0 op_sel_hi:[1,0]
	s_waitcnt vmcnt(10)
	v_pk_add_f32 v[2:3], v[2:3], v[6:7]
	v_pk_add_f32 v[0:1], v[0:1], v[4:5]
	s_waitcnt vmcnt(9)
	v_pk_add_f32 v[2:3], v[2:3], v[10:11]
	s_waitcnt vmcnt(7)
	v_pk_add_f32 v[4:5], v[18:19], 0 op_sel_hi:[1,0]
	v_pk_add_f32 v[6:7], v[16:17], 0 op_sel_hi:[1,0]
	v_pk_add_f32 v[0:1], v[0:1], v[8:9]
	s_waitcnt vmcnt(6)
	v_pk_add_f32 v[4:5], v[4:5], v[22:23]
	v_pk_add_f32 v[6:7], v[6:7], v[20:21]
	v_pk_add_f32 v[2:3], v[2:3], v[14:15]
	v_pk_add_f32 v[0:1], v[0:1], v[12:13]
	s_waitcnt vmcnt(5)
	v_pk_add_f32 v[4:5], v[4:5], v[26:27]
	v_pk_add_f32 v[6:7], v[6:7], v[24:25]
	v_mul_f32_e32 v228, 0x3d800000, v0
	v_mul_f32_e32 v231, 0x3d800000, v1
	v_mul_f32_e32 v229, 0x3d800000, v2
	v_mul_f32_e32 v225, 0x3d800000, v3
	s_waitcnt vmcnt(4)
	v_pk_add_f32 v[0:1], v[4:5], v[30:31]
	v_pk_add_f32 v[2:3], v[6:7], v[28:29]
	v_mul_f32_e32 v227, 0x3d800000, v0
	v_mul_f32_e32 v226, 0x3d800000, v2
	v_mul_f32_e32 v230, 0x3d800000, v3
	v_mul_f32_e32 v224, 0x3d800000, v1
	s_waitcnt vmcnt(3)
	v_pk_add_f32 v[0:1], v[34:35], 0 op_sel_hi:[1,0]
	v_pk_add_f32 v[2:3], v[32:33], 0 op_sel_hi:[1,0]
	s_waitcnt vmcnt(2)
	v_pk_add_f32 v[0:1], v[0:1], v[38:39]
	v_pk_add_f32 v[2:3], v[2:3], v[36:37]
	s_waitcnt vmcnt(1)
	v_pk_add_f32 v[0:1], v[0:1], v[42:43]
	v_pk_add_f32 v[2:3], v[2:3], v[40:41]
	s_waitcnt vmcnt(0)
	v_pk_add_f32 v[210:211], v[0:1], v[46:47]
	v_pk_add_f32 v[0:1], v[2:3], v[44:45]
	v_mul_f32_e32 v233, 0x3d800000, v210
	v_mul_f32_e32 v232, 0x3d800000, v0
	v_mul_f32_e32 v234, 0x3d800000, v1
	v_lshl_add_u64 v[0:1], v[48:49], 0, s[6:7]
	v_add_co_u32_e32 v2, vcc, s3, v0
	v_ashrrev_i32_e32 v210, 6, v222
	s_nop 0
	v_addc_co_u32_e32 v3, vcc, 0, v1, vcc
	global_load_dwordx4 v[128:131], v[0:1], off
	global_load_dwordx4 v[132:135], v[2:3], off
	v_add_co_u32_e32 v2, vcc, s33, v0
	v_mul_f32_e32 v211, 0x3d800000, v211
	s_nop 0
	v_addc_co_u32_e32 v3, vcc, 0, v1, vcc
	v_add_co_u32_e32 v0, vcc, s38, v0
	v_cmp_lt_i32_e64 s[6:7], v218, v216
	s_nop 0
	v_addc_co_u32_e32 v1, vcc, 0, v1, vcc
	global_load_dwordx4 v[136:139], v[2:3], off
	global_load_dwordx4 v[140:143], v[0:1], off
	v_lshlrev_b32_e32 v0, 5, v210
	v_ashrrev_i32_e32 v1, 31, v0
	v_or_b32_e32 v6, 1, v0
	v_lshl_add_u64 v[2:3], s[4:5], 0, v[144:145]
	v_lshlrev_b64 v[162:163], 12, v[0:1]
	v_ashrrev_i32_e32 v7, 31, v6
	v_lshl_add_u64 v[4:5], v[2:3], 0, v[162:163]
	v_lshlrev_b64 v[166:167], 12, v[6:7]
	v_lshl_add_u64 v[6:7], v[2:3], 0, v[166:167]
	global_load_dwordx4 v[124:127], v[4:5], off nt
	global_load_dwordx4 v[120:123], v[6:7], off nt
	v_or_b32_e32 v4, 2, v0
	v_ashrrev_i32_e32 v5, 31, v4
	v_or_b32_e32 v6, 3, v0
	v_lshlrev_b64 v[168:169], 12, v[4:5]
	v_ashrrev_i32_e32 v7, 31, v6
	v_lshl_add_u64 v[4:5], v[2:3], 0, v[168:169]
	v_lshlrev_b64 v[172:173], 12, v[6:7]
	v_lshl_add_u64 v[6:7], v[2:3], 0, v[172:173]
	global_load_dwordx4 v[116:119], v[4:5], off nt
	global_load_dwordx4 v[112:115], v[6:7], off nt
	v_or_b32_e32 v4, 4, v0
	v_ashrrev_i32_e32 v5, 31, v4
	v_or_b32_e32 v6, 5, v0
	v_lshlrev_b64 v[176:177], 12, v[4:5]
	v_ashrrev_i32_e32 v7, 31, v6
	v_lshl_add_u64 v[4:5], v[2:3], 0, v[176:177]
	v_lshlrev_b64 v[180:181], 12, v[6:7]
	v_lshl_add_u64 v[6:7], v[2:3], 0, v[180:181]
	global_load_dwordx4 v[108:111], v[4:5], off nt
	global_load_dwordx4 v[104:107], v[6:7], off nt
	v_or_b32_e32 v4, 6, v0
	v_ashrrev_i32_e32 v5, 31, v4
	v_or_b32_e32 v6, 7, v0
; DI void attn_sample_item(const Params& p, int item, ldsp lds, int tid_) {
;     ...
;   for (int j = 0; j < 16; ++j) kvA[j] = __builtin_nontemporal_load((const f32x4*)(ck + (size_t)(wid * 32 + j) * 1024 + lane * 4));
; #pragma unroll
;   for (int j = 0; j < 16; ++j) kvB[j] = __builtin_nontemporal_load((const f32x4*)(ck + (size_t)(wid * 32 + 16 + j) * 1024 + lane * 4));
	v_lshlrev_b64 v[182:183], 12, v[4:5]
	v_ashrrev_i32_e32 v7, 31, v6
	v_lshl_add_u64 v[4:5], v[2:3], 0, v[182:183]
	v_lshlrev_b64 v[186:187], 12, v[6:7]
	v_lshl_add_u64 v[6:7], v[2:3], 0, v[186:187]
	global_load_dwordx4 v[100:103], v[4:5], off nt
	global_load_dwordx4 v[96:99], v[6:7], off nt
	v_or_b32_e32 v4, 8, v0
	v_ashrrev_i32_e32 v5, 31, v4
	v_or_b32_e32 v6, 9, v0
	v_lshlrev_b64 v[190:191], 12, v[4:5]
	v_ashrrev_i32_e32 v7, 31, v6
	v_lshl_add_u64 v[4:5], v[2:3], 0, v[190:191]
	v_lshlrev_b64 v[194:195], 12, v[6:7]
	v_lshl_add_u64 v[6:7], v[2:3], 0, v[194:195]
	global_load_dwordx4 v[92:95], v[4:5], off nt
	global_load_dwordx4 v[88:91], v[6:7], off nt
	v_or_b32_e32 v4, 10, v0
	v_ashrrev_i32_e32 v5, 31, v4
	v_or_b32_e32 v6, 11, v0
	v_lshlrev_b64 v[198:199], 12, v[4:5]
	v_ashrrev_i32_e32 v7, 31, v6
	v_lshl_add_u64 v[4:5], v[2:3], 0, v[198:199]
	v_lshlrev_b64 v[200:201], 12, v[6:7]
	v_lshl_add_u64 v[6:7], v[2:3], 0, v[200:201]
	global_load_dwordx4 v[84:87], v[4:5], off nt
	global_load_dwordx4 v[80:83], v[6:7], off nt
	v_or_b32_e32 v4, 12, v0
	v_ashrrev_i32_e32 v5, 31, v4
	v_or_b32_e32 v6, 13, v0
	v_lshlrev_b64 v[202:203], 12, v[4:5]
	v_ashrrev_i32_e32 v7, 31, v6
	v_lshl_add_u64 v[4:5], v[2:3], 0, v[202:203]
	v_lshlrev_b64 v[204:205], 12, v[6:7]
	v_lshl_add_u64 v[6:7], v[2:3], 0, v[204:205]
	global_load_dwordx4 v[76:79], v[4:5], off nt
	global_load_dwordx4 v[72:75], v[6:7], off nt
	v_or_b32_e32 v4, 14, v0
	v_ashrrev_i32_e32 v5, 31, v4
	v_or_b32_e32 v6, 15, v0
	v_lshlrev_b64 v[206:207], 12, v[4:5]
	v_ashrrev_i32_e32 v7, 31, v6
	v_lshl_add_u64 v[4:5], v[2:3], 0, v[206:207]
	v_lshlrev_b64 v[208:209], 12, v[6:7]
	v_lshl_add_u64 v[6:7], v[2:3], 0, v[208:209]
	global_load_dwordx4 v[68:71], v[4:5], off nt
	global_load_dwordx4 v[64:67], v[6:7], off nt
	v_or_b32_e32 v4, 16, v0
	v_ashrrev_i32_e32 v5, 31, v4
	v_or_b32_e32 v6, 17, v0
	v_lshlrev_b64 v[146:147], 12, v[4:5]
	v_ashrrev_i32_e32 v7, 31, v6
	v_lshl_add_u64 v[4:5], v[2:3], 0, v[146:147]
	v_lshlrev_b64 v[148:149], 12, v[6:7]
	v_lshl_add_u64 v[6:7], v[2:3], 0, v[148:149]
	global_load_dwordx4 v[60:63], v[4:5], off nt
	global_load_dwordx4 v[56:59], v[6:7], off nt
	v_or_b32_e32 v4, 18, v0
	v_ashrrev_i32_e32 v5, 31, v4
	v_or_b32_e32 v6, 19, v0
	v_lshlrev_b64 v[150:151], 12, v[4:5]
	v_ashrrev_i32_e32 v7, 31, v6
	v_lshl_add_u64 v[4:5], v[2:3], 0, v[150:151]
	v_lshlrev_b64 v[152:153], 12, v[6:7]
	v_lshl_add_u64 v[6:7], v[2:3], 0, v[152:153]
	global_load_dwordx4 v[52:55], v[4:5], off nt
	global_load_dwordx4 v[48:51], v[6:7], off nt
	v_or_b32_e32 v4, 20, v0
	v_ashrrev_i32_e32 v5, 31, v4
	v_or_b32_e32 v6, 21, v0
	v_lshlrev_b64 v[154:155], 12, v[4:5]
	v_ashrrev_i32_e32 v7, 31, v6
	v_lshl_add_u64 v[4:5], v[2:3], 0, v[154:155]
	v_lshlrev_b64 v[156:157], 12, v[6:7]
	v_lshl_add_u64 v[6:7], v[2:3], 0, v[156:157]
	global_load_dwordx4 v[44:47], v[4:5], off nt
	global_load_dwordx4 v[40:43], v[6:7], off nt
	v_or_b32_e32 v4, 22, v0
	v_ashrrev_i32_e32 v5, 31, v4
	v_or_b32_e32 v6, 23, v0
	v_lshlrev_b64 v[158:159], 12, v[4:5]
	v_ashrrev_i32_e32 v7, 31, v6
	v_lshl_add_u64 v[4:5], v[2:3], 0, v[158:159]
	v_lshlrev_b64 v[160:161], 12, v[6:7]
	v_lshl_add_u64 v[6:7], v[2:3], 0, v[160:161]
	global_load_dwordx4 v[36:39], v[4:5], off nt
	global_load_dwordx4 v[32:35], v[6:7], off nt
	v_or_b32_e32 v4, 24, v0
	v_ashrrev_i32_e32 v5, 31, v4
	v_or_b32_e32 v6, 25, v0
	v_lshlrev_b64 v[164:165], 12, v[4:5]
	v_ashrrev_i32_e32 v7, 31, v6
	v_lshl_add_u64 v[4:5], v[2:3], 0, v[164:165]
	v_lshlrev_b64 v[170:171], 12, v[6:7]
	v_lshl_add_u64 v[6:7], v[2:3], 0, v[170:171]
	global_load_dwordx4 v[28:31], v[4:5], off nt
	global_load_dwordx4 v[24:27], v[6:7], off nt
	v_or_b32_e32 v4, 26, v0
	v_ashrrev_i32_e32 v5, 31, v4
	v_or_b32_e32 v6, 27, v0
	v_lshlrev_b64 v[174:175], 12, v[4:5]
	v_ashrrev_i32_e32 v7, 31, v6
	v_lshl_add_u64 v[4:5], v[2:3], 0, v[174:175]
	v_lshlrev_b64 v[178:179], 12, v[6:7]
	v_lshl_add_u64 v[6:7], v[2:3], 0, v[178:179]
	global_load_dwordx4 v[20:23], v[4:5], off nt
	global_load_dwordx4 v[16:19], v[6:7], off nt
	v_or_b32_e32 v4, 28, v0
	v_ashrrev_i32_e32 v5, 31, v4
	v_or_b32_e32 v6, 29, v0
	v_lshlrev_b64 v[184:185], 12, v[4:5]
	v_ashrrev_i32_e32 v7, 31, v6
	v_lshl_add_u64 v[4:5], v[2:3], 0, v[184:185]
	v_lshlrev_b64 v[188:189], 12, v[6:7]
	v_lshl_add_u64 v[6:7], v[2:3], 0, v[188:189]
	global_load_dwordx4 v[12:15], v[4:5], off nt
	global_load_dwordx4 v[8:11], v[6:7], off nt
	v_or_b32_e32 v4, 30, v0
	v_or_b32_e32 v0, 31, v0
	v_ashrrev_i32_e32 v5, 31, v4
	v_ashrrev_i32_e32 v1, 31, v0
	v_lshlrev_b64 v[192:193], 12, v[4:5]
	v_lshlrev_b64 v[196:197], 12, v[0:1]
	v_lshl_add_u64 v[4:5], v[2:3], 0, v[192:193]
	v_lshl_add_u64 v[0:1], v[2:3], 0, v[196:197]
	global_load_dwordx4 v[4:7], v[4:5], off nt
	s_nop 0
	global_load_dwordx4 v[0:3], v[0:1], off nt
	s_waitcnt vmcnt(35)
	v_pk_add_f32 v[128:129], v[128:129], 0 op_sel_hi:[1,0]
	v_pk_add_f32 v[130:131], v[130:131], 0 op_sel_hi:[1,0]
	s_waitcnt vmcnt(34)
	v_pk_add_f32 v[128:129], v[128:129], v[132:133]
	v_pk_add_f32 v[130:131], v[130:131], v[134:135]
	s_waitcnt vmcnt(33)
	v_pk_add_f32 v[128:129], v[128:129], v[136:137]
	v_pk_add_f32 v[130:131], v[130:131], v[138:139]
	s_waitcnt vmcnt(32)
; DI void attn_sample_item(const Params& p, int item, ldsp lds, int tid_) {
;     ...
;     q[t][0] = a[0] * 0.0625f; q[t][1] = a[1] * 0.0625f; q[t][2] = a[2] * 0.0625f; q[t][3] = a[3] * 0.0625f; }
;     ...
;   SC_SCORE(kvA, 0)
;   SC_SCORE(kvB, 1)
	v_pk_add_f32 v[128:129], v[128:129], v[140:141]
	v_pk_add_f32 v[130:131], v[130:131], v[142:143]
	v_mul_f32_e32 v138, 0x3d800000, v129
	v_mul_f32_e32 v135, 0x3d800000, v128
	v_mul_f32_e32 v134, 0x3d800000, v131
	s_add_u32 s66, s14, s30
	s_addc_u32 s67, s15, s31
	v_mul_f32_e32 v137, 0x3d800000, v130
	v_lshlrev_b32_e32 v128, 2, v215
	v_lshlrev_b32_e32 v129, 2, v217
	v_lshlrev_b32_e32 v130, 2, v218
	v_lshlrev_b32_e32 v131, 2, v219
	v_lshlrev_b32_e32 v132, 2, v220
	v_lshlrev_b32_e32 v133, 2, v221
	v_lshl_add_u32 v136, v210, 7, 16
	v_and_b32_e32 v139, 3, v223
	v_bfrev_b32_e32 v139, v139
	v_lshrrev_b32_e32 v139, 20, v139
	v_and_b32_e32 v235, -4, v223
	v_add3_u32 v235, v136, v139, v235
	v_mov_b32_e32 v236, v228
	v_mov_b32_e32 v237, v226
	v_mov_b32_e32 v238, v231
	v_mov_b32_e32 v239, v230
	v_mov_b32_e32 v240, v229
	v_mov_b32_e32 v241, v227
	v_mov_b32_e32 v242, v225
	v_mov_b32_e32 v243, v224
	v_mov_b32_e32 v244, v232
	v_mov_b32_e32 v245, v135
	v_mov_b32_e32 v246, v234
	v_mov_b32_e32 v247, v138
	v_mov_b32_e32 v248, v233
	v_mov_b32_e32 v249, v137
	v_mov_b32_e32 v250, v211
	v_mov_b32_e32 v251, v134
	s_mov_b32 vcc_lo, 0x55555555
	s_mov_b32 vcc_hi, 0x55555555
	s_mov_b32 s4, 0x33333333
	s_mov_b32 s5, 0x33333333
	s_mov_b32 s6, 0x0f0f0f0f
	s_mov_b32 s7, 0x0f0f0f0f
	s_mov_b32 s64, 0x00ff00ff
	s_mov_b32 s65, 0x00ff00ff
	s_waitcnt vmcnt(31)
	v_pk_mul_f32 v[252:253], v[236:237], v[124:125] op_sel_hi:[1,0]
	v_pk_mul_f32 v[254:255], v[244:245], v[124:125] op_sel_hi:[1,0]
	v_pk_fma_f32 v[252:253], v[238:239], v[124:125], v[252:253] op_sel:[0,1,0]
	v_pk_fma_f32 v[254:255], v[246:247], v[124:125], v[254:255] op_sel:[0,1,0]
	v_pk_fma_f32 v[252:253], v[240:241], v[126:127], v[252:253] op_sel_hi:[1,0,1]
	v_pk_fma_f32 v[254:255], v[248:249], v[126:127], v[254:255] op_sel_hi:[1,0,1]
	v_pk_fma_f32 v[252:253], v[242:243], v[126:127], v[252:253] op_sel:[0,1,0]
	v_pk_fma_f32 v[254:255], v[250:251], v[126:127], v[254:255] op_sel:[0,1,0]
	s_waitcnt vmcnt(30)
	v_pk_mul_f32 v[140:141], v[236:237], v[120:121] op_sel_hi:[1,0]
	v_pk_mul_f32 v[142:143], v[244:245], v[120:121] op_sel_hi:[1,0]
	v_pk_fma_f32 v[140:141], v[238:239], v[120:121], v[140:141] op_sel:[0,1,0]
	v_pk_fma_f32 v[142:143], v[246:247], v[120:121], v[142:143] op_sel:[0,1,0]
	v_pk_fma_f32 v[140:141], v[240:241], v[122:123], v[140:141] op_sel_hi:[1,0,1]
	v_pk_fma_f32 v[142:143], v[248:249], v[122:123], v[142:143] op_sel_hi:[1,0,1]
	v_pk_fma_f32 v[140:141], v[242:243], v[122:123], v[140:141] op_sel:[0,1,0]
	v_pk_fma_f32 v[142:143], v[250:251], v[122:123], v[142:143] op_sel:[0,1,0]
	v_add_f32_dpp v124, v252, v252 quad_perm:[1,0,3,2] row_mask:0xf bank_mask:0xf
	v_add_f32_dpp v125, v253, v253 quad_perm:[1,0,3,2] row_mask:0xf bank_mask:0xf
	v_add_f32_dpp v126, v254, v254 quad_perm:[1,0,3,2] row_mask:0xf bank_mask:0xf
	v_add_f32_dpp v127, v255, v255 quad_perm:[1,0,3,2] row_mask:0xf bank_mask:0xf
	v_cndmask_b32_e32 v124, v126, v124, vcc
	v_cndmask_b32_e32 v125, v127, v125, vcc
	s_waitcnt vmcnt(29)
	v_pk_mul_f32 v[252:253], v[236:237], v[116:117] op_sel_hi:[1,0]
	v_pk_mul_f32 v[254:255], v[244:245], v[116:117] op_sel_hi:[1,0]
	v_pk_fma_f32 v[252:253], v[238:239], v[116:117], v[252:253] op_sel:[0,1,0]
	v_pk_fma_f32 v[254:255], v[246:247], v[116:117], v[254:255] op_sel:[0,1,0]
	v_pk_fma_f32 v[252:253], v[240:241], v[118:119], v[252:253] op_sel_hi:[1,0,1]
	v_pk_fma_f32 v[254:255], v[248:249], v[118:119], v[254:255] op_sel_hi:[1,0,1]
	v_pk_fma_f32 v[252:253], v[242:243], v[118:119], v[252:253] op_sel:[0,1,0]
	v_pk_fma_f32 v[254:255], v[250:251], v[118:119], v[254:255] op_sel:[0,1,0]
	v_add_f32_dpp v120, v140, v140 quad_perm:[1,0,3,2] row_mask:0xf bank_mask:0xf
	v_add_f32_dpp v121, v141, v141 quad_perm:[1,0,3,2] row_mask:0xf bank_mask:0xf
	v_add_f32_dpp v122, v142, v142 quad_perm:[1,0,3,2] row_mask:0xf bank_mask:0xf
	v_add_f32_dpp v123, v143, v143 quad_perm:[1,0,3,2] row_mask:0xf bank_mask:0xf
	v_cndmask_b32_e32 v120, v122, v120, vcc
	v_cndmask_b32_e32 v121, v123, v121, vcc
	v_add_f32_dpp v126, v124, v124 quad_perm:[2,3,0,1] row_mask:0xf bank_mask:0xf
	v_add_f32_dpp v127, v125, v125 quad_perm:[2,3,0,1] row_mask:0xf bank_mask:0xf
	v_cndmask_b32_e64 v124, v127, v126, s[4:5]
	s_waitcnt vmcnt(28)
	v_pk_mul_f32 v[140:141], v[236:237], v[112:113] op_sel_hi:[1,0]
	v_pk_mul_f32 v[142:143], v[244:245], v[112:113] op_sel_hi:[1,0]
	v_pk_fma_f32 v[140:141], v[238:239], v[112:113], v[140:141] op_sel:[0,1,0]
	v_pk_fma_f32 v[142:143], v[246:247], v[112:113], v[142:143] op_sel:[0,1,0]
	v_pk_fma_f32 v[140:141], v[240:241], v[114:115], v[140:141] op_sel_hi:[1,0,1]
	v_pk_fma_f32 v[142:143], v[248:249], v[114:115], v[142:143] op_sel_hi:[1,0,1]
	v_pk_fma_f32 v[140:141], v[242:243], v[114:115], v[140:141] op_sel:[0,1,0]
	v_pk_fma_f32 v[142:143], v[250:251], v[114:115], v[142:143] op_sel:[0,1,0]
	v_add_f32_dpp v116, v252, v252 quad_perm:[1,0,3,2] row_mask:0xf bank_mask:0xf
	v_add_f32_dpp v117, v253, v253 quad_perm:[1,0,3,2] row_mask:0xf bank_mask:0xf
	v_add_f32_dpp v118, v254, v254 quad_perm:[1,0,3,2] row_mask:0xf bank_mask:0xf
	v_add_f32_dpp v119, v255, v255 quad_perm:[1,0,3,2] row_mask:0xf bank_mask:0xf
	v_cndmask_b32_e32 v116, v118, v116, vcc
	v_cndmask_b32_e32 v117, v119, v117, vcc
	v_add_f32_dpp v122, v120, v120 quad_perm:[2,3,0,1] row_mask:0xf bank_mask:0xf
	v_add_f32_dpp v123, v121, v121 quad_perm:[2,3,0,1] row_mask:0xf bank_mask:0xf
	v_cndmask_b32_e64 v120, v123, v122, s[4:5]
	v_cndmask_b32_e64 v125, v120, v124, s[6:7]
	v_cndmask_b32_e64 v126, v124, v120, s[6:7]
	s_waitcnt vmcnt(27)
; DI void attn_sample_item(const Params& p, int item, ldsp lds, int tid_) {
;     ...
;   SC_SCORE(kvA, 0)
;   SC_SCORE(kvB, 1)
	v_pk_mul_f32 v[252:253], v[236:237], v[108:109] op_sel_hi:[1,0]
	v_pk_mul_f32 v[254:255], v[244:245], v[108:109] op_sel_hi:[1,0]
	v_pk_fma_f32 v[252:253], v[238:239], v[108:109], v[252:253] op_sel:[0,1,0]
	v_pk_fma_f32 v[254:255], v[246:247], v[108:109], v[254:255] op_sel:[0,1,0]
	v_pk_fma_f32 v[252:253], v[240:241], v[110:111], v[252:253] op_sel_hi:[1,0,1]
	v_pk_fma_f32 v[254:255], v[248:249], v[110:111], v[254:255] op_sel_hi:[1,0,1]
	v_pk_fma_f32 v[252:253], v[242:243], v[110:111], v[252:253] op_sel:[0,1,0]
	v_pk_fma_f32 v[254:255], v[250:251], v[110:111], v[254:255] op_sel:[0,1,0]
	v_add_f32_dpp v124, v126, v125 row_ror:4 row_mask:0xf bank_mask:0xf
	v_add_f32_dpp v112, v140, v140 quad_perm:[1,0,3,2] row_mask:0xf bank_mask:0xf
	v_add_f32_dpp v113, v141, v141 quad_perm:[1,0,3,2] row_mask:0xf bank_mask:0xf
	v_add_f32_dpp v114, v142, v142 quad_perm:[1,0,3,2] row_mask:0xf bank_mask:0xf
	v_add_f32_dpp v115, v143, v143 quad_perm:[1,0,3,2] row_mask:0xf bank_mask:0xf
	v_cndmask_b32_e32 v112, v114, v112, vcc
	v_cndmask_b32_e32 v113, v115, v113, vcc
	v_add_f32_dpp v118, v116, v116 quad_perm:[2,3,0,1] row_mask:0xf bank_mask:0xf
	v_add_f32_dpp v119, v117, v117 quad_perm:[2,3,0,1] row_mask:0xf bank_mask:0xf
	v_cndmask_b32_e64 v116, v119, v118, s[4:5]
	s_waitcnt vmcnt(26)
	v_pk_mul_f32 v[140:141], v[236:237], v[104:105] op_sel_hi:[1,0]
	v_pk_mul_f32 v[142:143], v[244:245], v[104:105] op_sel_hi:[1,0]
	v_pk_fma_f32 v[140:141], v[238:239], v[104:105], v[140:141] op_sel:[0,1,0]
	v_pk_fma_f32 v[142:143], v[246:247], v[104:105], v[142:143] op_sel:[0,1,0]
	v_pk_fma_f32 v[140:141], v[240:241], v[106:107], v[140:141] op_sel_hi:[1,0,1]
	v_pk_fma_f32 v[142:143], v[248:249], v[106:107], v[142:143] op_sel_hi:[1,0,1]
	v_pk_fma_f32 v[140:141], v[242:243], v[106:107], v[140:141] op_sel:[0,1,0]
	v_pk_fma_f32 v[142:143], v[250:251], v[106:107], v[142:143] op_sel:[0,1,0]
	v_add_f32_dpp v108, v252, v252 quad_perm:[1,0,3,2] row_mask:0xf bank_mask:0xf
	v_add_f32_dpp v109, v253, v253 quad_perm:[1,0,3,2] row_mask:0xf bank_mask:0xf
	v_add_f32_dpp v110, v254, v254 quad_perm:[1,0,3,2] row_mask:0xf bank_mask:0xf
	v_add_f32_dpp v111, v255, v255 quad_perm:[1,0,3,2] row_mask:0xf bank_mask:0xf
	v_cndmask_b32_e32 v108, v110, v108, vcc
	v_cndmask_b32_e32 v109, v111, v109, vcc
	v_add_f32_dpp v114, v112, v112 quad_perm:[2,3,0,1] row_mask:0xf bank_mask:0xf
	v_add_f32_dpp v115, v113, v113 quad_perm:[2,3,0,1] row_mask:0xf bank_mask:0xf
	v_cndmask_b32_e64 v112, v115, v114, s[4:5]
	v_cndmask_b32_e64 v117, v112, v116, s[6:7]
	v_cndmask_b32_e64 v118, v116, v112, s[6:7]
	s_waitcnt vmcnt(25)
	v_pk_mul_f32 v[252:253], v[236:237], v[100:101] op_sel_hi:[1,0]
	v_pk_mul_f32 v[254:255], v[244:245], v[100:101] op_sel_hi:[1,0]
	v_pk_fma_f32 v[252:253], v[238:239], v[100:101], v[252:253] op_sel:[0,1,0]
	v_pk_fma_f32 v[254:255], v[246:247], v[100:101], v[254:255] op_sel:[0,1,0]
	v_pk_fma_f32 v[252:253], v[240:241], v[102:103], v[252:253] op_sel_hi:[1,0,1]
	v_pk_fma_f32 v[254:255], v[248:249], v[102:103], v[254:255] op_sel_hi:[1,0,1]
	v_pk_fma_f32 v[252:253], v[242:243], v[102:103], v[252:253] op_sel:[0,1,0]
	v_pk_fma_f32 v[254:255], v[250:251], v[102:103], v[254:255] op_sel:[0,1,0]
	v_add_f32_dpp v116, v118, v117 row_ror:4 row_mask:0xf bank_mask:0xf
	v_cndmask_b32_e64 v125, v116, v124, s[64:65]
	v_cndmask_b32_e64 v126, v124, v116, s[64:65]
	v_add_f32_dpp v104, v140, v140 quad_perm:[1,0,3,2] row_mask:0xf bank_mask:0xf
	v_add_f32_dpp v105, v141, v141 quad_perm:[1,0,3,2] row_mask:0xf bank_mask:0xf
	v_add_f32_dpp v106, v142, v142 quad_perm:[1,0,3,2] row_mask:0xf bank_mask:0xf
	v_add_f32_dpp v107, v143, v143 quad_perm:[1,0,3,2] row_mask:0xf bank_mask:0xf
	v_cndmask_b32_e32 v104, v106, v104, vcc
	v_cndmask_b32_e32 v105, v107, v105, vcc
	v_add_f32_dpp v110, v108, v108 quad_perm:[2,3,0,1] row_mask:0xf bank_mask:0xf
	v_add_f32_dpp v111, v109, v109 quad_perm:[2,3,0,1] row_mask:0xf bank_mask:0xf
	v_cndmask_b32_e64 v108, v111, v110, s[4:5]
	s_waitcnt vmcnt(24)
	v_pk_mul_f32 v[140:141], v[236:237], v[96:97] op_sel_hi:[1,0]
	v_pk_mul_f32 v[142:143], v[244:245], v[96:97] op_sel_hi:[1,0]
	v_pk_fma_f32 v[140:141], v[238:239], v[96:97], v[140:141] op_sel:[0,1,0]
	v_pk_fma_f32 v[142:143], v[246:247], v[96:97], v[142:143] op_sel:[0,1,0]
	v_pk_fma_f32 v[140:141], v[240:241], v[98:99], v[140:141] op_sel_hi:[1,0,1]
	v_pk_fma_f32 v[142:143], v[248:249], v[98:99], v[142:143] op_sel_hi:[1,0,1]
	v_pk_fma_f32 v[140:141], v[242:243], v[98:99], v[140:141] op_sel:[0,1,0]
	v_pk_fma_f32 v[142:143], v[250:251], v[98:99], v[142:143] op_sel:[0,1,0]
	v_add_f32_dpp v124, v126, v125 row_ror:8 row_mask:0xf bank_mask:0xf
	v_add_f32_dpp v100, v252, v252 quad_perm:[1,0,3,2] row_mask:0xf bank_mask:0xf
	v_add_f32_dpp v101, v253, v253 quad_perm:[1,0,3,2] row_mask:0xf bank_mask:0xf
	v_add_f32_dpp v102, v254, v254 quad_perm:[1,0,3,2] row_mask:0xf bank_mask:0xf
	v_add_f32_dpp v103, v255, v255 quad_perm:[1,0,3,2] row_mask:0xf bank_mask:0xf
	v_cndmask_b32_e32 v100, v102, v100, vcc
	v_cndmask_b32_e32 v101, v103, v101, vcc
	v_add_f32_dpp v106, v104, v104 quad_perm:[2,3,0,1] row_mask:0xf bank_mask:0xf
	v_add_f32_dpp v107, v105, v105 quad_perm:[2,3,0,1] row_mask:0xf bank_mask:0xf
	v_cndmask_b32_e64 v104, v107, v106, s[4:5]
	v_cndmask_b32_e64 v109, v104, v108, s[6:7]
	v_cndmask_b32_e64 v110, v108, v104, s[6:7]
	s_waitcnt vmcnt(23)
; DI void attn_sample_item(const Params& p, int item, ldsp lds, int tid_) {
;     ...
;   SC_SCORE(kvA, 0)
;   SC_SCORE(kvB, 1)
	v_pk_mul_f32 v[252:253], v[236:237], v[92:93] op_sel_hi:[1,0]
	v_pk_mul_f32 v[254:255], v[244:245], v[92:93] op_sel_hi:[1,0]
	v_pk_fma_f32 v[252:253], v[238:239], v[92:93], v[252:253] op_sel:[0,1,0]
	v_pk_fma_f32 v[254:255], v[246:247], v[92:93], v[254:255] op_sel:[0,1,0]
	v_pk_fma_f32 v[252:253], v[240:241], v[94:95], v[252:253] op_sel_hi:[1,0,1]
	v_pk_fma_f32 v[254:255], v[248:249], v[94:95], v[254:255] op_sel_hi:[1,0,1]
	v_pk_fma_f32 v[252:253], v[242:243], v[94:95], v[252:253] op_sel:[0,1,0]
	v_pk_fma_f32 v[254:255], v[250:251], v[94:95], v[254:255] op_sel:[0,1,0]
	v_add_f32_dpp v108, v110, v109 row_ror:4 row_mask:0xf bank_mask:0xf
	v_add_f32_dpp v96, v140, v140 quad_perm:[1,0,3,2] row_mask:0xf bank_mask:0xf
	v_add_f32_dpp v97, v141, v141 quad_perm:[1,0,3,2] row_mask:0xf bank_mask:0xf
	v_add_f32_dpp v98, v142, v142 quad_perm:[1,0,3,2] row_mask:0xf bank_mask:0xf
	v_add_f32_dpp v99, v143, v143 quad_perm:[1,0,3,2] row_mask:0xf bank_mask:0xf
	v_cndmask_b32_e32 v96, v98, v96, vcc
	v_cndmask_b32_e32 v97, v99, v97, vcc
	v_add_f32_dpp v102, v100, v100 quad_perm:[2,3,0,1] row_mask:0xf bank_mask:0xf
	v_add_f32_dpp v103, v101, v101 quad_perm:[2,3,0,1] row_mask:0xf bank_mask:0xf
	v_cndmask_b32_e64 v100, v103, v102, s[4:5]
	s_waitcnt vmcnt(22)
	v_pk_mul_f32 v[140:141], v[236:237], v[88:89] op_sel_hi:[1,0]
	v_pk_mul_f32 v[142:143], v[244:245], v[88:89] op_sel_hi:[1,0]
	v_pk_fma_f32 v[140:141], v[238:239], v[88:89], v[140:141] op_sel:[0,1,0]
	v_pk_fma_f32 v[142:143], v[246:247], v[88:89], v[142:143] op_sel:[0,1,0]
	v_pk_fma_f32 v[140:141], v[240:241], v[90:91], v[140:141] op_sel_hi:[1,0,1]
	v_pk_fma_f32 v[142:143], v[248:249], v[90:91], v[142:143] op_sel_hi:[1,0,1]
	v_pk_fma_f32 v[140:141], v[242:243], v[90:91], v[140:141] op_sel:[0,1,0]
	v_pk_fma_f32 v[142:143], v[250:251], v[90:91], v[142:143] op_sel:[0,1,0]
	v_add_f32_dpp v92, v252, v252 quad_perm:[1,0,3,2] row_mask:0xf bank_mask:0xf
	v_add_f32_dpp v93, v253, v253 quad_perm:[1,0,3,2] row_mask:0xf bank_mask:0xf
	v_add_f32_dpp v94, v254, v254 quad_perm:[1,0,3,2] row_mask:0xf bank_mask:0xf
	v_add_f32_dpp v95, v255, v255 quad_perm:[1,0,3,2] row_mask:0xf bank_mask:0xf
	v_cndmask_b32_e32 v92, v94, v92, vcc
	v_cndmask_b32_e32 v93, v95, v93, vcc
	v_add_f32_dpp v98, v96, v96 quad_perm:[2,3,0,1] row_mask:0xf bank_mask:0xf
	v_add_f32_dpp v99, v97, v97 quad_perm:[2,3,0,1] row_mask:0xf bank_mask:0xf
	v_cndmask_b32_e64 v96, v99, v98, s[4:5]
	v_cndmask_b32_e64 v101, v96, v100, s[6:7]
	v_cndmask_b32_e64 v102, v100, v96, s[6:7]
	s_waitcnt vmcnt(21)
	v_pk_mul_f32 v[252:253], v[236:237], v[84:85] op_sel_hi:[1,0]
	v_pk_mul_f32 v[254:255], v[244:245], v[84:85] op_sel_hi:[1,0]
	v_pk_fma_f32 v[252:253], v[238:239], v[84:85], v[252:253] op_sel:[0,1,0]
	v_pk_fma_f32 v[254:255], v[246:247], v[84:85], v[254:255] op_sel:[0,1,0]
	v_pk_fma_f32 v[252:253], v[240:241], v[86:87], v[252:253] op_sel_hi:[1,0,1]
	v_pk_fma_f32 v[254:255], v[248:249], v[86:87], v[254:255] op_sel_hi:[1,0,1]
	v_pk_fma_f32 v[252:253], v[242:243], v[86:87], v[252:253] op_sel:[0,1,0]
	v_pk_fma_f32 v[254:255], v[250:251], v[86:87], v[254:255] op_sel:[0,1,0]
	v_add_f32_dpp v100, v102, v101 row_ror:4 row_mask:0xf bank_mask:0xf
	v_cndmask_b32_e64 v109, v100, v108, s[64:65]
	v_cndmask_b32_e64 v110, v108, v100, s[64:65]
	v_add_f32_dpp v88, v140, v140 quad_perm:[1,0,3,2] row_mask:0xf bank_mask:0xf
	v_add_f32_dpp v89, v141, v141 quad_perm:[1,0,3,2] row_mask:0xf bank_mask:0xf
	v_add_f32_dpp v90, v142, v142 quad_perm:[1,0,3,2] row_mask:0xf bank_mask:0xf
	v_add_f32_dpp v91, v143, v143 quad_perm:[1,0,3,2] row_mask:0xf bank_mask:0xf
	v_cndmask_b32_e32 v88, v90, v88, vcc
	v_cndmask_b32_e32 v89, v91, v89, vcc
	v_add_f32_dpp v94, v92, v92 quad_perm:[2,3,0,1] row_mask:0xf bank_mask:0xf
	v_add_f32_dpp v95, v93, v93 quad_perm:[2,3,0,1] row_mask:0xf bank_mask:0xf
	v_cndmask_b32_e64 v92, v95, v94, s[4:5]
	s_waitcnt vmcnt(20)
	v_pk_mul_f32 v[140:141], v[236:237], v[80:81] op_sel_hi:[1,0]
	v_pk_mul_f32 v[142:143], v[244:245], v[80:81] op_sel_hi:[1,0]
	v_pk_fma_f32 v[140:141], v[238:239], v[80:81], v[140:141] op_sel:[0,1,0]
	v_pk_fma_f32 v[142:143], v[246:247], v[80:81], v[142:143] op_sel:[0,1,0]
	v_pk_fma_f32 v[140:141], v[240:241], v[82:83], v[140:141] op_sel_hi:[1,0,1]
	v_pk_fma_f32 v[142:143], v[248:249], v[82:83], v[142:143] op_sel_hi:[1,0,1]
	v_pk_fma_f32 v[140:141], v[242:243], v[82:83], v[140:141] op_sel:[0,1,0]
	v_pk_fma_f32 v[142:143], v[250:251], v[82:83], v[142:143] op_sel:[0,1,0]
	v_add_f32_dpp v108, v110, v109 row_ror:8 row_mask:0xf bank_mask:0xf
	v_add_f32_dpp v84, v252, v252 quad_perm:[1,0,3,2] row_mask:0xf bank_mask:0xf
	v_add_f32_dpp v85, v253, v253 quad_perm:[1,0,3,2] row_mask:0xf bank_mask:0xf
	v_add_f32_dpp v86, v254, v254 quad_perm:[1,0,3,2] row_mask:0xf bank_mask:0xf
	v_add_f32_dpp v87, v255, v255 quad_perm:[1,0,3,2] row_mask:0xf bank_mask:0xf
	v_cndmask_b32_e32 v84, v86, v84, vcc
	v_cndmask_b32_e32 v85, v87, v85, vcc
	v_add_f32_dpp v90, v88, v88 quad_perm:[2,3,0,1] row_mask:0xf bank_mask:0xf
	v_add_f32_dpp v91, v89, v89 quad_perm:[2,3,0,1] row_mask:0xf bank_mask:0xf
	v_cndmask_b32_e64 v88, v91, v90, s[4:5]
	v_cndmask_b32_e64 v93, v88, v92, s[6:7]
	v_cndmask_b32_e64 v94, v92, v88, s[6:7]
	s_waitcnt vmcnt(19)
; DI void attn_sample_item(const Params& p, int item, ldsp lds, int tid_) {
;     ...
;   SC_SCORE(kvA, 0)
;   SC_SCORE(kvB, 1)
	v_pk_mul_f32 v[252:253], v[236:237], v[76:77] op_sel_hi:[1,0]
	v_pk_mul_f32 v[254:255], v[244:245], v[76:77] op_sel_hi:[1,0]
	v_pk_fma_f32 v[252:253], v[238:239], v[76:77], v[252:253] op_sel:[0,1,0]
	v_pk_fma_f32 v[254:255], v[246:247], v[76:77], v[254:255] op_sel:[0,1,0]
	v_pk_fma_f32 v[252:253], v[240:241], v[78:79], v[252:253] op_sel_hi:[1,0,1]
	v_pk_fma_f32 v[254:255], v[248:249], v[78:79], v[254:255] op_sel_hi:[1,0,1]
	v_pk_fma_f32 v[252:253], v[242:243], v[78:79], v[252:253] op_sel:[0,1,0]
	v_pk_fma_f32 v[254:255], v[250:251], v[78:79], v[254:255] op_sel:[0,1,0]
	v_permlane16_swap_b32_e32 v124, v108
	v_add_f32_e32 v124, v124, v108
	v_add_f32_dpp v92, v94, v93 row_ror:4 row_mask:0xf bank_mask:0xf
	v_add_f32_dpp v80, v140, v140 quad_perm:[1,0,3,2] row_mask:0xf bank_mask:0xf
	v_add_f32_dpp v81, v141, v141 quad_perm:[1,0,3,2] row_mask:0xf bank_mask:0xf
	v_add_f32_dpp v82, v142, v142 quad_perm:[1,0,3,2] row_mask:0xf bank_mask:0xf
	v_add_f32_dpp v83, v143, v143 quad_perm:[1,0,3,2] row_mask:0xf bank_mask:0xf
	v_cndmask_b32_e32 v80, v82, v80, vcc
	v_cndmask_b32_e32 v81, v83, v81, vcc
	v_add_f32_dpp v86, v84, v84 quad_perm:[2,3,0,1] row_mask:0xf bank_mask:0xf
	v_add_f32_dpp v87, v85, v85 quad_perm:[2,3,0,1] row_mask:0xf bank_mask:0xf
	v_cndmask_b32_e64 v84, v87, v86, s[4:5]
	s_waitcnt vmcnt(18)
	v_pk_mul_f32 v[140:141], v[236:237], v[72:73] op_sel_hi:[1,0]
	v_pk_mul_f32 v[142:143], v[244:245], v[72:73] op_sel_hi:[1,0]
	v_pk_fma_f32 v[140:141], v[238:239], v[72:73], v[140:141] op_sel:[0,1,0]
	v_pk_fma_f32 v[142:143], v[246:247], v[72:73], v[142:143] op_sel:[0,1,0]
	v_pk_fma_f32 v[140:141], v[240:241], v[74:75], v[140:141] op_sel_hi:[1,0,1]
	v_pk_fma_f32 v[142:143], v[248:249], v[74:75], v[142:143] op_sel_hi:[1,0,1]
	v_pk_fma_f32 v[140:141], v[242:243], v[74:75], v[140:141] op_sel:[0,1,0]
	v_pk_fma_f32 v[142:143], v[250:251], v[74:75], v[142:143] op_sel:[0,1,0]
	v_add_f32_dpp v76, v252, v252 quad_perm:[1,0,3,2] row_mask:0xf bank_mask:0xf
	v_add_f32_dpp v77, v253, v253 quad_perm:[1,0,3,2] row_mask:0xf bank_mask:0xf
	v_add_f32_dpp v78, v254, v254 quad_perm:[1,0,3,2] row_mask:0xf bank_mask:0xf
	v_add_f32_dpp v79, v255, v255 quad_perm:[1,0,3,2] row_mask:0xf bank_mask:0xf
	v_cndmask_b32_e32 v76, v78, v76, vcc
	v_cndmask_b32_e32 v77, v79, v77, vcc
	v_add_f32_dpp v82, v80, v80 quad_perm:[2,3,0,1] row_mask:0xf bank_mask:0xf
	v_add_f32_dpp v83, v81, v81 quad_perm:[2,3,0,1] row_mask:0xf bank_mask:0xf
	v_cndmask_b32_e64 v80, v83, v82, s[4:5]
	v_cndmask_b32_e64 v85, v80, v84, s[6:7]
	v_cndmask_b32_e64 v86, v84, v80, s[6:7]
	s_waitcnt vmcnt(17)
	v_pk_mul_f32 v[252:253], v[236:237], v[68:69] op_sel_hi:[1,0]
	v_pk_mul_f32 v[254:255], v[244:245], v[68:69] op_sel_hi:[1,0]
	v_pk_fma_f32 v[252:253], v[238:239], v[68:69], v[252:253] op_sel:[0,1,0]
	v_pk_fma_f32 v[254:255], v[246:247], v[68:69], v[254:255] op_sel:[0,1,0]
	v_pk_fma_f32 v[252:253], v[240:241], v[70:71], v[252:253] op_sel_hi:[1,0,1]
	v_pk_fma_f32 v[254:255], v[248:249], v[70:71], v[254:255] op_sel_hi:[1,0,1]
	v_pk_fma_f32 v[252:253], v[242:243], v[70:71], v[252:253] op_sel:[0,1,0]
	v_pk_fma_f32 v[254:255], v[250:251], v[70:71], v[254:255] op_sel:[0,1,0]
	v_add_f32_dpp v84, v86, v85 row_ror:4 row_mask:0xf bank_mask:0xf
	v_cndmask_b32_e64 v93, v84, v92, s[64:65]
	v_cndmask_b32_e64 v94, v92, v84, s[64:65]
	v_add_f32_dpp v72, v140, v140 quad_perm:[1,0,3,2] row_mask:0xf bank_mask:0xf
	v_add_f32_dpp v73, v141, v141 quad_perm:[1,0,3,2] row_mask:0xf bank_mask:0xf
	v_add_f32_dpp v74, v142, v142 quad_perm:[1,0,3,2] row_mask:0xf bank_mask:0xf
	v_add_f32_dpp v75, v143, v143 quad_perm:[1,0,3,2] row_mask:0xf bank_mask:0xf
	v_cndmask_b32_e32 v72, v74, v72, vcc
	v_cndmask_b32_e32 v73, v75, v73, vcc
	v_add_f32_dpp v78, v76, v76 quad_perm:[2,3,0,1] row_mask:0xf bank_mask:0xf
	v_add_f32_dpp v79, v77, v77 quad_perm:[2,3,0,1] row_mask:0xf bank_mask:0xf
	v_cndmask_b32_e64 v76, v79, v78, s[4:5]
	s_waitcnt vmcnt(16)
	v_pk_mul_f32 v[140:141], v[236:237], v[64:65] op_sel_hi:[1,0]
	v_pk_mul_f32 v[142:143], v[244:245], v[64:65] op_sel_hi:[1,0]
	v_pk_fma_f32 v[140:141], v[238:239], v[64:65], v[140:141] op_sel:[0,1,0]
	v_pk_fma_f32 v[142:143], v[246:247], v[64:65], v[142:143] op_sel:[0,1,0]
	v_pk_fma_f32 v[140:141], v[240:241], v[66:67], v[140:141] op_sel_hi:[1,0,1]
	v_pk_fma_f32 v[142:143], v[248:249], v[66:67], v[142:143] op_sel_hi:[1,0,1]
	v_pk_fma_f32 v[140:141], v[242:243], v[66:67], v[140:141] op_sel:[0,1,0]
	v_pk_fma_f32 v[142:143], v[250:251], v[66:67], v[142:143] op_sel:[0,1,0]
	v_add_f32_dpp v92, v94, v93 row_ror:8 row_mask:0xf bank_mask:0xf
	v_add_f32_dpp v68, v252, v252 quad_perm:[1,0,3,2] row_mask:0xf bank_mask:0xf
	v_add_f32_dpp v69, v253, v253 quad_perm:[1,0,3,2] row_mask:0xf bank_mask:0xf
	v_add_f32_dpp v70, v254, v254 quad_perm:[1,0,3,2] row_mask:0xf bank_mask:0xf
	v_add_f32_dpp v71, v255, v255 quad_perm:[1,0,3,2] row_mask:0xf bank_mask:0xf
	v_cndmask_b32_e32 v68, v70, v68, vcc
	v_cndmask_b32_e32 v69, v71, v69, vcc
	v_add_f32_dpp v74, v72, v72 quad_perm:[2,3,0,1] row_mask:0xf bank_mask:0xf
	v_add_f32_dpp v75, v73, v73 quad_perm:[2,3,0,1] row_mask:0xf bank_mask:0xf
	v_cndmask_b32_e64 v72, v75, v74, s[4:5]
	v_cndmask_b32_e64 v77, v72, v76, s[6:7]
	v_cndmask_b32_e64 v78, v76, v72, s[6:7]
	s_waitcnt vmcnt(15)
; DI void attn_sample_item(const Params& p, int item, ldsp lds, int tid_) {
;     ...
;   SC_SCORE(kvA, 0)
;   SC_SCORE(kvB, 1)
	v_pk_mul_f32 v[252:253], v[236:237], v[60:61] op_sel_hi:[1,0]
	v_pk_mul_f32 v[254:255], v[244:245], v[60:61] op_sel_hi:[1,0]
	v_pk_fma_f32 v[252:253], v[238:239], v[60:61], v[252:253] op_sel:[0,1,0]
	v_pk_fma_f32 v[254:255], v[246:247], v[60:61], v[254:255] op_sel:[0,1,0]
	v_pk_fma_f32 v[252:253], v[240:241], v[62:63], v[252:253] op_sel_hi:[1,0,1]
	v_pk_fma_f32 v[254:255], v[248:249], v[62:63], v[254:255] op_sel_hi:[1,0,1]
	v_pk_fma_f32 v[252:253], v[242:243], v[62:63], v[252:253] op_sel:[0,1,0]
	v_pk_fma_f32 v[254:255], v[250:251], v[62:63], v[254:255] op_sel:[0,1,0]
	v_add_f32_dpp v76, v78, v77 row_ror:4 row_mask:0xf bank_mask:0xf
	v_add_f32_dpp v64, v140, v140 quad_perm:[1,0,3,2] row_mask:0xf bank_mask:0xf
	v_add_f32_dpp v65, v141, v141 quad_perm:[1,0,3,2] row_mask:0xf bank_mask:0xf
	v_add_f32_dpp v66, v142, v142 quad_perm:[1,0,3,2] row_mask:0xf bank_mask:0xf
	v_add_f32_dpp v67, v143, v143 quad_perm:[1,0,3,2] row_mask:0xf bank_mask:0xf
	v_cndmask_b32_e32 v64, v66, v64, vcc
	v_cndmask_b32_e32 v65, v67, v65, vcc
	v_add_f32_dpp v70, v68, v68 quad_perm:[2,3,0,1] row_mask:0xf bank_mask:0xf
	v_add_f32_dpp v71, v69, v69 quad_perm:[2,3,0,1] row_mask:0xf bank_mask:0xf
	v_cndmask_b32_e64 v68, v71, v70, s[4:5]
	s_waitcnt vmcnt(14)
	v_pk_mul_f32 v[140:141], v[236:237], v[56:57] op_sel_hi:[1,0]
	v_pk_mul_f32 v[142:143], v[244:245], v[56:57] op_sel_hi:[1,0]
	v_pk_fma_f32 v[140:141], v[238:239], v[56:57], v[140:141] op_sel:[0,1,0]
	v_pk_fma_f32 v[142:143], v[246:247], v[56:57], v[142:143] op_sel:[0,1,0]
	v_pk_fma_f32 v[140:141], v[240:241], v[58:59], v[140:141] op_sel_hi:[1,0,1]
	v_pk_fma_f32 v[142:143], v[248:249], v[58:59], v[142:143] op_sel_hi:[1,0,1]
	v_pk_fma_f32 v[140:141], v[242:243], v[58:59], v[140:141] op_sel:[0,1,0]
	v_pk_fma_f32 v[142:143], v[250:251], v[58:59], v[142:143] op_sel:[0,1,0]
	v_add_f32_dpp v60, v252, v252 quad_perm:[1,0,3,2] row_mask:0xf bank_mask:0xf
	v_add_f32_dpp v61, v253, v253 quad_perm:[1,0,3,2] row_mask:0xf bank_mask:0xf
	v_add_f32_dpp v62, v254, v254 quad_perm:[1,0,3,2] row_mask:0xf bank_mask:0xf
	v_add_f32_dpp v63, v255, v255 quad_perm:[1,0,3,2] row_mask:0xf bank_mask:0xf
	v_cndmask_b32_e32 v60, v62, v60, vcc
	v_cndmask_b32_e32 v61, v63, v61, vcc
	v_add_f32_dpp v66, v64, v64 quad_perm:[2,3,0,1] row_mask:0xf bank_mask:0xf
	v_add_f32_dpp v67, v65, v65 quad_perm:[2,3,0,1] row_mask:0xf bank_mask:0xf
	v_cndmask_b32_e64 v64, v67, v66, s[4:5]
	v_cndmask_b32_e64 v69, v64, v68, s[6:7]
	v_cndmask_b32_e64 v70, v68, v64, s[6:7]
	s_waitcnt vmcnt(13)
	v_pk_mul_f32 v[252:253], v[236:237], v[52:53] op_sel_hi:[1,0]
	v_pk_mul_f32 v[254:255], v[244:245], v[52:53] op_sel_hi:[1,0]
	v_pk_fma_f32 v[252:253], v[238:239], v[52:53], v[252:253] op_sel:[0,1,0]
	v_pk_fma_f32 v[254:255], v[246:247], v[52:53], v[254:255] op_sel:[0,1,0]
	v_pk_fma_f32 v[252:253], v[240:241], v[54:55], v[252:253] op_sel_hi:[1,0,1]
	v_pk_fma_f32 v[254:255], v[248:249], v[54:55], v[254:255] op_sel_hi:[1,0,1]
	v_pk_fma_f32 v[252:253], v[242:243], v[54:55], v[252:253] op_sel:[0,1,0]
	v_pk_fma_f32 v[254:255], v[250:251], v[54:55], v[254:255] op_sel:[0,1,0]
	v_add_f32_dpp v68, v70, v69 row_ror:4 row_mask:0xf bank_mask:0xf
	v_cndmask_b32_e64 v77, v68, v76, s[64:65]
	v_cndmask_b32_e64 v78, v76, v68, s[64:65]
	v_add_f32_dpp v56, v140, v140 quad_perm:[1,0,3,2] row_mask:0xf bank_mask:0xf
	v_add_f32_dpp v57, v141, v141 quad_perm:[1,0,3,2] row_mask:0xf bank_mask:0xf
	v_add_f32_dpp v58, v142, v142 quad_perm:[1,0,3,2] row_mask:0xf bank_mask:0xf
	v_add_f32_dpp v59, v143, v143 quad_perm:[1,0,3,2] row_mask:0xf bank_mask:0xf
	v_cndmask_b32_e32 v56, v58, v56, vcc
	v_cndmask_b32_e32 v57, v59, v57, vcc
	v_add_f32_dpp v62, v60, v60 quad_perm:[2,3,0,1] row_mask:0xf bank_mask:0xf
	v_add_f32_dpp v63, v61, v61 quad_perm:[2,3,0,1] row_mask:0xf bank_mask:0xf
	v_cndmask_b32_e64 v60, v63, v62, s[4:5]
	s_waitcnt vmcnt(12)
	v_pk_mul_f32 v[140:141], v[236:237], v[48:49] op_sel_hi:[1,0]
	v_pk_mul_f32 v[142:143], v[244:245], v[48:49] op_sel_hi:[1,0]
	v_pk_fma_f32 v[140:141], v[238:239], v[48:49], v[140:141] op_sel:[0,1,0]
	v_pk_fma_f32 v[142:143], v[246:247], v[48:49], v[142:143] op_sel:[0,1,0]
	v_pk_fma_f32 v[140:141], v[240:241], v[50:51], v[140:141] op_sel_hi:[1,0,1]
	v_pk_fma_f32 v[142:143], v[248:249], v[50:51], v[142:143] op_sel_hi:[1,0,1]
	v_pk_fma_f32 v[140:141], v[242:243], v[50:51], v[140:141] op_sel:[0,1,0]
	v_pk_fma_f32 v[142:143], v[250:251], v[50:51], v[142:143] op_sel:[0,1,0]
	v_add_f32_dpp v76, v78, v77 row_ror:8 row_mask:0xf bank_mask:0xf
	v_add_f32_dpp v52, v252, v252 quad_perm:[1,0,3,2] row_mask:0xf bank_mask:0xf
	v_add_f32_dpp v53, v253, v253 quad_perm:[1,0,3,2] row_mask:0xf bank_mask:0xf
	v_add_f32_dpp v54, v254, v254 quad_perm:[1,0,3,2] row_mask:0xf bank_mask:0xf
	v_add_f32_dpp v55, v255, v255 quad_perm:[1,0,3,2] row_mask:0xf bank_mask:0xf
	v_cndmask_b32_e32 v52, v54, v52, vcc
	v_cndmask_b32_e32 v53, v55, v53, vcc
	v_add_f32_dpp v58, v56, v56 quad_perm:[2,3,0,1] row_mask:0xf bank_mask:0xf
	v_add_f32_dpp v59, v57, v57 quad_perm:[2,3,0,1] row_mask:0xf bank_mask:0xf
	v_cndmask_b32_e64 v56, v59, v58, s[4:5]
	v_cndmask_b32_e64 v61, v56, v60, s[6:7]
	v_cndmask_b32_e64 v62, v60, v56, s[6:7]
	s_waitcnt vmcnt(11)
; DI void attn_sample_item(const Params& p, int item, ldsp lds, int tid_) {
;     ...
;   SC_SCORE(kvA, 0)
;   SC_SCORE(kvB, 1)
	v_pk_mul_f32 v[252:253], v[236:237], v[44:45] op_sel_hi:[1,0]
	v_pk_mul_f32 v[254:255], v[244:245], v[44:45] op_sel_hi:[1,0]
	v_pk_fma_f32 v[252:253], v[238:239], v[44:45], v[252:253] op_sel:[0,1,0]
	v_pk_fma_f32 v[254:255], v[246:247], v[44:45], v[254:255] op_sel:[0,1,0]
	v_pk_fma_f32 v[252:253], v[240:241], v[46:47], v[252:253] op_sel_hi:[1,0,1]
	v_pk_fma_f32 v[254:255], v[248:249], v[46:47], v[254:255] op_sel_hi:[1,0,1]
	v_pk_fma_f32 v[252:253], v[242:243], v[46:47], v[252:253] op_sel:[0,1,0]
	v_pk_fma_f32 v[254:255], v[250:251], v[46:47], v[254:255] op_sel:[0,1,0]
	v_permlane16_swap_b32_e32 v92, v76
	v_add_f32_e32 v92, v92, v76
	v_add_f32_dpp v60, v62, v61 row_ror:4 row_mask:0xf bank_mask:0xf
	v_add_f32_dpp v48, v140, v140 quad_perm:[1,0,3,2] row_mask:0xf bank_mask:0xf
	v_add_f32_dpp v49, v141, v141 quad_perm:[1,0,3,2] row_mask:0xf bank_mask:0xf
	v_add_f32_dpp v50, v142, v142 quad_perm:[1,0,3,2] row_mask:0xf bank_mask:0xf
	v_add_f32_dpp v51, v143, v143 quad_perm:[1,0,3,2] row_mask:0xf bank_mask:0xf
	v_cndmask_b32_e32 v48, v50, v48, vcc
	v_cndmask_b32_e32 v49, v51, v49, vcc
	v_add_f32_dpp v54, v52, v52 quad_perm:[2,3,0,1] row_mask:0xf bank_mask:0xf
	v_add_f32_dpp v55, v53, v53 quad_perm:[2,3,0,1] row_mask:0xf bank_mask:0xf
	v_cndmask_b32_e64 v52, v55, v54, s[4:5]
	s_waitcnt vmcnt(10)
	v_pk_mul_f32 v[140:141], v[236:237], v[40:41] op_sel_hi:[1,0]
	v_pk_mul_f32 v[142:143], v[244:245], v[40:41] op_sel_hi:[1,0]
	v_pk_fma_f32 v[140:141], v[238:239], v[40:41], v[140:141] op_sel:[0,1,0]
	v_pk_fma_f32 v[142:143], v[246:247], v[40:41], v[142:143] op_sel:[0,1,0]
	v_pk_fma_f32 v[140:141], v[240:241], v[42:43], v[140:141] op_sel_hi:[1,0,1]
	v_pk_fma_f32 v[142:143], v[248:249], v[42:43], v[142:143] op_sel_hi:[1,0,1]
	v_pk_fma_f32 v[140:141], v[242:243], v[42:43], v[140:141] op_sel:[0,1,0]
	v_pk_fma_f32 v[142:143], v[250:251], v[42:43], v[142:143] op_sel:[0,1,0]
	v_permlane32_swap_b32_e32 v124, v92
	v_add_f32_e32 v124, v124, v92
	ds_write_b32 v235, v124
	v_add_f32_dpp v44, v252, v252 quad_perm:[1,0,3,2] row_mask:0xf bank_mask:0xf
	v_add_f32_dpp v45, v253, v253 quad_perm:[1,0,3,2] row_mask:0xf bank_mask:0xf
	v_add_f32_dpp v46, v254, v254 quad_perm:[1,0,3,2] row_mask:0xf bank_mask:0xf
	v_add_f32_dpp v47, v255, v255 quad_perm:[1,0,3,2] row_mask:0xf bank_mask:0xf
	v_cndmask_b32_e32 v44, v46, v44, vcc
	v_cndmask_b32_e32 v45, v47, v45, vcc
	v_add_f32_dpp v50, v48, v48 quad_perm:[2,3,0,1] row_mask:0xf bank_mask:0xf
	v_add_f32_dpp v51, v49, v49 quad_perm:[2,3,0,1] row_mask:0xf bank_mask:0xf
	v_cndmask_b32_e64 v48, v51, v50, s[4:5]
	v_cndmask_b32_e64 v53, v48, v52, s[6:7]
	v_cndmask_b32_e64 v54, v52, v48, s[6:7]
	s_waitcnt vmcnt(9)
	v_pk_mul_f32 v[252:253], v[236:237], v[36:37] op_sel_hi:[1,0]
	v_pk_mul_f32 v[254:255], v[244:245], v[36:37] op_sel_hi:[1,0]
	v_pk_fma_f32 v[252:253], v[238:239], v[36:37], v[252:253] op_sel:[0,1,0]
	v_pk_fma_f32 v[254:255], v[246:247], v[36:37], v[254:255] op_sel:[0,1,0]
	v_pk_fma_f32 v[252:253], v[240:241], v[38:39], v[252:253] op_sel_hi:[1,0,1]
	v_pk_fma_f32 v[254:255], v[248:249], v[38:39], v[254:255] op_sel_hi:[1,0,1]
	v_pk_fma_f32 v[252:253], v[242:243], v[38:39], v[252:253] op_sel:[0,1,0]
	v_pk_fma_f32 v[254:255], v[250:251], v[38:39], v[254:255] op_sel:[0,1,0]
	v_add_f32_dpp v52, v54, v53 row_ror:4 row_mask:0xf bank_mask:0xf
	v_cndmask_b32_e64 v61, v52, v60, s[64:65]
	v_cndmask_b32_e64 v62, v60, v52, s[64:65]
	v_add_f32_dpp v40, v140, v140 quad_perm:[1,0,3,2] row_mask:0xf bank_mask:0xf
	v_add_f32_dpp v41, v141, v141 quad_perm:[1,0,3,2] row_mask:0xf bank_mask:0xf
	v_add_f32_dpp v42, v142, v142 quad_perm:[1,0,3,2] row_mask:0xf bank_mask:0xf
	v_add_f32_dpp v43, v143, v143 quad_perm:[1,0,3,2] row_mask:0xf bank_mask:0xf
	v_cndmask_b32_e32 v40, v42, v40, vcc
	v_cndmask_b32_e32 v41, v43, v41, vcc
	v_add_f32_dpp v46, v44, v44 quad_perm:[2,3,0,1] row_mask:0xf bank_mask:0xf
	v_add_f32_dpp v47, v45, v45 quad_perm:[2,3,0,1] row_mask:0xf bank_mask:0xf
	v_cndmask_b32_e64 v44, v47, v46, s[4:5]
	s_waitcnt vmcnt(8)
	v_pk_mul_f32 v[140:141], v[236:237], v[32:33] op_sel_hi:[1,0]
	v_pk_mul_f32 v[142:143], v[244:245], v[32:33] op_sel_hi:[1,0]
	v_pk_fma_f32 v[140:141], v[238:239], v[32:33], v[140:141] op_sel:[0,1,0]
	v_pk_fma_f32 v[142:143], v[246:247], v[32:33], v[142:143] op_sel:[0,1,0]
	v_pk_fma_f32 v[140:141], v[240:241], v[34:35], v[140:141] op_sel_hi:[1,0,1]
	v_pk_fma_f32 v[142:143], v[248:249], v[34:35], v[142:143] op_sel_hi:[1,0,1]
	v_pk_fma_f32 v[140:141], v[242:243], v[34:35], v[140:141] op_sel:[0,1,0]
	v_pk_fma_f32 v[142:143], v[250:251], v[34:35], v[142:143] op_sel:[0,1,0]
	v_add_f32_dpp v60, v62, v61 row_ror:8 row_mask:0xf bank_mask:0xf
	v_add_f32_dpp v36, v252, v252 quad_perm:[1,0,3,2] row_mask:0xf bank_mask:0xf
	v_add_f32_dpp v37, v253, v253 quad_perm:[1,0,3,2] row_mask:0xf bank_mask:0xf
	v_add_f32_dpp v38, v254, v254 quad_perm:[1,0,3,2] row_mask:0xf bank_mask:0xf
	v_add_f32_dpp v39, v255, v255 quad_perm:[1,0,3,2] row_mask:0xf bank_mask:0xf
	v_cndmask_b32_e32 v36, v38, v36, vcc
	v_cndmask_b32_e32 v37, v39, v37, vcc
	v_add_f32_dpp v42, v40, v40 quad_perm:[2,3,0,1] row_mask:0xf bank_mask:0xf
	v_add_f32_dpp v43, v41, v41 quad_perm:[2,3,0,1] row_mask:0xf bank_mask:0xf
	v_cndmask_b32_e64 v40, v43, v42, s[4:5]
	v_cndmask_b32_e64 v45, v40, v44, s[6:7]
	v_cndmask_b32_e64 v46, v44, v40, s[6:7]
	s_waitcnt vmcnt(7)
; DI void attn_sample_item(const Params& p, int item, ldsp lds, int tid_) {
;     ...
;   SC_SCORE(kvA, 0)
;   SC_SCORE(kvB, 1)
	v_pk_mul_f32 v[252:253], v[236:237], v[28:29] op_sel_hi:[1,0]
	v_pk_mul_f32 v[254:255], v[244:245], v[28:29] op_sel_hi:[1,0]
	v_pk_fma_f32 v[252:253], v[238:239], v[28:29], v[252:253] op_sel:[0,1,0]
	v_pk_fma_f32 v[254:255], v[246:247], v[28:29], v[254:255] op_sel:[0,1,0]
	v_pk_fma_f32 v[252:253], v[240:241], v[30:31], v[252:253] op_sel_hi:[1,0,1]
	v_pk_fma_f32 v[254:255], v[248:249], v[30:31], v[254:255] op_sel_hi:[1,0,1]
	v_pk_fma_f32 v[252:253], v[242:243], v[30:31], v[252:253] op_sel:[0,1,0]
	v_pk_fma_f32 v[254:255], v[250:251], v[30:31], v[254:255] op_sel:[0,1,0]
	v_add_f32_dpp v44, v46, v45 row_ror:4 row_mask:0xf bank_mask:0xf
	v_add_f32_dpp v32, v140, v140 quad_perm:[1,0,3,2] row_mask:0xf bank_mask:0xf
	v_add_f32_dpp v33, v141, v141 quad_perm:[1,0,3,2] row_mask:0xf bank_mask:0xf
	v_add_f32_dpp v34, v142, v142 quad_perm:[1,0,3,2] row_mask:0xf bank_mask:0xf
	v_add_f32_dpp v35, v143, v143 quad_perm:[1,0,3,2] row_mask:0xf bank_mask:0xf
	v_cndmask_b32_e32 v32, v34, v32, vcc
	v_cndmask_b32_e32 v33, v35, v33, vcc
	v_add_f32_dpp v38, v36, v36 quad_perm:[2,3,0,1] row_mask:0xf bank_mask:0xf
	v_add_f32_dpp v39, v37, v37 quad_perm:[2,3,0,1] row_mask:0xf bank_mask:0xf
	v_cndmask_b32_e64 v36, v39, v38, s[4:5]
	s_waitcnt vmcnt(6)
	v_pk_mul_f32 v[140:141], v[236:237], v[24:25] op_sel_hi:[1,0]
	v_pk_mul_f32 v[142:143], v[244:245], v[24:25] op_sel_hi:[1,0]
	v_pk_fma_f32 v[140:141], v[238:239], v[24:25], v[140:141] op_sel:[0,1,0]
	v_pk_fma_f32 v[142:143], v[246:247], v[24:25], v[142:143] op_sel:[0,1,0]
	v_pk_fma_f32 v[140:141], v[240:241], v[26:27], v[140:141] op_sel_hi:[1,0,1]
	v_pk_fma_f32 v[142:143], v[248:249], v[26:27], v[142:143] op_sel_hi:[1,0,1]
	v_pk_fma_f32 v[140:141], v[242:243], v[26:27], v[140:141] op_sel:[0,1,0]
	v_pk_fma_f32 v[142:143], v[250:251], v[26:27], v[142:143] op_sel:[0,1,0]
	v_add_f32_dpp v28, v252, v252 quad_perm:[1,0,3,2] row_mask:0xf bank_mask:0xf
	v_add_f32_dpp v29, v253, v253 quad_perm:[1,0,3,2] row_mask:0xf bank_mask:0xf
	v_add_f32_dpp v30, v254, v254 quad_perm:[1,0,3,2] row_mask:0xf bank_mask:0xf
	v_add_f32_dpp v31, v255, v255 quad_perm:[1,0,3,2] row_mask:0xf bank_mask:0xf
	v_cndmask_b32_e32 v28, v30, v28, vcc
	v_cndmask_b32_e32 v29, v31, v29, vcc
	v_add_f32_dpp v34, v32, v32 quad_perm:[2,3,0,1] row_mask:0xf bank_mask:0xf
	v_add_f32_dpp v35, v33, v33 quad_perm:[2,3,0,1] row_mask:0xf bank_mask:0xf
	v_cndmask_b32_e64 v32, v35, v34, s[4:5]
	v_cndmask_b32_e64 v37, v32, v36, s[6:7]
	v_cndmask_b32_e64 v38, v36, v32, s[6:7]
	s_waitcnt vmcnt(5)
	v_pk_mul_f32 v[252:253], v[236:237], v[20:21] op_sel_hi:[1,0]
	v_pk_mul_f32 v[254:255], v[244:245], v[20:21] op_sel_hi:[1,0]
	v_pk_fma_f32 v[252:253], v[238:239], v[20:21], v[252:253] op_sel:[0,1,0]
	v_pk_fma_f32 v[254:255], v[246:247], v[20:21], v[254:255] op_sel:[0,1,0]
	v_pk_fma_f32 v[252:253], v[240:241], v[22:23], v[252:253] op_sel_hi:[1,0,1]
	v_pk_fma_f32 v[254:255], v[248:249], v[22:23], v[254:255] op_sel_hi:[1,0,1]
	v_pk_fma_f32 v[252:253], v[242:243], v[22:23], v[252:253] op_sel:[0,1,0]
	v_pk_fma_f32 v[254:255], v[250:251], v[22:23], v[254:255] op_sel:[0,1,0]
	v_add_f32_dpp v36, v38, v37 row_ror:4 row_mask:0xf bank_mask:0xf
	v_cndmask_b32_e64 v45, v36, v44, s[64:65]
	v_cndmask_b32_e64 v46, v44, v36, s[64:65]
	v_add_f32_dpp v24, v140, v140 quad_perm:[1,0,3,2] row_mask:0xf bank_mask:0xf
	v_add_f32_dpp v25, v141, v141 quad_perm:[1,0,3,2] row_mask:0xf bank_mask:0xf
	v_add_f32_dpp v26, v142, v142 quad_perm:[1,0,3,2] row_mask:0xf bank_mask:0xf
	v_add_f32_dpp v27, v143, v143 quad_perm:[1,0,3,2] row_mask:0xf bank_mask:0xf
	v_cndmask_b32_e32 v24, v26, v24, vcc
	v_cndmask_b32_e32 v25, v27, v25, vcc
	v_add_f32_dpp v30, v28, v28 quad_perm:[2,3,0,1] row_mask:0xf bank_mask:0xf
	v_add_f32_dpp v31, v29, v29 quad_perm:[2,3,0,1] row_mask:0xf bank_mask:0xf
	v_cndmask_b32_e64 v28, v31, v30, s[4:5]
	s_waitcnt vmcnt(4)
	v_pk_mul_f32 v[140:141], v[236:237], v[16:17] op_sel_hi:[1,0]
	v_pk_mul_f32 v[142:143], v[244:245], v[16:17] op_sel_hi:[1,0]
	v_pk_fma_f32 v[140:141], v[238:239], v[16:17], v[140:141] op_sel:[0,1,0]
	v_pk_fma_f32 v[142:143], v[246:247], v[16:17], v[142:143] op_sel:[0,1,0]
	v_pk_fma_f32 v[140:141], v[240:241], v[18:19], v[140:141] op_sel_hi:[1,0,1]
	v_pk_fma_f32 v[142:143], v[248:249], v[18:19], v[142:143] op_sel_hi:[1,0,1]
	v_pk_fma_f32 v[140:141], v[242:243], v[18:19], v[140:141] op_sel:[0,1,0]
	v_pk_fma_f32 v[142:143], v[250:251], v[18:19], v[142:143] op_sel:[0,1,0]
	v_add_f32_dpp v44, v46, v45 row_ror:8 row_mask:0xf bank_mask:0xf
	v_add_f32_dpp v20, v252, v252 quad_perm:[1,0,3,2] row_mask:0xf bank_mask:0xf
	v_add_f32_dpp v21, v253, v253 quad_perm:[1,0,3,2] row_mask:0xf bank_mask:0xf
	v_add_f32_dpp v22, v254, v254 quad_perm:[1,0,3,2] row_mask:0xf bank_mask:0xf
	v_add_f32_dpp v23, v255, v255 quad_perm:[1,0,3,2] row_mask:0xf bank_mask:0xf
	v_cndmask_b32_e32 v20, v22, v20, vcc
	v_cndmask_b32_e32 v21, v23, v21, vcc
	v_add_f32_dpp v26, v24, v24 quad_perm:[2,3,0,1] row_mask:0xf bank_mask:0xf
	v_add_f32_dpp v27, v25, v25 quad_perm:[2,3,0,1] row_mask:0xf bank_mask:0xf
	v_cndmask_b32_e64 v24, v27, v26, s[4:5]
	v_cndmask_b32_e64 v29, v24, v28, s[6:7]
	v_cndmask_b32_e64 v30, v28, v24, s[6:7]
	s_waitcnt vmcnt(3)
; DI void attn_sample_item(const Params& p, int item, ldsp lds, int tid_) {
;     ...
;   SC_SCORE(kvA, 0)
;   SC_SCORE(kvB, 1)
	v_pk_mul_f32 v[252:253], v[236:237], v[12:13] op_sel_hi:[1,0]
	v_pk_mul_f32 v[254:255], v[244:245], v[12:13] op_sel_hi:[1,0]
	v_pk_fma_f32 v[252:253], v[238:239], v[12:13], v[252:253] op_sel:[0,1,0]
	v_pk_fma_f32 v[254:255], v[246:247], v[12:13], v[254:255] op_sel:[0,1,0]
	v_pk_fma_f32 v[252:253], v[240:241], v[14:15], v[252:253] op_sel_hi:[1,0,1]
	v_pk_fma_f32 v[254:255], v[248:249], v[14:15], v[254:255] op_sel_hi:[1,0,1]
	v_pk_fma_f32 v[252:253], v[242:243], v[14:15], v[252:253] op_sel:[0,1,0]
	v_pk_fma_f32 v[254:255], v[250:251], v[14:15], v[254:255] op_sel:[0,1,0]
	v_permlane16_swap_b32_e32 v60, v44
	v_add_f32_e32 v60, v60, v44
	v_add_f32_dpp v28, v30, v29 row_ror:4 row_mask:0xf bank_mask:0xf
	v_add_f32_dpp v16, v140, v140 quad_perm:[1,0,3,2] row_mask:0xf bank_mask:0xf
	v_add_f32_dpp v17, v141, v141 quad_perm:[1,0,3,2] row_mask:0xf bank_mask:0xf
	v_add_f32_dpp v18, v142, v142 quad_perm:[1,0,3,2] row_mask:0xf bank_mask:0xf
	v_add_f32_dpp v19, v143, v143 quad_perm:[1,0,3,2] row_mask:0xf bank_mask:0xf
	v_cndmask_b32_e32 v16, v18, v16, vcc
	v_cndmask_b32_e32 v17, v19, v17, vcc
	v_add_f32_dpp v22, v20, v20 quad_perm:[2,3,0,1] row_mask:0xf bank_mask:0xf
	v_add_f32_dpp v23, v21, v21 quad_perm:[2,3,0,1] row_mask:0xf bank_mask:0xf
	v_cndmask_b32_e64 v20, v23, v22, s[4:5]
	s_waitcnt vmcnt(2)
	v_pk_mul_f32 v[140:141], v[236:237], v[8:9] op_sel_hi:[1,0]
	v_pk_mul_f32 v[142:143], v[244:245], v[8:9] op_sel_hi:[1,0]
	v_pk_fma_f32 v[140:141], v[238:239], v[8:9], v[140:141] op_sel:[0,1,0]
	v_pk_fma_f32 v[142:143], v[246:247], v[8:9], v[142:143] op_sel:[0,1,0]
	v_pk_fma_f32 v[140:141], v[240:241], v[10:11], v[140:141] op_sel_hi:[1,0,1]
	v_pk_fma_f32 v[142:143], v[248:249], v[10:11], v[142:143] op_sel_hi:[1,0,1]
	v_pk_fma_f32 v[140:141], v[242:243], v[10:11], v[140:141] op_sel:[0,1,0]
	v_pk_fma_f32 v[142:143], v[250:251], v[10:11], v[142:143] op_sel:[0,1,0]
	v_add_f32_dpp v12, v252, v252 quad_perm:[1,0,3,2] row_mask:0xf bank_mask:0xf
	v_add_f32_dpp v13, v253, v253 quad_perm:[1,0,3,2] row_mask:0xf bank_mask:0xf
	v_add_f32_dpp v14, v254, v254 quad_perm:[1,0,3,2] row_mask:0xf bank_mask:0xf
	v_add_f32_dpp v15, v255, v255 quad_perm:[1,0,3,2] row_mask:0xf bank_mask:0xf
	v_cndmask_b32_e32 v12, v14, v12, vcc
	v_cndmask_b32_e32 v13, v15, v13, vcc
	v_add_f32_dpp v18, v16, v16 quad_perm:[2,3,0,1] row_mask:0xf bank_mask:0xf
	v_add_f32_dpp v19, v17, v17 quad_perm:[2,3,0,1] row_mask:0xf bank_mask:0xf
	v_cndmask_b32_e64 v16, v19, v18, s[4:5]
	v_cndmask_b32_e64 v21, v16, v20, s[6:7]
	v_cndmask_b32_e64 v22, v20, v16, s[6:7]
	s_waitcnt vmcnt(1)
	v_pk_mul_f32 v[252:253], v[236:237], v[4:5] op_sel_hi:[1,0]
	v_pk_mul_f32 v[254:255], v[244:245], v[4:5] op_sel_hi:[1,0]
	v_pk_fma_f32 v[252:253], v[238:239], v[4:5], v[252:253] op_sel:[0,1,0]
	v_pk_fma_f32 v[254:255], v[246:247], v[4:5], v[254:255] op_sel:[0,1,0]
	v_pk_fma_f32 v[252:253], v[240:241], v[6:7], v[252:253] op_sel_hi:[1,0,1]
	v_pk_fma_f32 v[254:255], v[248:249], v[6:7], v[254:255] op_sel_hi:[1,0,1]
	v_pk_fma_f32 v[252:253], v[242:243], v[6:7], v[252:253] op_sel:[0,1,0]
	v_pk_fma_f32 v[254:255], v[250:251], v[6:7], v[254:255] op_sel:[0,1,0]
	v_add_f32_dpp v20, v22, v21 row_ror:4 row_mask:0xf bank_mask:0xf
	v_cndmask_b32_e64 v29, v20, v28, s[64:65]
	v_cndmask_b32_e64 v30, v28, v20, s[64:65]
	v_add_f32_dpp v8, v140, v140 quad_perm:[1,0,3,2] row_mask:0xf bank_mask:0xf
	v_add_f32_dpp v9, v141, v141 quad_perm:[1,0,3,2] row_mask:0xf bank_mask:0xf
	v_add_f32_dpp v10, v142, v142 quad_perm:[1,0,3,2] row_mask:0xf bank_mask:0xf
	v_add_f32_dpp v11, v143, v143 quad_perm:[1,0,3,2] row_mask:0xf bank_mask:0xf
	v_cndmask_b32_e32 v8, v10, v8, vcc
	v_cndmask_b32_e32 v9, v11, v9, vcc
	v_add_f32_dpp v14, v12, v12 quad_perm:[2,3,0,1] row_mask:0xf bank_mask:0xf
	v_add_f32_dpp v15, v13, v13 quad_perm:[2,3,0,1] row_mask:0xf bank_mask:0xf
	v_cndmask_b32_e64 v12, v15, v14, s[4:5]
	s_waitcnt vmcnt(0)
; DI void lbar() { asm volatile("s_waitcnt lgkmcnt(0)" ::: "memory"); __builtin_amdgcn_s_barrier(); asm volatile("" ::: "memory"); }
; DI float wave_sum(float v) { for (int o = 32; o >= 1; o >>= 1) v += __shfl_xor(v, o); return v; }
; DI void attn_sample_item(const Params& p, int item, ldsp lds, int tid_) {
;     ...
;   SC_SCORE(kvA, 0)
;   SC_SCORE(kvB, 1)
;     ...
;   for (int j = 0; j < 16; ++j) vvA[j] = __builtin_nontemporal_load((const f32x4*)(cv + (size_t)(wid * 32 + j) * 1024 + lane * 4));
;   lbar();
;   if (wid < 4) {
;     float v[4]; float mx = -1e30f;
; #pragma unroll
;     for (int j = 0; j < 4; ++j) { v[j] = SC[wid * 256 + j * 64 + lane]; mx = fmaxf(mx, v[j]); }
;     for (int o = 32; o >= 1; o >>= 1) mx = fmaxf(mx, __shfl_xor(mx, o));
;     float s = 0.f;
; #pragma unroll
;     for (int j = 0; j < 4; ++j) { v[j] = __expf(v[j] - mx); s += v[j]; }
;     s = wave_sum(s); const float inv = 1.f / s;
; #pragma unroll
;     for (int j = 0; j < 4; ++j) SC[wid * 256 + j * 64 + lane] = v[j] * inv;
;   }
; #pragma unroll
;   for (int j = 0; j < 16; ++j) vvB[j] = __builtin_nontemporal_load((const f32x4*)(cv + (size_t)(wid * 32 + 16 + j) * 1024 + lane * 4));
	v_pk_mul_f32 v[140:141], v[236:237], v[0:1] op_sel_hi:[1,0]
	v_pk_mul_f32 v[142:143], v[244:245], v[0:1] op_sel_hi:[1,0]
	v_pk_fma_f32 v[140:141], v[238:239], v[0:1], v[140:141] op_sel:[0,1,0]
	v_pk_fma_f32 v[142:143], v[246:247], v[0:1], v[142:143] op_sel:[0,1,0]
	v_pk_fma_f32 v[140:141], v[240:241], v[2:3], v[140:141] op_sel_hi:[1,0,1]
	v_pk_fma_f32 v[142:143], v[248:249], v[2:3], v[142:143] op_sel_hi:[1,0,1]
	v_pk_fma_f32 v[140:141], v[242:243], v[2:3], v[140:141] op_sel:[0,1,0]
	v_pk_fma_f32 v[142:143], v[250:251], v[2:3], v[142:143] op_sel:[0,1,0]
	v_add_f32_dpp v28, v30, v29 row_ror:8 row_mask:0xf bank_mask:0xf
	v_add_f32_dpp v4, v252, v252 quad_perm:[1,0,3,2] row_mask:0xf bank_mask:0xf
	v_add_f32_dpp v5, v253, v253 quad_perm:[1,0,3,2] row_mask:0xf bank_mask:0xf
	v_add_f32_dpp v6, v254, v254 quad_perm:[1,0,3,2] row_mask:0xf bank_mask:0xf
	v_add_f32_dpp v7, v255, v255 quad_perm:[1,0,3,2] row_mask:0xf bank_mask:0xf
	v_cndmask_b32_e32 v4, v6, v4, vcc
	v_cndmask_b32_e32 v5, v7, v5, vcc
	v_add_f32_dpp v10, v8, v8 quad_perm:[2,3,0,1] row_mask:0xf bank_mask:0xf
	v_add_f32_dpp v11, v9, v9 quad_perm:[2,3,0,1] row_mask:0xf bank_mask:0xf
	v_cndmask_b32_e64 v8, v11, v10, s[4:5]
	v_cndmask_b32_e64 v13, v8, v12, s[6:7]
	v_cndmask_b32_e64 v14, v12, v8, s[6:7]
	s_nop 1
	v_add_f32_dpp v12, v14, v13 row_ror:4 row_mask:0xf bank_mask:0xf
	v_add_f32_dpp v0, v140, v140 quad_perm:[1,0,3,2] row_mask:0xf bank_mask:0xf
	v_add_f32_dpp v1, v141, v141 quad_perm:[1,0,3,2] row_mask:0xf bank_mask:0xf
	v_add_f32_dpp v2, v142, v142 quad_perm:[1,0,3,2] row_mask:0xf bank_mask:0xf
	v_add_f32_dpp v3, v143, v143 quad_perm:[1,0,3,2] row_mask:0xf bank_mask:0xf
	v_cndmask_b32_e32 v0, v2, v0, vcc
	v_cndmask_b32_e32 v1, v3, v1, vcc
	v_add_f32_dpp v6, v4, v4 quad_perm:[2,3,0,1] row_mask:0xf bank_mask:0xf
	v_add_f32_dpp v7, v5, v5 quad_perm:[2,3,0,1] row_mask:0xf bank_mask:0xf
	v_cndmask_b32_e64 v4, v7, v6, s[4:5]
	v_add_f32_dpp v2, v0, v0 quad_perm:[2,3,0,1] row_mask:0xf bank_mask:0xf
	v_add_f32_dpp v3, v1, v1 quad_perm:[2,3,0,1] row_mask:0xf bank_mask:0xf
	v_cndmask_b32_e64 v0, v3, v2, s[4:5]
	v_cndmask_b32_e64 v5, v0, v4, s[6:7]
	v_cndmask_b32_e64 v6, v4, v0, s[6:7]
	s_nop 1
	v_add_f32_dpp v4, v6, v5 row_ror:4 row_mask:0xf bank_mask:0xf
	v_cndmask_b32_e64 v13, v4, v12, s[64:65]
	v_cndmask_b32_e64 v14, v12, v4, s[64:65]
	s_nop 1
	v_add_f32_dpp v12, v14, v13 row_ror:8 row_mask:0xf bank_mask:0xf
	s_nop 1
	v_permlane16_swap_b32_e32 v28, v12
	v_add_f32_e32 v28, v28, v12
	s_nop 1
	v_permlane32_swap_b32_e32 v60, v28
	v_add_f32_e32 v60, v60, v28
	ds_write_b32 v235, v60 offset:64
	v_add_u32_e32 v100, v162, v144
	global_load_dwordx4 v[100:103], v100, s[66:67] nt
	v_add_u32_e32 v92, v166, v144
	global_load_dwordx4 v[92:95], v92, s[66:67] nt
	v_add_u32_e32 v112, v168, v144
	global_load_dwordx4 v[112:115], v112, s[66:67] nt
	v_add_u32_e32 v108, v172, v144
	global_load_dwordx4 v[108:111], v108, s[66:67] nt
	v_add_u32_e32 v120, v176, v144
	global_load_dwordx4 v[120:123], v120, s[66:67] nt
	v_add_u32_e32 v116, v180, v144
	global_load_dwordx4 v[116:119], v116, s[66:67] nt
	v_add_u32_e32 v124, v182, v144
	global_load_dwordx4 v[124:127], v124, s[66:67] nt
	v_add_u32_e32 v104, v186, v144
	global_load_dwordx4 v[104:107], v104, s[66:67] nt
	v_add_u32_e32 v68, v190, v144
	global_load_dwordx4 v[68:71], v68, s[66:67] nt
	v_add_u32_e32 v64, v194, v144
	global_load_dwordx4 v[64:67], v64, s[66:67] nt
	v_add_u32_e32 v80, v198, v144
	global_load_dwordx4 v[80:83], v80, s[66:67] nt
	v_add_u32_e32 v76, v200, v144
	global_load_dwordx4 v[76:79], v76, s[66:67] nt
	v_add_u32_e32 v88, v202, v144
	global_load_dwordx4 v[88:91], v88, s[66:67] nt
	v_add_u32_e32 v84, v204, v144
	global_load_dwordx4 v[84:87], v84, s[66:67] nt
	v_add_u32_e32 v96, v206, v144
	global_load_dwordx4 v[96:99], v96, s[66:67] nt
	v_add_u32_e32 v72, v208, v144
	global_load_dwordx4 v[72:75], v72, s[66:67] nt
	v_add_u32_e32 v40, v146, v144
	global_load_dwordx4 v[40:43], v40, s[66:67] nt
	v_add_u32_e32 v36, v148, v144
	global_load_dwordx4 v[36:39], v36, s[66:67] nt
	v_add_u32_e32 v48, v150, v144
	global_load_dwordx4 v[48:51], v48, s[66:67] nt
	v_add_u32_e32 v44, v152, v144
	global_load_dwordx4 v[44:47], v44, s[66:67] nt
	v_add_u32_e32 v56, v154, v144
	global_load_dwordx4 v[56:59], v56, s[66:67] nt
	v_add_u32_e32 v52, v156, v144
	global_load_dwordx4 v[52:55], v52, s[66:67] nt
	v_add_u32_e32 v60, v158, v144
	global_load_dwordx4 v[60:63], v60, s[66:67] nt
	v_add_u32_e32 v32, v160, v144
	global_load_dwordx4 v[32:35], v32, s[66:67] nt
	v_add_u32_e32 v12, v164, v144
	global_load_dwordx4 v[12:15], v12, s[66:67] nt
	v_add_u32_e32 v4, v170, v144
	global_load_dwordx4 v[4:7], v4, s[66:67] nt
	v_add_u32_e32 v20, v174, v144
	global_load_dwordx4 v[20:23], v20, s[66:67] nt
	v_add_u32_e32 v8, v178, v144
	global_load_dwordx4 v[8:11], v8, s[66:67] nt
	v_add_u32_e32 v24, v184, v144
	global_load_dwordx4 v[24:27], v24, s[66:67] nt
	v_add_u32_e32 v16, v188, v144
	global_load_dwordx4 v[16:19], v16, s[66:67] nt
	v_add_u32_e32 v28, v192, v144
	global_load_dwordx4 v[28:31], v28, s[66:67] nt
	v_add_u32_e32 v0, v196, v144
	global_load_dwordx4 v[0:3], v0, s[66:67] nt
	v_lshlrev_b32_e32 v240, 2, v223
	s_waitcnt lgkmcnt(0)
	s_barrier
	v_cmp_gt_i32_e32 vcc, 4, v210
	s_and_saveexec_b64 s[4:5], vcc
	s_cbranch_execz .LBB0_1603

; DI float wave_sum(float v) { for (int o = 32; o >= 1; o >>= 1) v += __shfl_xor(v, o); return v; }
; DI void attn_sample_item(const Params& p, int item, ldsp lds, int tid_) {
;     ...
;   if (wid < 4) {
;     float v[4]; float mx = -1e30f;
; #pragma unroll
;     for (int j = 0; j < 4; ++j) { v[j] = SC[wid * 256 + j * 64 + lane]; mx = fmaxf(mx, v[j]); }
;     for (int o = 32; o >= 1; o >>= 1) mx = fmaxf(mx, __shfl_xor(mx, o));
;     float s = 0.f;
; #pragma unroll
;     for (int j = 0; j < 4; ++j) { v[j] = __expf(v[j] - mx); s += v[j]; }
;     s = wave_sum(s); const float inv = 1.f / s;
; #pragma unroll
;     for (int j = 0; j < 4; ++j) SC[wid * 256 + j * 64 + lane] = v[j] * inv;
;   }
	v_lshlrev_b32_e32 v241, 10, v210
	v_add3_u32 v244, 16, v241, v240
	ds_read2st64_b32 v[240:241], v244 offset1:1
	ds_read2st64_b32 v[242:243], v244 offset0:2 offset1:3
	s_waitcnt lgkmcnt(1)
	v_max3_f32 v245, v240, s39, v241
	s_waitcnt lgkmcnt(0)
	v_max3_f32 v245, v245, v242, v243
	ds_bpermute_b32 v246, v133, v245
	s_waitcnt lgkmcnt(0)
	v_max_f32_e32 v246, v246, v246
	v_max_f32_e32 v245, v245, v246
	ds_bpermute_b32 v246, v132, v245
	s_waitcnt lgkmcnt(0)
	v_max_f32_e32 v246, v246, v246
	v_max_f32_e32 v245, v245, v246
	ds_bpermute_b32 v246, v131, v245
	s_waitcnt lgkmcnt(0)
	v_max_f32_e32 v246, v246, v246
	v_max_f32_e32 v245, v245, v246
	ds_bpermute_b32 v246, v130, v245
	s_waitcnt lgkmcnt(0)
	v_max_f32_e32 v246, v246, v246
	v_max_f32_e32 v245, v245, v246
	ds_bpermute_b32 v246, v129, v245
	s_waitcnt lgkmcnt(0)
	v_max_f32_e32 v246, v246, v246
	v_max_f32_e32 v245, v245, v246
	ds_bpermute_b32 v246, v128, v245
	s_waitcnt lgkmcnt(0)
	v_max_f32_e32 v246, v246, v246
	v_max_f32_e32 v245, v245, v246
	v_sub_f32_e32 v240, v240, v245
	v_sub_f32_e32 v241, v241, v245
	v_mul_f32_e32 v240, 0x3fb8aa3b, v240
	v_sub_f32_e32 v242, v242, v245
	v_mul_f32_e32 v241, 0x3fb8aa3b, v241
	v_exp_f32_e32 v240, v240
	v_sub_f32_e32 v243, v243, v245
	v_mul_f32_e32 v242, 0x3fb8aa3b, v242
	v_exp_f32_e32 v241, v241
	v_mul_f32_e32 v243, 0x3fb8aa3b, v243
	v_exp_f32_e32 v242, v242
	v_exp_f32_e32 v243, v243
	v_add_f32_e32 v245, 0, v240
	v_add_f32_e32 v245, v241, v245
	v_add_f32_e32 v245, v242, v245
	v_add_f32_e32 v245, v243, v245
	ds_bpermute_b32 v246, v133, v245
	s_waitcnt lgkmcnt(0)
	v_add_f32_e32 v245, v245, v246
	ds_bpermute_b32 v246, v132, v245
	s_waitcnt lgkmcnt(0)
	v_add_f32_e32 v245, v245, v246
	ds_bpermute_b32 v246, v131, v245
	s_waitcnt lgkmcnt(0)
	v_add_f32_e32 v245, v245, v246
	ds_bpermute_b32 v246, v130, v245
	s_waitcnt lgkmcnt(0)
	v_add_f32_e32 v245, v245, v246
	ds_bpermute_b32 v246, v129, v245
	s_waitcnt lgkmcnt(0)
	v_add_f32_e32 v245, v245, v246
	ds_bpermute_b32 v246, v128, v245
	s_waitcnt lgkmcnt(0)
	v_add_f32_e32 v245, v245, v246
	v_div_scale_f32 v246, s[6:7], v245, v245, 1.0
	v_rcp_f32_e32 v247, v246
	v_div_scale_f32 v248, vcc, 1.0, v245, 1.0
	v_fma_f32 v249, -v246, v247, 1.0
	v_fmac_f32_e32 v247, v249, v247
	v_mul_f32_e32 v249, v248, v247
	v_fma_f32 v250, -v246, v249, v248
	v_fmac_f32_e32 v249, v250, v247
	v_fma_f32 v246, -v246, v249, v248
	v_div_fmas_f32 v246, v246, v247, v249
	v_div_fixup_f32 v245, v246, v245, 1.0
	v_mul_f32_e32 v240, v240, v245
	v_mul_f32_e32 v241, v241, v245
	v_mul_f32_e32 v242, v242, v245
	v_mul_f32_e32 v243, v243, v245
	ds_write2st64_b32 v244, v240, v241 offset1:1
	ds_write2st64_b32 v244, v242, v243 offset0:2 offset1:3
	s_branch .LBB0_1603

; DI void attn_sample_item(const Params& p, int item, ldsp lds, int tid_) {
;     ...
;   for (int t = 0; t < 4; ++t) { f32x4 a = {0.f, 0.f, 0.f, 0.f}; const float* pp = (const float*)(p.ws + B_PART) + (size_t)(b * 4 + t) * 1024 + h * 256 + lane * 4;
; #pragma unroll
;     for (int kp = 0; kp < 4; ++kp) a += *(const f32x4*)(pp + (size_t)kp * 512 * 1024);
;     q[t][0] = a[0] * 0.0625f; q[t][1] = a[1] * 0.0625f; q[t][2] = a[2] * 0.0625f; q[t][3] = a[3] * 0.0625f; }
;   const bool b0 = lane & 1, b1 = lane & 2;
;   f32x4 kvA[16], kvB[16];
; #pragma unroll
;   for (int j = 0; j < 16; ++j) kvA[j] = __builtin_nontemporal_load((const f32x4*)(ck + (size_t)(wid * 32 + j) * 1024 + lane * 4));
; #pragma unroll
;   for (int j = 0; j < 16; ++j) kvB[j] = __builtin_nontemporal_load((const f32x4*)(ck + (size_t)(wid * 32 + 16 + j) * 1024 + lane * 4));
.LBB0_1676:
	s_ashr_i32 s4, s38, 2
	s_ashr_i32 s5, s4, 31
	s_lshl_b64 s[4:5], s[4:5], 18
	s_and_b32 s24, s0, 0x300
	v_mov_b32_e32 v222, v212
	s_or_b32 s4, s4, s24
	s_and_b32 s26, s38, -4
	s_lshl_b32 s6, s24, 2
	s_add_u32 s6, s36, s6
	v_and_b32_e32 v223, 63, v222
	s_addc_u32 s7, s37, 0
	v_lshlrev_b32_e32 v144, 4, v223
	s_ashr_i32 s27, s26, 31
	v_lshl_add_u64 v[48:49], s[6:7], 0, v[144:145]
	s_lshl_b64 s[6:7], s[26:27], 12
	v_lshl_add_u64 v[8:9], v[48:49], 0, s[6:7]
	v_add_co_u32_e32 v10, vcc, s3, v8
	s_or_b32 s6, s26, 1
	s_nop 0
	v_addc_co_u32_e32 v11, vcc, 0, v9, vcc
	global_load_dwordx4 v[0:3], v[8:9], off
	global_load_dwordx4 v[4:7], v[10:11], off
	v_add_co_u32_e32 v10, vcc, s33, v8
	s_ashr_i32 s7, s6, 31
	s_nop 0
	v_addc_co_u32_e32 v11, vcc, 0, v9, vcc
	v_add_co_u32_e32 v12, vcc, s34, v8
	s_lshl_b64 s[6:7], s[6:7], 12
	s_nop 0
	v_addc_co_u32_e32 v13, vcc, 0, v9, vcc
	v_lshl_add_u64 v[24:25], v[48:49], 0, s[6:7]
	v_add_co_u32_e32 v20, vcc, s3, v24
	s_or_b32 s6, s26, 2
	s_nop 0
	v_addc_co_u32_e32 v21, vcc, 0, v25, vcc
	v_add_co_u32_e32 v26, vcc, s33, v24
	s_ashr_i32 s7, s6, 31
	s_nop 0
	v_addc_co_u32_e32 v27, vcc, 0, v25, vcc
	v_add_co_u32_e32 v28, vcc, s34, v24
	s_lshl_b64 s[6:7], s[6:7], 12
	s_nop 0
	v_addc_co_u32_e32 v29, vcc, 0, v25, vcc
	v_lshl_add_u64 v[44:45], v[48:49], 0, s[6:7]
	global_load_dwordx4 v[8:11], v[10:11], off
	s_nop 0
	global_load_dwordx4 v[12:15], v[12:13], off
	s_nop 0
	global_load_dwordx4 v[16:19], v[24:25], off
	s_nop 0
	global_load_dwordx4 v[20:23], v[20:21], off
	v_add_co_u32_e32 v36, vcc, s3, v44
	global_load_dwordx4 v[24:27], v[26:27], off
	s_nop 0
	global_load_dwordx4 v[28:31], v[28:29], off
	v_addc_co_u32_e32 v37, vcc, 0, v45, vcc
	v_add_co_u32_e32 v40, vcc, s33, v44
	global_load_dwordx4 v[32:35], v[44:45], off
	s_nop 0
	global_load_dwordx4 v[36:39], v[36:37], off
	v_addc_co_u32_e32 v41, vcc, 0, v45, vcc
	v_add_co_u32_e32 v44, vcc, s34, v44
	global_load_dwordx4 v[40:43], v[40:41], off
	s_nop 0
	v_addc_co_u32_e32 v45, vcc, 0, v45, vcc
	global_load_dwordx4 v[44:47], v[44:45], off
	s_or_b32 s6, s38, 3
	s_ashr_i32 s7, s6, 31
	s_lshl_b64 s[6:7], s[6:7], 12
	s_lshl_b64 s[28:29], s[4:5], 2
	s_add_u32 s4, s12, s28
	s_addc_u32 s5, s13, s29
	s_waitcnt vmcnt(11)
	v_pk_add_f32 v[2:3], v[2:3], 0 op_sel_hi:[1,0]
	v_pk_add_f32 v[0:1], v[0:1], 0 op_sel_hi:[1,0]
	s_waitcnt vmcnt(10)
	v_pk_add_f32 v[2:3], v[2:3], v[6:7]
	v_pk_add_f32 v[0:1], v[0:1], v[4:5]
	s_waitcnt vmcnt(9)
	v_pk_add_f32 v[2:3], v[2:3], v[10:11]
	s_waitcnt vmcnt(7)
	v_pk_add_f32 v[4:5], v[18:19], 0 op_sel_hi:[1,0]
	v_pk_add_f32 v[6:7], v[16:17], 0 op_sel_hi:[1,0]
	v_pk_add_f32 v[0:1], v[0:1], v[8:9]
	s_waitcnt vmcnt(6)
	v_pk_add_f32 v[4:5], v[4:5], v[22:23]
	v_pk_add_f32 v[6:7], v[6:7], v[20:21]
	v_pk_add_f32 v[2:3], v[2:3], v[14:15]
	v_pk_add_f32 v[0:1], v[0:1], v[12:13]
	s_waitcnt vmcnt(5)
	v_pk_add_f32 v[4:5], v[4:5], v[26:27]
	v_pk_add_f32 v[6:7], v[6:7], v[24:25]
	v_mul_f32_e32 v228, 0x3d800000, v0
	v_mul_f32_e32 v231, 0x3d800000, v1
	v_mul_f32_e32 v229, 0x3d800000, v2
	v_mul_f32_e32 v225, 0x3d800000, v3
	s_waitcnt vmcnt(4)
	v_pk_add_f32 v[0:1], v[4:5], v[30:31]
	v_pk_add_f32 v[2:3], v[6:7], v[28:29]
	v_mul_f32_e32 v227, 0x3d800000, v0
	v_mul_f32_e32 v226, 0x3d800000, v2
	v_mul_f32_e32 v230, 0x3d800000, v3
	v_mul_f32_e32 v224, 0x3d800000, v1
	s_waitcnt vmcnt(3)
	v_pk_add_f32 v[0:1], v[34:35], 0 op_sel_hi:[1,0]
	v_pk_add_f32 v[2:3], v[32:33], 0 op_sel_hi:[1,0]
	s_waitcnt vmcnt(2)
	v_pk_add_f32 v[0:1], v[0:1], v[38:39]
	v_pk_add_f32 v[2:3], v[2:3], v[36:37]
	s_waitcnt vmcnt(1)
	v_pk_add_f32 v[0:1], v[0:1], v[42:43]
	v_pk_add_f32 v[2:3], v[2:3], v[40:41]
	s_waitcnt vmcnt(0)
	v_pk_add_f32 v[210:211], v[0:1], v[46:47]
	v_pk_add_f32 v[0:1], v[2:3], v[44:45]
	v_mul_f32_e32 v233, 0x3d800000, v210
	v_mul_f32_e32 v232, 0x3d800000, v0
	v_mul_f32_e32 v234, 0x3d800000, v1
	v_lshl_add_u64 v[0:1], v[48:49], 0, s[6:7]
	v_add_co_u32_e32 v2, vcc, s3, v0
	v_ashrrev_i32_e32 v210, 6, v222
	s_nop 0
	v_addc_co_u32_e32 v3, vcc, 0, v1, vcc
	global_load_dwordx4 v[128:131], v[0:1], off
	global_load_dwordx4 v[132:135], v[2:3], off
	v_add_co_u32_e32 v2, vcc, s33, v0
	v_mul_f32_e32 v211, 0x3d800000, v211
	s_nop 0
	v_addc_co_u32_e32 v3, vcc, 0, v1, vcc
	v_add_co_u32_e32 v0, vcc, s34, v0
	v_cmp_lt_i32_e64 s[6:7], v218, v216
	s_nop 0
	v_addc_co_u32_e32 v1, vcc, 0, v1, vcc
	global_load_dwordx4 v[136:139], v[2:3], off
	global_load_dwordx4 v[140:143], v[0:1], off
	v_lshlrev_b32_e32 v0, 5, v210
	v_ashrrev_i32_e32 v1, 31, v0
	v_or_b32_e32 v6, 1, v0
	v_lshl_add_u64 v[2:3], s[4:5], 0, v[144:145]
	v_lshlrev_b64 v[158:159], 12, v[0:1]
	v_ashrrev_i32_e32 v7, 31, v6
	v_lshl_add_u64 v[4:5], v[2:3], 0, v[158:159]
	v_lshlrev_b64 v[162:163], 12, v[6:7]
	v_lshl_add_u64 v[6:7], v[2:3], 0, v[162:163]
	global_load_dwordx4 v[124:127], v[4:5], off nt
	global_load_dwordx4 v[120:123], v[6:7], off nt
	v_or_b32_e32 v4, 2, v0
	v_ashrrev_i32_e32 v5, 31, v4
	v_or_b32_e32 v6, 3, v0
	v_lshlrev_b64 v[164:165], 12, v[4:5]
	v_ashrrev_i32_e32 v7, 31, v6
	v_lshl_add_u64 v[4:5], v[2:3], 0, v[164:165]
	v_lshlrev_b64 v[168:169], 12, v[6:7]
	v_lshl_add_u64 v[6:7], v[2:3], 0, v[168:169]
	global_load_dwordx4 v[116:119], v[4:5], off nt
	global_load_dwordx4 v[112:115], v[6:7], off nt
	v_or_b32_e32 v4, 4, v0
	v_ashrrev_i32_e32 v5, 31, v4
	v_or_b32_e32 v6, 5, v0
	v_lshlrev_b64 v[172:173], 12, v[4:5]
	v_ashrrev_i32_e32 v7, 31, v6
	v_lshl_add_u64 v[4:5], v[2:3], 0, v[172:173]
	v_lshlrev_b64 v[176:177], 12, v[6:7]
	v_lshl_add_u64 v[6:7], v[2:3], 0, v[176:177]
	global_load_dwordx4 v[108:111], v[4:5], off nt
	global_load_dwordx4 v[104:107], v[6:7], off nt
	v_or_b32_e32 v4, 6, v0
	v_ashrrev_i32_e32 v5, 31, v4
	v_or_b32_e32 v6, 7, v0
; DI void attn_sample_item(const Params& p, int item, ldsp lds, int tid_) {
;     ...
;   for (int j = 0; j < 16; ++j) kvA[j] = __builtin_nontemporal_load((const f32x4*)(ck + (size_t)(wid * 32 + j) * 1024 + lane * 4));
; #pragma unroll
;   for (int j = 0; j < 16; ++j) kvB[j] = __builtin_nontemporal_load((const f32x4*)(ck + (size_t)(wid * 32 + 16 + j) * 1024 + lane * 4));
	v_lshlrev_b64 v[180:181], 12, v[4:5]
	v_ashrrev_i32_e32 v7, 31, v6
	v_lshl_add_u64 v[4:5], v[2:3], 0, v[180:181]
	v_lshlrev_b64 v[184:185], 12, v[6:7]
	v_lshl_add_u64 v[6:7], v[2:3], 0, v[184:185]
	global_load_dwordx4 v[100:103], v[4:5], off nt
	global_load_dwordx4 v[96:99], v[6:7], off nt
	v_or_b32_e32 v4, 8, v0
	v_ashrrev_i32_e32 v5, 31, v4
	v_or_b32_e32 v6, 9, v0
	v_lshlrev_b64 v[188:189], 12, v[4:5]
	v_ashrrev_i32_e32 v7, 31, v6
	v_lshl_add_u64 v[4:5], v[2:3], 0, v[188:189]
	v_lshlrev_b64 v[192:193], 12, v[6:7]
	v_lshl_add_u64 v[6:7], v[2:3], 0, v[192:193]
	global_load_dwordx4 v[92:95], v[4:5], off nt
	global_load_dwordx4 v[88:91], v[6:7], off nt
	v_or_b32_e32 v4, 10, v0
	v_ashrrev_i32_e32 v5, 31, v4
	v_or_b32_e32 v6, 11, v0
	v_lshlrev_b64 v[196:197], 12, v[4:5]
	v_ashrrev_i32_e32 v7, 31, v6
	v_lshl_add_u64 v[4:5], v[2:3], 0, v[196:197]
	v_lshlrev_b64 v[200:201], 12, v[6:7]
	v_lshl_add_u64 v[6:7], v[2:3], 0, v[200:201]
	global_load_dwordx4 v[84:87], v[4:5], off nt
	global_load_dwordx4 v[80:83], v[6:7], off nt
	v_or_b32_e32 v4, 12, v0
	v_ashrrev_i32_e32 v5, 31, v4
	v_or_b32_e32 v6, 13, v0
	v_lshlrev_b64 v[202:203], 12, v[4:5]
	v_ashrrev_i32_e32 v7, 31, v6
	v_lshl_add_u64 v[4:5], v[2:3], 0, v[202:203]
	v_lshlrev_b64 v[204:205], 12, v[6:7]
	v_lshl_add_u64 v[6:7], v[2:3], 0, v[204:205]
	global_load_dwordx4 v[76:79], v[4:5], off nt
	global_load_dwordx4 v[72:75], v[6:7], off nt
	v_or_b32_e32 v4, 14, v0
	v_ashrrev_i32_e32 v5, 31, v4
	v_or_b32_e32 v6, 15, v0
	v_lshlrev_b64 v[206:207], 12, v[4:5]
	v_ashrrev_i32_e32 v7, 31, v6
	v_lshl_add_u64 v[4:5], v[2:3], 0, v[206:207]
	v_lshlrev_b64 v[208:209], 12, v[6:7]
	v_lshl_add_u64 v[6:7], v[2:3], 0, v[208:209]
	global_load_dwordx4 v[68:71], v[4:5], off nt
	global_load_dwordx4 v[64:67], v[6:7], off nt
	v_or_b32_e32 v4, 16, v0
	v_ashrrev_i32_e32 v5, 31, v4
	v_or_b32_e32 v6, 17, v0
	v_lshlrev_b64 v[146:147], 12, v[4:5]
	v_ashrrev_i32_e32 v7, 31, v6
	v_lshl_add_u64 v[4:5], v[2:3], 0, v[146:147]
	v_lshlrev_b64 v[148:149], 12, v[6:7]
	v_lshl_add_u64 v[6:7], v[2:3], 0, v[148:149]
	global_load_dwordx4 v[60:63], v[4:5], off nt
	global_load_dwordx4 v[56:59], v[6:7], off nt
	v_or_b32_e32 v4, 18, v0
	v_ashrrev_i32_e32 v5, 31, v4
	v_or_b32_e32 v6, 19, v0
	v_lshlrev_b64 v[150:151], 12, v[4:5]
	v_ashrrev_i32_e32 v7, 31, v6
	v_lshl_add_u64 v[4:5], v[2:3], 0, v[150:151]
	v_lshlrev_b64 v[152:153], 12, v[6:7]
	v_lshl_add_u64 v[6:7], v[2:3], 0, v[152:153]
	global_load_dwordx4 v[52:55], v[4:5], off nt
	global_load_dwordx4 v[48:51], v[6:7], off nt
	v_or_b32_e32 v4, 20, v0
	v_ashrrev_i32_e32 v5, 31, v4
	v_or_b32_e32 v6, 21, v0
	v_lshlrev_b64 v[154:155], 12, v[4:5]
	v_ashrrev_i32_e32 v7, 31, v6
	v_lshl_add_u64 v[4:5], v[2:3], 0, v[154:155]
	v_lshlrev_b64 v[156:157], 12, v[6:7]
	v_lshl_add_u64 v[6:7], v[2:3], 0, v[156:157]
	global_load_dwordx4 v[44:47], v[4:5], off nt
	global_load_dwordx4 v[40:43], v[6:7], off nt
	v_or_b32_e32 v4, 22, v0
	v_ashrrev_i32_e32 v5, 31, v4
	v_or_b32_e32 v6, 23, v0
	v_lshlrev_b64 v[160:161], 12, v[4:5]
	v_ashrrev_i32_e32 v7, 31, v6
	v_lshl_add_u64 v[4:5], v[2:3], 0, v[160:161]
	v_lshlrev_b64 v[166:167], 12, v[6:7]
	v_lshl_add_u64 v[6:7], v[2:3], 0, v[166:167]
	global_load_dwordx4 v[36:39], v[4:5], off nt
	global_load_dwordx4 v[32:35], v[6:7], off nt
	v_or_b32_e32 v4, 24, v0
	v_ashrrev_i32_e32 v5, 31, v4
	v_or_b32_e32 v6, 25, v0
	v_lshlrev_b64 v[170:171], 12, v[4:5]
	v_ashrrev_i32_e32 v7, 31, v6
	v_lshl_add_u64 v[4:5], v[2:3], 0, v[170:171]
	v_lshlrev_b64 v[174:175], 12, v[6:7]
	v_lshl_add_u64 v[6:7], v[2:3], 0, v[174:175]
	global_load_dwordx4 v[28:31], v[4:5], off nt
	global_load_dwordx4 v[24:27], v[6:7], off nt
	v_or_b32_e32 v4, 26, v0
	v_ashrrev_i32_e32 v5, 31, v4
	v_or_b32_e32 v6, 27, v0
	v_lshlrev_b64 v[178:179], 12, v[4:5]
	v_ashrrev_i32_e32 v7, 31, v6
	v_lshl_add_u64 v[4:5], v[2:3], 0, v[178:179]
	v_lshlrev_b64 v[182:183], 12, v[6:7]
	v_lshl_add_u64 v[6:7], v[2:3], 0, v[182:183]
	global_load_dwordx4 v[20:23], v[4:5], off nt
	global_load_dwordx4 v[16:19], v[6:7], off nt
	v_or_b32_e32 v4, 28, v0
	v_ashrrev_i32_e32 v5, 31, v4
	v_or_b32_e32 v6, 29, v0
	v_lshlrev_b64 v[186:187], 12, v[4:5]
	v_ashrrev_i32_e32 v7, 31, v6
	v_lshl_add_u64 v[4:5], v[2:3], 0, v[186:187]
	v_lshlrev_b64 v[190:191], 12, v[6:7]
	v_lshl_add_u64 v[6:7], v[2:3], 0, v[190:191]
	global_load_dwordx4 v[12:15], v[4:5], off nt
	global_load_dwordx4 v[8:11], v[6:7], off nt
	v_or_b32_e32 v4, 30, v0
	v_or_b32_e32 v0, 31, v0
	v_ashrrev_i32_e32 v5, 31, v4
	v_ashrrev_i32_e32 v1, 31, v0
	v_lshlrev_b64 v[194:195], 12, v[4:5]
	v_lshlrev_b64 v[198:199], 12, v[0:1]
	v_lshl_add_u64 v[4:5], v[2:3], 0, v[194:195]
	v_lshl_add_u64 v[0:1], v[2:3], 0, v[198:199]
	global_load_dwordx4 v[4:7], v[4:5], off nt
	s_nop 0
	global_load_dwordx4 v[0:3], v[0:1], off nt
	s_waitcnt vmcnt(35)
	v_pk_add_f32 v[128:129], v[128:129], 0 op_sel_hi:[1,0]
	v_pk_add_f32 v[130:131], v[130:131], 0 op_sel_hi:[1,0]
	s_waitcnt vmcnt(34)
	v_pk_add_f32 v[128:129], v[128:129], v[132:133]
	v_pk_add_f32 v[130:131], v[130:131], v[134:135]
	s_waitcnt vmcnt(33)
	v_pk_add_f32 v[128:129], v[128:129], v[136:137]
	v_pk_add_f32 v[130:131], v[130:131], v[138:139]
	s_waitcnt vmcnt(32)
; DI void attn_sample_item(const Params& p, int item, ldsp lds, int tid_) {
;     ...
;     q[t][0] = a[0] * 0.0625f; q[t][1] = a[1] * 0.0625f; q[t][2] = a[2] * 0.0625f; q[t][3] = a[3] * 0.0625f; }
;     ...
;   SC_SCORE(kvA, 0)
;   SC_SCORE(kvB, 1)
	v_pk_add_f32 v[128:129], v[128:129], v[140:141]
	v_pk_add_f32 v[130:131], v[130:131], v[142:143]
	v_mul_f32_e32 v138, 0x3d800000, v129
	v_mul_f32_e32 v135, 0x3d800000, v128
	v_mul_f32_e32 v134, 0x3d800000, v131
	s_add_u32 s66, s14, s28
	s_addc_u32 s67, s15, s29
	v_mul_f32_e32 v137, 0x3d800000, v130
	v_lshlrev_b32_e32 v128, 2, v215
	v_lshlrev_b32_e32 v129, 2, v217
	v_lshlrev_b32_e32 v130, 2, v218
	v_lshlrev_b32_e32 v131, 2, v219
	v_lshlrev_b32_e32 v132, 2, v220
	v_lshlrev_b32_e32 v133, 2, v221
	v_lshl_add_u32 v136, v210, 7, 16
	v_and_b32_e32 v139, 3, v223
	v_bfrev_b32_e32 v139, v139
	v_lshrrev_b32_e32 v139, 20, v139
	v_and_b32_e32 v235, -4, v223
	v_add3_u32 v235, v136, v139, v235
	v_mov_b32_e32 v236, v228
	v_mov_b32_e32 v237, v226
	v_mov_b32_e32 v238, v231
	v_mov_b32_e32 v239, v230
	v_mov_b32_e32 v240, v229
	v_mov_b32_e32 v241, v227
	v_mov_b32_e32 v242, v225
	v_mov_b32_e32 v243, v224
	v_mov_b32_e32 v244, v232
	v_mov_b32_e32 v245, v135
	v_mov_b32_e32 v246, v234
	v_mov_b32_e32 v247, v138
	v_mov_b32_e32 v248, v233
	v_mov_b32_e32 v249, v137
	v_mov_b32_e32 v250, v211
	v_mov_b32_e32 v251, v134
	s_mov_b32 vcc_lo, 0x55555555
	s_mov_b32 vcc_hi, 0x55555555
	s_mov_b32 s4, 0x33333333
	s_mov_b32 s5, 0x33333333
	s_mov_b32 s6, 0x0f0f0f0f
	s_mov_b32 s7, 0x0f0f0f0f
	s_mov_b32 s64, 0x00ff00ff
	s_mov_b32 s65, 0x00ff00ff
	s_waitcnt vmcnt(31)
	v_pk_mul_f32 v[252:253], v[236:237], v[124:125] op_sel_hi:[1,0]
	v_pk_mul_f32 v[254:255], v[244:245], v[124:125] op_sel_hi:[1,0]
	v_pk_fma_f32 v[252:253], v[238:239], v[124:125], v[252:253] op_sel:[0,1,0]
	v_pk_fma_f32 v[254:255], v[246:247], v[124:125], v[254:255] op_sel:[0,1,0]
	v_pk_fma_f32 v[252:253], v[240:241], v[126:127], v[252:253] op_sel_hi:[1,0,1]
	v_pk_fma_f32 v[254:255], v[248:249], v[126:127], v[254:255] op_sel_hi:[1,0,1]
	v_pk_fma_f32 v[252:253], v[242:243], v[126:127], v[252:253] op_sel:[0,1,0]
	v_pk_fma_f32 v[254:255], v[250:251], v[126:127], v[254:255] op_sel:[0,1,0]
	s_waitcnt vmcnt(30)
	v_pk_mul_f32 v[140:141], v[236:237], v[120:121] op_sel_hi:[1,0]
	v_pk_mul_f32 v[142:143], v[244:245], v[120:121] op_sel_hi:[1,0]
	v_pk_fma_f32 v[140:141], v[238:239], v[120:121], v[140:141] op_sel:[0,1,0]
	v_pk_fma_f32 v[142:143], v[246:247], v[120:121], v[142:143] op_sel:[0,1,0]
	v_pk_fma_f32 v[140:141], v[240:241], v[122:123], v[140:141] op_sel_hi:[1,0,1]
	v_pk_fma_f32 v[142:143], v[248:249], v[122:123], v[142:143] op_sel_hi:[1,0,1]
	v_pk_fma_f32 v[140:141], v[242:243], v[122:123], v[140:141] op_sel:[0,1,0]
	v_pk_fma_f32 v[142:143], v[250:251], v[122:123], v[142:143] op_sel:[0,1,0]
	v_add_f32_dpp v124, v252, v252 quad_perm:[1,0,3,2] row_mask:0xf bank_mask:0xf
	v_add_f32_dpp v125, v253, v253 quad_perm:[1,0,3,2] row_mask:0xf bank_mask:0xf
	v_add_f32_dpp v126, v254, v254 quad_perm:[1,0,3,2] row_mask:0xf bank_mask:0xf
	v_add_f32_dpp v127, v255, v255 quad_perm:[1,0,3,2] row_mask:0xf bank_mask:0xf
	v_cndmask_b32_e32 v124, v126, v124, vcc
	v_cndmask_b32_e32 v125, v127, v125, vcc
	s_waitcnt vmcnt(29)
	v_pk_mul_f32 v[252:253], v[236:237], v[116:117] op_sel_hi:[1,0]
	v_pk_mul_f32 v[254:255], v[244:245], v[116:117] op_sel_hi:[1,0]
	v_pk_fma_f32 v[252:253], v[238:239], v[116:117], v[252:253] op_sel:[0,1,0]
	v_pk_fma_f32 v[254:255], v[246:247], v[116:117], v[254:255] op_sel:[0,1,0]
	v_pk_fma_f32 v[252:253], v[240:241], v[118:119], v[252:253] op_sel_hi:[1,0,1]
	v_pk_fma_f32 v[254:255], v[248:249], v[118:119], v[254:255] op_sel_hi:[1,0,1]
	v_pk_fma_f32 v[252:253], v[242:243], v[118:119], v[252:253] op_sel:[0,1,0]
	v_pk_fma_f32 v[254:255], v[250:251], v[118:119], v[254:255] op_sel:[0,1,0]
	v_add_f32_dpp v120, v140, v140 quad_perm:[1,0,3,2] row_mask:0xf bank_mask:0xf
	v_add_f32_dpp v121, v141, v141 quad_perm:[1,0,3,2] row_mask:0xf bank_mask:0xf
	v_add_f32_dpp v122, v142, v142 quad_perm:[1,0,3,2] row_mask:0xf bank_mask:0xf
	v_add_f32_dpp v123, v143, v143 quad_perm:[1,0,3,2] row_mask:0xf bank_mask:0xf
	v_cndmask_b32_e32 v120, v122, v120, vcc
	v_cndmask_b32_e32 v121, v123, v121, vcc
	v_add_f32_dpp v126, v124, v124 quad_perm:[2,3,0,1] row_mask:0xf bank_mask:0xf
	v_add_f32_dpp v127, v125, v125 quad_perm:[2,3,0,1] row_mask:0xf bank_mask:0xf
	v_cndmask_b32_e64 v124, v127, v126, s[4:5]
	s_waitcnt vmcnt(28)
	v_pk_mul_f32 v[140:141], v[236:237], v[112:113] op_sel_hi:[1,0]
	v_pk_mul_f32 v[142:143], v[244:245], v[112:113] op_sel_hi:[1,0]
	v_pk_fma_f32 v[140:141], v[238:239], v[112:113], v[140:141] op_sel:[0,1,0]
	v_pk_fma_f32 v[142:143], v[246:247], v[112:113], v[142:143] op_sel:[0,1,0]
	v_pk_fma_f32 v[140:141], v[240:241], v[114:115], v[140:141] op_sel_hi:[1,0,1]
	v_pk_fma_f32 v[142:143], v[248:249], v[114:115], v[142:143] op_sel_hi:[1,0,1]
	v_pk_fma_f32 v[140:141], v[242:243], v[114:115], v[140:141] op_sel:[0,1,0]
	v_pk_fma_f32 v[142:143], v[250:251], v[114:115], v[142:143] op_sel:[0,1,0]
	v_add_f32_dpp v116, v252, v252 quad_perm:[1,0,3,2] row_mask:0xf bank_mask:0xf
	v_add_f32_dpp v117, v253, v253 quad_perm:[1,0,3,2] row_mask:0xf bank_mask:0xf
	v_add_f32_dpp v118, v254, v254 quad_perm:[1,0,3,2] row_mask:0xf bank_mask:0xf
	v_add_f32_dpp v119, v255, v255 quad_perm:[1,0,3,2] row_mask:0xf bank_mask:0xf
	v_cndmask_b32_e32 v116, v118, v116, vcc
	v_cndmask_b32_e32 v117, v119, v117, vcc
	v_add_f32_dpp v122, v120, v120 quad_perm:[2,3,0,1] row_mask:0xf bank_mask:0xf
	v_add_f32_dpp v123, v121, v121 quad_perm:[2,3,0,1] row_mask:0xf bank_mask:0xf
	v_cndmask_b32_e64 v120, v123, v122, s[4:5]
	v_cndmask_b32_e64 v125, v120, v124, s[6:7]
	v_cndmask_b32_e64 v126, v124, v120, s[6:7]
	s_waitcnt vmcnt(27)
; DI void attn_sample_item(const Params& p, int item, ldsp lds, int tid_) {
;     ...
;   SC_SCORE(kvA, 0)
;   SC_SCORE(kvB, 1)
	v_pk_mul_f32 v[252:253], v[236:237], v[108:109] op_sel_hi:[1,0]
	v_pk_mul_f32 v[254:255], v[244:245], v[108:109] op_sel_hi:[1,0]
	v_pk_fma_f32 v[252:253], v[238:239], v[108:109], v[252:253] op_sel:[0,1,0]
	v_pk_fma_f32 v[254:255], v[246:247], v[108:109], v[254:255] op_sel:[0,1,0]
	v_pk_fma_f32 v[252:253], v[240:241], v[110:111], v[252:253] op_sel_hi:[1,0,1]
	v_pk_fma_f32 v[254:255], v[248:249], v[110:111], v[254:255] op_sel_hi:[1,0,1]
	v_pk_fma_f32 v[252:253], v[242:243], v[110:111], v[252:253] op_sel:[0,1,0]
	v_pk_fma_f32 v[254:255], v[250:251], v[110:111], v[254:255] op_sel:[0,1,0]
	v_add_f32_dpp v124, v126, v125 row_ror:4 row_mask:0xf bank_mask:0xf
	v_add_f32_dpp v112, v140, v140 quad_perm:[1,0,3,2] row_mask:0xf bank_mask:0xf
	v_add_f32_dpp v113, v141, v141 quad_perm:[1,0,3,2] row_mask:0xf bank_mask:0xf
	v_add_f32_dpp v114, v142, v142 quad_perm:[1,0,3,2] row_mask:0xf bank_mask:0xf
	v_add_f32_dpp v115, v143, v143 quad_perm:[1,0,3,2] row_mask:0xf bank_mask:0xf
	v_cndmask_b32_e32 v112, v114, v112, vcc
	v_cndmask_b32_e32 v113, v115, v113, vcc
	v_add_f32_dpp v118, v116, v116 quad_perm:[2,3,0,1] row_mask:0xf bank_mask:0xf
	v_add_f32_dpp v119, v117, v117 quad_perm:[2,3,0,1] row_mask:0xf bank_mask:0xf
	v_cndmask_b32_e64 v116, v119, v118, s[4:5]
	s_waitcnt vmcnt(26)
	v_pk_mul_f32 v[140:141], v[236:237], v[104:105] op_sel_hi:[1,0]
	v_pk_mul_f32 v[142:143], v[244:245], v[104:105] op_sel_hi:[1,0]
	v_pk_fma_f32 v[140:141], v[238:239], v[104:105], v[140:141] op_sel:[0,1,0]
	v_pk_fma_f32 v[142:143], v[246:247], v[104:105], v[142:143] op_sel:[0,1,0]
	v_pk_fma_f32 v[140:141], v[240:241], v[106:107], v[140:141] op_sel_hi:[1,0,1]
	v_pk_fma_f32 v[142:143], v[248:249], v[106:107], v[142:143] op_sel_hi:[1,0,1]
	v_pk_fma_f32 v[140:141], v[242:243], v[106:107], v[140:141] op_sel:[0,1,0]
	v_pk_fma_f32 v[142:143], v[250:251], v[106:107], v[142:143] op_sel:[0,1,0]
	v_add_f32_dpp v108, v252, v252 quad_perm:[1,0,3,2] row_mask:0xf bank_mask:0xf
	v_add_f32_dpp v109, v253, v253 quad_perm:[1,0,3,2] row_mask:0xf bank_mask:0xf
	v_add_f32_dpp v110, v254, v254 quad_perm:[1,0,3,2] row_mask:0xf bank_mask:0xf
	v_add_f32_dpp v111, v255, v255 quad_perm:[1,0,3,2] row_mask:0xf bank_mask:0xf
	v_cndmask_b32_e32 v108, v110, v108, vcc
	v_cndmask_b32_e32 v109, v111, v109, vcc
	v_add_f32_dpp v114, v112, v112 quad_perm:[2,3,0,1] row_mask:0xf bank_mask:0xf
	v_add_f32_dpp v115, v113, v113 quad_perm:[2,3,0,1] row_mask:0xf bank_mask:0xf
	v_cndmask_b32_e64 v112, v115, v114, s[4:5]
	v_cndmask_b32_e64 v117, v112, v116, s[6:7]
	v_cndmask_b32_e64 v118, v116, v112, s[6:7]
	s_waitcnt vmcnt(25)
	v_pk_mul_f32 v[252:253], v[236:237], v[100:101] op_sel_hi:[1,0]
	v_pk_mul_f32 v[254:255], v[244:245], v[100:101] op_sel_hi:[1,0]
	v_pk_fma_f32 v[252:253], v[238:239], v[100:101], v[252:253] op_sel:[0,1,0]
	v_pk_fma_f32 v[254:255], v[246:247], v[100:101], v[254:255] op_sel:[0,1,0]
	v_pk_fma_f32 v[252:253], v[240:241], v[102:103], v[252:253] op_sel_hi:[1,0,1]
	v_pk_fma_f32 v[254:255], v[248:249], v[102:103], v[254:255] op_sel_hi:[1,0,1]
	v_pk_fma_f32 v[252:253], v[242:243], v[102:103], v[252:253] op_sel:[0,1,0]
	v_pk_fma_f32 v[254:255], v[250:251], v[102:103], v[254:255] op_sel:[0,1,0]
	v_add_f32_dpp v116, v118, v117 row_ror:4 row_mask:0xf bank_mask:0xf
	v_cndmask_b32_e64 v125, v116, v124, s[64:65]
	v_cndmask_b32_e64 v126, v124, v116, s[64:65]
	v_add_f32_dpp v104, v140, v140 quad_perm:[1,0,3,2] row_mask:0xf bank_mask:0xf
	v_add_f32_dpp v105, v141, v141 quad_perm:[1,0,3,2] row_mask:0xf bank_mask:0xf
	v_add_f32_dpp v106, v142, v142 quad_perm:[1,0,3,2] row_mask:0xf bank_mask:0xf
	v_add_f32_dpp v107, v143, v143 quad_perm:[1,0,3,2] row_mask:0xf bank_mask:0xf
	v_cndmask_b32_e32 v104, v106, v104, vcc
	v_cndmask_b32_e32 v105, v107, v105, vcc
	v_add_f32_dpp v110, v108, v108 quad_perm:[2,3,0,1] row_mask:0xf bank_mask:0xf
	v_add_f32_dpp v111, v109, v109 quad_perm:[2,3,0,1] row_mask:0xf bank_mask:0xf
	v_cndmask_b32_e64 v108, v111, v110, s[4:5]
	s_waitcnt vmcnt(24)
	v_pk_mul_f32 v[140:141], v[236:237], v[96:97] op_sel_hi:[1,0]
	v_pk_mul_f32 v[142:143], v[244:245], v[96:97] op_sel_hi:[1,0]
	v_pk_fma_f32 v[140:141], v[238:239], v[96:97], v[140:141] op_sel:[0,1,0]
	v_pk_fma_f32 v[142:143], v[246:247], v[96:97], v[142:143] op_sel:[0,1,0]
	v_pk_fma_f32 v[140:141], v[240:241], v[98:99], v[140:141] op_sel_hi:[1,0,1]
	v_pk_fma_f32 v[142:143], v[248:249], v[98:99], v[142:143] op_sel_hi:[1,0,1]
	v_pk_fma_f32 v[140:141], v[242:243], v[98:99], v[140:141] op_sel:[0,1,0]
	v_pk_fma_f32 v[142:143], v[250:251], v[98:99], v[142:143] op_sel:[0,1,0]
	v_add_f32_dpp v124, v126, v125 row_ror:8 row_mask:0xf bank_mask:0xf
	v_add_f32_dpp v100, v252, v252 quad_perm:[1,0,3,2] row_mask:0xf bank_mask:0xf
	v_add_f32_dpp v101, v253, v253 quad_perm:[1,0,3,2] row_mask:0xf bank_mask:0xf
	v_add_f32_dpp v102, v254, v254 quad_perm:[1,0,3,2] row_mask:0xf bank_mask:0xf
	v_add_f32_dpp v103, v255, v255 quad_perm:[1,0,3,2] row_mask:0xf bank_mask:0xf
	v_cndmask_b32_e32 v100, v102, v100, vcc
	v_cndmask_b32_e32 v101, v103, v101, vcc
	v_add_f32_dpp v106, v104, v104 quad_perm:[2,3,0,1] row_mask:0xf bank_mask:0xf
	v_add_f32_dpp v107, v105, v105 quad_perm:[2,3,0,1] row_mask:0xf bank_mask:0xf
	v_cndmask_b32_e64 v104, v107, v106, s[4:5]
	v_cndmask_b32_e64 v109, v104, v108, s[6:7]
	v_cndmask_b32_e64 v110, v108, v104, s[6:7]
	s_waitcnt vmcnt(23)
; DI void attn_sample_item(const Params& p, int item, ldsp lds, int tid_) {
;     ...
;   SC_SCORE(kvA, 0)
;   SC_SCORE(kvB, 1)
	v_pk_mul_f32 v[252:253], v[236:237], v[92:93] op_sel_hi:[1,0]
	v_pk_mul_f32 v[254:255], v[244:245], v[92:93] op_sel_hi:[1,0]
	v_pk_fma_f32 v[252:253], v[238:239], v[92:93], v[252:253] op_sel:[0,1,0]
	v_pk_fma_f32 v[254:255], v[246:247], v[92:93], v[254:255] op_sel:[0,1,0]
	v_pk_fma_f32 v[252:253], v[240:241], v[94:95], v[252:253] op_sel_hi:[1,0,1]
	v_pk_fma_f32 v[254:255], v[248:249], v[94:95], v[254:255] op_sel_hi:[1,0,1]
	v_pk_fma_f32 v[252:253], v[242:243], v[94:95], v[252:253] op_sel:[0,1,0]
	v_pk_fma_f32 v[254:255], v[250:251], v[94:95], v[254:255] op_sel:[0,1,0]
	v_add_f32_dpp v108, v110, v109 row_ror:4 row_mask:0xf bank_mask:0xf
	v_add_f32_dpp v96, v140, v140 quad_perm:[1,0,3,2] row_mask:0xf bank_mask:0xf
	v_add_f32_dpp v97, v141, v141 quad_perm:[1,0,3,2] row_mask:0xf bank_mask:0xf
	v_add_f32_dpp v98, v142, v142 quad_perm:[1,0,3,2] row_mask:0xf bank_mask:0xf
	v_add_f32_dpp v99, v143, v143 quad_perm:[1,0,3,2] row_mask:0xf bank_mask:0xf
	v_cndmask_b32_e32 v96, v98, v96, vcc
	v_cndmask_b32_e32 v97, v99, v97, vcc
	v_add_f32_dpp v102, v100, v100 quad_perm:[2,3,0,1] row_mask:0xf bank_mask:0xf
	v_add_f32_dpp v103, v101, v101 quad_perm:[2,3,0,1] row_mask:0xf bank_mask:0xf
	v_cndmask_b32_e64 v100, v103, v102, s[4:5]
	s_waitcnt vmcnt(22)
	v_pk_mul_f32 v[140:141], v[236:237], v[88:89] op_sel_hi:[1,0]
	v_pk_mul_f32 v[142:143], v[244:245], v[88:89] op_sel_hi:[1,0]
	v_pk_fma_f32 v[140:141], v[238:239], v[88:89], v[140:141] op_sel:[0,1,0]
	v_pk_fma_f32 v[142:143], v[246:247], v[88:89], v[142:143] op_sel:[0,1,0]
	v_pk_fma_f32 v[140:141], v[240:241], v[90:91], v[140:141] op_sel_hi:[1,0,1]
	v_pk_fma_f32 v[142:143], v[248:249], v[90:91], v[142:143] op_sel_hi:[1,0,1]
	v_pk_fma_f32 v[140:141], v[242:243], v[90:91], v[140:141] op_sel:[0,1,0]
	v_pk_fma_f32 v[142:143], v[250:251], v[90:91], v[142:143] op_sel:[0,1,0]
	v_add_f32_dpp v92, v252, v252 quad_perm:[1,0,3,2] row_mask:0xf bank_mask:0xf
	v_add_f32_dpp v93, v253, v253 quad_perm:[1,0,3,2] row_mask:0xf bank_mask:0xf
	v_add_f32_dpp v94, v254, v254 quad_perm:[1,0,3,2] row_mask:0xf bank_mask:0xf
	v_add_f32_dpp v95, v255, v255 quad_perm:[1,0,3,2] row_mask:0xf bank_mask:0xf
	v_cndmask_b32_e32 v92, v94, v92, vcc
	v_cndmask_b32_e32 v93, v95, v93, vcc
	v_add_f32_dpp v98, v96, v96 quad_perm:[2,3,0,1] row_mask:0xf bank_mask:0xf
	v_add_f32_dpp v99, v97, v97 quad_perm:[2,3,0,1] row_mask:0xf bank_mask:0xf
	v_cndmask_b32_e64 v96, v99, v98, s[4:5]
	v_cndmask_b32_e64 v101, v96, v100, s[6:7]
	v_cndmask_b32_e64 v102, v100, v96, s[6:7]
	s_waitcnt vmcnt(21)
	v_pk_mul_f32 v[252:253], v[236:237], v[84:85] op_sel_hi:[1,0]
	v_pk_mul_f32 v[254:255], v[244:245], v[84:85] op_sel_hi:[1,0]
	v_pk_fma_f32 v[252:253], v[238:239], v[84:85], v[252:253] op_sel:[0,1,0]
	v_pk_fma_f32 v[254:255], v[246:247], v[84:85], v[254:255] op_sel:[0,1,0]
	v_pk_fma_f32 v[252:253], v[240:241], v[86:87], v[252:253] op_sel_hi:[1,0,1]
	v_pk_fma_f32 v[254:255], v[248:249], v[86:87], v[254:255] op_sel_hi:[1,0,1]
	v_pk_fma_f32 v[252:253], v[242:243], v[86:87], v[252:253] op_sel:[0,1,0]
	v_pk_fma_f32 v[254:255], v[250:251], v[86:87], v[254:255] op_sel:[0,1,0]
	v_add_f32_dpp v100, v102, v101 row_ror:4 row_mask:0xf bank_mask:0xf
	v_cndmask_b32_e64 v109, v100, v108, s[64:65]
	v_cndmask_b32_e64 v110, v108, v100, s[64:65]
	v_add_f32_dpp v88, v140, v140 quad_perm:[1,0,3,2] row_mask:0xf bank_mask:0xf
	v_add_f32_dpp v89, v141, v141 quad_perm:[1,0,3,2] row_mask:0xf bank_mask:0xf
	v_add_f32_dpp v90, v142, v142 quad_perm:[1,0,3,2] row_mask:0xf bank_mask:0xf
	v_add_f32_dpp v91, v143, v143 quad_perm:[1,0,3,2] row_mask:0xf bank_mask:0xf
	v_cndmask_b32_e32 v88, v90, v88, vcc
	v_cndmask_b32_e32 v89, v91, v89, vcc
	v_add_f32_dpp v94, v92, v92 quad_perm:[2,3,0,1] row_mask:0xf bank_mask:0xf
	v_add_f32_dpp v95, v93, v93 quad_perm:[2,3,0,1] row_mask:0xf bank_mask:0xf
	v_cndmask_b32_e64 v92, v95, v94, s[4:5]
	s_waitcnt vmcnt(20)
	v_pk_mul_f32 v[140:141], v[236:237], v[80:81] op_sel_hi:[1,0]
	v_pk_mul_f32 v[142:143], v[244:245], v[80:81] op_sel_hi:[1,0]
	v_pk_fma_f32 v[140:141], v[238:239], v[80:81], v[140:141] op_sel:[0,1,0]
	v_pk_fma_f32 v[142:143], v[246:247], v[80:81], v[142:143] op_sel:[0,1,0]
	v_pk_fma_f32 v[140:141], v[240:241], v[82:83], v[140:141] op_sel_hi:[1,0,1]
	v_pk_fma_f32 v[142:143], v[248:249], v[82:83], v[142:143] op_sel_hi:[1,0,1]
	v_pk_fma_f32 v[140:141], v[242:243], v[82:83], v[140:141] op_sel:[0,1,0]
	v_pk_fma_f32 v[142:143], v[250:251], v[82:83], v[142:143] op_sel:[0,1,0]
	v_add_f32_dpp v108, v110, v109 row_ror:8 row_mask:0xf bank_mask:0xf
	v_add_f32_dpp v84, v252, v252 quad_perm:[1,0,3,2] row_mask:0xf bank_mask:0xf
	v_add_f32_dpp v85, v253, v253 quad_perm:[1,0,3,2] row_mask:0xf bank_mask:0xf
	v_add_f32_dpp v86, v254, v254 quad_perm:[1,0,3,2] row_mask:0xf bank_mask:0xf
	v_add_f32_dpp v87, v255, v255 quad_perm:[1,0,3,2] row_mask:0xf bank_mask:0xf
	v_cndmask_b32_e32 v84, v86, v84, vcc
	v_cndmask_b32_e32 v85, v87, v85, vcc
	v_add_f32_dpp v90, v88, v88 quad_perm:[2,3,0,1] row_mask:0xf bank_mask:0xf
	v_add_f32_dpp v91, v89, v89 quad_perm:[2,3,0,1] row_mask:0xf bank_mask:0xf
	v_cndmask_b32_e64 v88, v91, v90, s[4:5]
	v_cndmask_b32_e64 v93, v88, v92, s[6:7]
	v_cndmask_b32_e64 v94, v92, v88, s[6:7]
	s_waitcnt vmcnt(19)
; DI void attn_sample_item(const Params& p, int item, ldsp lds, int tid_) {
;     ...
;   SC_SCORE(kvA, 0)
;   SC_SCORE(kvB, 1)
	v_pk_mul_f32 v[252:253], v[236:237], v[76:77] op_sel_hi:[1,0]
	v_pk_mul_f32 v[254:255], v[244:245], v[76:77] op_sel_hi:[1,0]
	v_pk_fma_f32 v[252:253], v[238:239], v[76:77], v[252:253] op_sel:[0,1,0]
	v_pk_fma_f32 v[254:255], v[246:247], v[76:77], v[254:255] op_sel:[0,1,0]
	v_pk_fma_f32 v[252:253], v[240:241], v[78:79], v[252:253] op_sel_hi:[1,0,1]
	v_pk_fma_f32 v[254:255], v[248:249], v[78:79], v[254:255] op_sel_hi:[1,0,1]
	v_pk_fma_f32 v[252:253], v[242:243], v[78:79], v[252:253] op_sel:[0,1,0]
	v_pk_fma_f32 v[254:255], v[250:251], v[78:79], v[254:255] op_sel:[0,1,0]
	v_permlane16_swap_b32_e32 v124, v108
	v_add_f32_e32 v124, v124, v108
	v_add_f32_dpp v92, v94, v93 row_ror:4 row_mask:0xf bank_mask:0xf
	v_add_f32_dpp v80, v140, v140 quad_perm:[1,0,3,2] row_mask:0xf bank_mask:0xf
	v_add_f32_dpp v81, v141, v141 quad_perm:[1,0,3,2] row_mask:0xf bank_mask:0xf
	v_add_f32_dpp v82, v142, v142 quad_perm:[1,0,3,2] row_mask:0xf bank_mask:0xf
	v_add_f32_dpp v83, v143, v143 quad_perm:[1,0,3,2] row_mask:0xf bank_mask:0xf
	v_cndmask_b32_e32 v80, v82, v80, vcc
	v_cndmask_b32_e32 v81, v83, v81, vcc
	v_add_f32_dpp v86, v84, v84 quad_perm:[2,3,0,1] row_mask:0xf bank_mask:0xf
	v_add_f32_dpp v87, v85, v85 quad_perm:[2,3,0,1] row_mask:0xf bank_mask:0xf
	v_cndmask_b32_e64 v84, v87, v86, s[4:5]
	s_waitcnt vmcnt(18)
	v_pk_mul_f32 v[140:141], v[236:237], v[72:73] op_sel_hi:[1,0]
	v_pk_mul_f32 v[142:143], v[244:245], v[72:73] op_sel_hi:[1,0]
	v_pk_fma_f32 v[140:141], v[238:239], v[72:73], v[140:141] op_sel:[0,1,0]
	v_pk_fma_f32 v[142:143], v[246:247], v[72:73], v[142:143] op_sel:[0,1,0]
	v_pk_fma_f32 v[140:141], v[240:241], v[74:75], v[140:141] op_sel_hi:[1,0,1]
	v_pk_fma_f32 v[142:143], v[248:249], v[74:75], v[142:143] op_sel_hi:[1,0,1]
	v_pk_fma_f32 v[140:141], v[242:243], v[74:75], v[140:141] op_sel:[0,1,0]
	v_pk_fma_f32 v[142:143], v[250:251], v[74:75], v[142:143] op_sel:[0,1,0]
	v_add_f32_dpp v76, v252, v252 quad_perm:[1,0,3,2] row_mask:0xf bank_mask:0xf
	v_add_f32_dpp v77, v253, v253 quad_perm:[1,0,3,2] row_mask:0xf bank_mask:0xf
	v_add_f32_dpp v78, v254, v254 quad_perm:[1,0,3,2] row_mask:0xf bank_mask:0xf
	v_add_f32_dpp v79, v255, v255 quad_perm:[1,0,3,2] row_mask:0xf bank_mask:0xf
	v_cndmask_b32_e32 v76, v78, v76, vcc
	v_cndmask_b32_e32 v77, v79, v77, vcc
	v_add_f32_dpp v82, v80, v80 quad_perm:[2,3,0,1] row_mask:0xf bank_mask:0xf
	v_add_f32_dpp v83, v81, v81 quad_perm:[2,3,0,1] row_mask:0xf bank_mask:0xf
	v_cndmask_b32_e64 v80, v83, v82, s[4:5]
	v_cndmask_b32_e64 v85, v80, v84, s[6:7]
	v_cndmask_b32_e64 v86, v84, v80, s[6:7]
	s_waitcnt vmcnt(17)
	v_pk_mul_f32 v[252:253], v[236:237], v[68:69] op_sel_hi:[1,0]
	v_pk_mul_f32 v[254:255], v[244:245], v[68:69] op_sel_hi:[1,0]
	v_pk_fma_f32 v[252:253], v[238:239], v[68:69], v[252:253] op_sel:[0,1,0]
	v_pk_fma_f32 v[254:255], v[246:247], v[68:69], v[254:255] op_sel:[0,1,0]
	v_pk_fma_f32 v[252:253], v[240:241], v[70:71], v[252:253] op_sel_hi:[1,0,1]
	v_pk_fma_f32 v[254:255], v[248:249], v[70:71], v[254:255] op_sel_hi:[1,0,1]
	v_pk_fma_f32 v[252:253], v[242:243], v[70:71], v[252:253] op_sel:[0,1,0]
	v_pk_fma_f32 v[254:255], v[250:251], v[70:71], v[254:255] op_sel:[0,1,0]
	v_add_f32_dpp v84, v86, v85 row_ror:4 row_mask:0xf bank_mask:0xf
	v_cndmask_b32_e64 v93, v84, v92, s[64:65]
	v_cndmask_b32_e64 v94, v92, v84, s[64:65]
	v_add_f32_dpp v72, v140, v140 quad_perm:[1,0,3,2] row_mask:0xf bank_mask:0xf
	v_add_f32_dpp v73, v141, v141 quad_perm:[1,0,3,2] row_mask:0xf bank_mask:0xf
	v_add_f32_dpp v74, v142, v142 quad_perm:[1,0,3,2] row_mask:0xf bank_mask:0xf
	v_add_f32_dpp v75, v143, v143 quad_perm:[1,0,3,2] row_mask:0xf bank_mask:0xf
	v_cndmask_b32_e32 v72, v74, v72, vcc
	v_cndmask_b32_e32 v73, v75, v73, vcc
	v_add_f32_dpp v78, v76, v76 quad_perm:[2,3,0,1] row_mask:0xf bank_mask:0xf
	v_add_f32_dpp v79, v77, v77 quad_perm:[2,3,0,1] row_mask:0xf bank_mask:0xf
	v_cndmask_b32_e64 v76, v79, v78, s[4:5]
	s_waitcnt vmcnt(16)
	v_pk_mul_f32 v[140:141], v[236:237], v[64:65] op_sel_hi:[1,0]
	v_pk_mul_f32 v[142:143], v[244:245], v[64:65] op_sel_hi:[1,0]
	v_pk_fma_f32 v[140:141], v[238:239], v[64:65], v[140:141] op_sel:[0,1,0]
	v_pk_fma_f32 v[142:143], v[246:247], v[64:65], v[142:143] op_sel:[0,1,0]
	v_pk_fma_f32 v[140:141], v[240:241], v[66:67], v[140:141] op_sel_hi:[1,0,1]
	v_pk_fma_f32 v[142:143], v[248:249], v[66:67], v[142:143] op_sel_hi:[1,0,1]
	v_pk_fma_f32 v[140:141], v[242:243], v[66:67], v[140:141] op_sel:[0,1,0]
	v_pk_fma_f32 v[142:143], v[250:251], v[66:67], v[142:143] op_sel:[0,1,0]
	v_add_f32_dpp v92, v94, v93 row_ror:8 row_mask:0xf bank_mask:0xf
	v_add_f32_dpp v68, v252, v252 quad_perm:[1,0,3,2] row_mask:0xf bank_mask:0xf
	v_add_f32_dpp v69, v253, v253 quad_perm:[1,0,3,2] row_mask:0xf bank_mask:0xf
	v_add_f32_dpp v70, v254, v254 quad_perm:[1,0,3,2] row_mask:0xf bank_mask:0xf
	v_add_f32_dpp v71, v255, v255 quad_perm:[1,0,3,2] row_mask:0xf bank_mask:0xf
	v_cndmask_b32_e32 v68, v70, v68, vcc
	v_cndmask_b32_e32 v69, v71, v69, vcc
	v_add_f32_dpp v74, v72, v72 quad_perm:[2,3,0,1] row_mask:0xf bank_mask:0xf
	v_add_f32_dpp v75, v73, v73 quad_perm:[2,3,0,1] row_mask:0xf bank_mask:0xf
	v_cndmask_b32_e64 v72, v75, v74, s[4:5]
	v_cndmask_b32_e64 v77, v72, v76, s[6:7]
	v_cndmask_b32_e64 v78, v76, v72, s[6:7]
	s_waitcnt vmcnt(15)
; DI void attn_sample_item(const Params& p, int item, ldsp lds, int tid_) {
;     ...
;   SC_SCORE(kvA, 0)
;   SC_SCORE(kvB, 1)
	v_pk_mul_f32 v[252:253], v[236:237], v[60:61] op_sel_hi:[1,0]
	v_pk_mul_f32 v[254:255], v[244:245], v[60:61] op_sel_hi:[1,0]
	v_pk_fma_f32 v[252:253], v[238:239], v[60:61], v[252:253] op_sel:[0,1,0]
	v_pk_fma_f32 v[254:255], v[246:247], v[60:61], v[254:255] op_sel:[0,1,0]
	v_pk_fma_f32 v[252:253], v[240:241], v[62:63], v[252:253] op_sel_hi:[1,0,1]
	v_pk_fma_f32 v[254:255], v[248:249], v[62:63], v[254:255] op_sel_hi:[1,0,1]
	v_pk_fma_f32 v[252:253], v[242:243], v[62:63], v[252:253] op_sel:[0,1,0]
	v_pk_fma_f32 v[254:255], v[250:251], v[62:63], v[254:255] op_sel:[0,1,0]
	v_add_f32_dpp v76, v78, v77 row_ror:4 row_mask:0xf bank_mask:0xf
	v_add_f32_dpp v64, v140, v140 quad_perm:[1,0,3,2] row_mask:0xf bank_mask:0xf
	v_add_f32_dpp v65, v141, v141 quad_perm:[1,0,3,2] row_mask:0xf bank_mask:0xf
	v_add_f32_dpp v66, v142, v142 quad_perm:[1,0,3,2] row_mask:0xf bank_mask:0xf
	v_add_f32_dpp v67, v143, v143 quad_perm:[1,0,3,2] row_mask:0xf bank_mask:0xf
	v_cndmask_b32_e32 v64, v66, v64, vcc
	v_cndmask_b32_e32 v65, v67, v65, vcc
	v_add_f32_dpp v70, v68, v68 quad_perm:[2,3,0,1] row_mask:0xf bank_mask:0xf
	v_add_f32_dpp v71, v69, v69 quad_perm:[2,3,0,1] row_mask:0xf bank_mask:0xf
	v_cndmask_b32_e64 v68, v71, v70, s[4:5]
	s_waitcnt vmcnt(14)
	v_pk_mul_f32 v[140:141], v[236:237], v[56:57] op_sel_hi:[1,0]
	v_pk_mul_f32 v[142:143], v[244:245], v[56:57] op_sel_hi:[1,0]
	v_pk_fma_f32 v[140:141], v[238:239], v[56:57], v[140:141] op_sel:[0,1,0]
	v_pk_fma_f32 v[142:143], v[246:247], v[56:57], v[142:143] op_sel:[0,1,0]
	v_pk_fma_f32 v[140:141], v[240:241], v[58:59], v[140:141] op_sel_hi:[1,0,1]
	v_pk_fma_f32 v[142:143], v[248:249], v[58:59], v[142:143] op_sel_hi:[1,0,1]
	v_pk_fma_f32 v[140:141], v[242:243], v[58:59], v[140:141] op_sel:[0,1,0]
	v_pk_fma_f32 v[142:143], v[250:251], v[58:59], v[142:143] op_sel:[0,1,0]
	v_add_f32_dpp v60, v252, v252 quad_perm:[1,0,3,2] row_mask:0xf bank_mask:0xf
	v_add_f32_dpp v61, v253, v253 quad_perm:[1,0,3,2] row_mask:0xf bank_mask:0xf
	v_add_f32_dpp v62, v254, v254 quad_perm:[1,0,3,2] row_mask:0xf bank_mask:0xf
	v_add_f32_dpp v63, v255, v255 quad_perm:[1,0,3,2] row_mask:0xf bank_mask:0xf
	v_cndmask_b32_e32 v60, v62, v60, vcc
	v_cndmask_b32_e32 v61, v63, v61, vcc
	v_add_f32_dpp v66, v64, v64 quad_perm:[2,3,0,1] row_mask:0xf bank_mask:0xf
	v_add_f32_dpp v67, v65, v65 quad_perm:[2,3,0,1] row_mask:0xf bank_mask:0xf
	v_cndmask_b32_e64 v64, v67, v66, s[4:5]
	v_cndmask_b32_e64 v69, v64, v68, s[6:7]
	v_cndmask_b32_e64 v70, v68, v64, s[6:7]
	s_waitcnt vmcnt(13)
	v_pk_mul_f32 v[252:253], v[236:237], v[52:53] op_sel_hi:[1,0]
	v_pk_mul_f32 v[254:255], v[244:245], v[52:53] op_sel_hi:[1,0]
	v_pk_fma_f32 v[252:253], v[238:239], v[52:53], v[252:253] op_sel:[0,1,0]
	v_pk_fma_f32 v[254:255], v[246:247], v[52:53], v[254:255] op_sel:[0,1,0]
	v_pk_fma_f32 v[252:253], v[240:241], v[54:55], v[252:253] op_sel_hi:[1,0,1]
	v_pk_fma_f32 v[254:255], v[248:249], v[54:55], v[254:255] op_sel_hi:[1,0,1]
	v_pk_fma_f32 v[252:253], v[242:243], v[54:55], v[252:253] op_sel:[0,1,0]
	v_pk_fma_f32 v[254:255], v[250:251], v[54:55], v[254:255] op_sel:[0,1,0]
	v_add_f32_dpp v68, v70, v69 row_ror:4 row_mask:0xf bank_mask:0xf
	v_cndmask_b32_e64 v77, v68, v76, s[64:65]
	v_cndmask_b32_e64 v78, v76, v68, s[64:65]
	v_add_f32_dpp v56, v140, v140 quad_perm:[1,0,3,2] row_mask:0xf bank_mask:0xf
	v_add_f32_dpp v57, v141, v141 quad_perm:[1,0,3,2] row_mask:0xf bank_mask:0xf
	v_add_f32_dpp v58, v142, v142 quad_perm:[1,0,3,2] row_mask:0xf bank_mask:0xf
	v_add_f32_dpp v59, v143, v143 quad_perm:[1,0,3,2] row_mask:0xf bank_mask:0xf
	v_cndmask_b32_e32 v56, v58, v56, vcc
	v_cndmask_b32_e32 v57, v59, v57, vcc
	v_add_f32_dpp v62, v60, v60 quad_perm:[2,3,0,1] row_mask:0xf bank_mask:0xf
	v_add_f32_dpp v63, v61, v61 quad_perm:[2,3,0,1] row_mask:0xf bank_mask:0xf
	v_cndmask_b32_e64 v60, v63, v62, s[4:5]
	s_waitcnt vmcnt(12)
	v_pk_mul_f32 v[140:141], v[236:237], v[48:49] op_sel_hi:[1,0]
	v_pk_mul_f32 v[142:143], v[244:245], v[48:49] op_sel_hi:[1,0]
	v_pk_fma_f32 v[140:141], v[238:239], v[48:49], v[140:141] op_sel:[0,1,0]
	v_pk_fma_f32 v[142:143], v[246:247], v[48:49], v[142:143] op_sel:[0,1,0]
	v_pk_fma_f32 v[140:141], v[240:241], v[50:51], v[140:141] op_sel_hi:[1,0,1]
	v_pk_fma_f32 v[142:143], v[248:249], v[50:51], v[142:143] op_sel_hi:[1,0,1]
	v_pk_fma_f32 v[140:141], v[242:243], v[50:51], v[140:141] op_sel:[0,1,0]
	v_pk_fma_f32 v[142:143], v[250:251], v[50:51], v[142:143] op_sel:[0,1,0]
	v_add_f32_dpp v76, v78, v77 row_ror:8 row_mask:0xf bank_mask:0xf
	v_add_f32_dpp v52, v252, v252 quad_perm:[1,0,3,2] row_mask:0xf bank_mask:0xf
	v_add_f32_dpp v53, v253, v253 quad_perm:[1,0,3,2] row_mask:0xf bank_mask:0xf
	v_add_f32_dpp v54, v254, v254 quad_perm:[1,0,3,2] row_mask:0xf bank_mask:0xf
	v_add_f32_dpp v55, v255, v255 quad_perm:[1,0,3,2] row_mask:0xf bank_mask:0xf
	v_cndmask_b32_e32 v52, v54, v52, vcc
	v_cndmask_b32_e32 v53, v55, v53, vcc
	v_add_f32_dpp v58, v56, v56 quad_perm:[2,3,0,1] row_mask:0xf bank_mask:0xf
	v_add_f32_dpp v59, v57, v57 quad_perm:[2,3,0,1] row_mask:0xf bank_mask:0xf
	v_cndmask_b32_e64 v56, v59, v58, s[4:5]
	v_cndmask_b32_e64 v61, v56, v60, s[6:7]
	v_cndmask_b32_e64 v62, v60, v56, s[6:7]
	s_waitcnt vmcnt(11)
; DI void attn_sample_item(const Params& p, int item, ldsp lds, int tid_) {
;     ...
;   SC_SCORE(kvA, 0)
;   SC_SCORE(kvB, 1)
	v_pk_mul_f32 v[252:253], v[236:237], v[44:45] op_sel_hi:[1,0]
	v_pk_mul_f32 v[254:255], v[244:245], v[44:45] op_sel_hi:[1,0]
	v_pk_fma_f32 v[252:253], v[238:239], v[44:45], v[252:253] op_sel:[0,1,0]
	v_pk_fma_f32 v[254:255], v[246:247], v[44:45], v[254:255] op_sel:[0,1,0]
	v_pk_fma_f32 v[252:253], v[240:241], v[46:47], v[252:253] op_sel_hi:[1,0,1]
	v_pk_fma_f32 v[254:255], v[248:249], v[46:47], v[254:255] op_sel_hi:[1,0,1]
	v_pk_fma_f32 v[252:253], v[242:243], v[46:47], v[252:253] op_sel:[0,1,0]
	v_pk_fma_f32 v[254:255], v[250:251], v[46:47], v[254:255] op_sel:[0,1,0]
	v_permlane16_swap_b32_e32 v92, v76
	v_add_f32_e32 v92, v92, v76
	v_add_f32_dpp v60, v62, v61 row_ror:4 row_mask:0xf bank_mask:0xf
	v_add_f32_dpp v48, v140, v140 quad_perm:[1,0,3,2] row_mask:0xf bank_mask:0xf
	v_add_f32_dpp v49, v141, v141 quad_perm:[1,0,3,2] row_mask:0xf bank_mask:0xf
	v_add_f32_dpp v50, v142, v142 quad_perm:[1,0,3,2] row_mask:0xf bank_mask:0xf
	v_add_f32_dpp v51, v143, v143 quad_perm:[1,0,3,2] row_mask:0xf bank_mask:0xf
	v_cndmask_b32_e32 v48, v50, v48, vcc
	v_cndmask_b32_e32 v49, v51, v49, vcc
	v_add_f32_dpp v54, v52, v52 quad_perm:[2,3,0,1] row_mask:0xf bank_mask:0xf
	v_add_f32_dpp v55, v53, v53 quad_perm:[2,3,0,1] row_mask:0xf bank_mask:0xf
	v_cndmask_b32_e64 v52, v55, v54, s[4:5]
	s_waitcnt vmcnt(10)
	v_pk_mul_f32 v[140:141], v[236:237], v[40:41] op_sel_hi:[1,0]
	v_pk_mul_f32 v[142:143], v[244:245], v[40:41] op_sel_hi:[1,0]
	v_pk_fma_f32 v[140:141], v[238:239], v[40:41], v[140:141] op_sel:[0,1,0]
	v_pk_fma_f32 v[142:143], v[246:247], v[40:41], v[142:143] op_sel:[0,1,0]
	v_pk_fma_f32 v[140:141], v[240:241], v[42:43], v[140:141] op_sel_hi:[1,0,1]
	v_pk_fma_f32 v[142:143], v[248:249], v[42:43], v[142:143] op_sel_hi:[1,0,1]
	v_pk_fma_f32 v[140:141], v[242:243], v[42:43], v[140:141] op_sel:[0,1,0]
	v_pk_fma_f32 v[142:143], v[250:251], v[42:43], v[142:143] op_sel:[0,1,0]
	v_permlane32_swap_b32_e32 v124, v92
	v_add_f32_e32 v124, v124, v92
	ds_write_b32 v235, v124
	v_add_f32_dpp v44, v252, v252 quad_perm:[1,0,3,2] row_mask:0xf bank_mask:0xf
	v_add_f32_dpp v45, v253, v253 quad_perm:[1,0,3,2] row_mask:0xf bank_mask:0xf
	v_add_f32_dpp v46, v254, v254 quad_perm:[1,0,3,2] row_mask:0xf bank_mask:0xf
	v_add_f32_dpp v47, v255, v255 quad_perm:[1,0,3,2] row_mask:0xf bank_mask:0xf
	v_cndmask_b32_e32 v44, v46, v44, vcc
	v_cndmask_b32_e32 v45, v47, v45, vcc
	v_add_f32_dpp v50, v48, v48 quad_perm:[2,3,0,1] row_mask:0xf bank_mask:0xf
	v_add_f32_dpp v51, v49, v49 quad_perm:[2,3,0,1] row_mask:0xf bank_mask:0xf
	v_cndmask_b32_e64 v48, v51, v50, s[4:5]
	v_cndmask_b32_e64 v53, v48, v52, s[6:7]
	v_cndmask_b32_e64 v54, v52, v48, s[6:7]
	s_waitcnt vmcnt(9)
	v_pk_mul_f32 v[252:253], v[236:237], v[36:37] op_sel_hi:[1,0]
	v_pk_mul_f32 v[254:255], v[244:245], v[36:37] op_sel_hi:[1,0]
	v_pk_fma_f32 v[252:253], v[238:239], v[36:37], v[252:253] op_sel:[0,1,0]
	v_pk_fma_f32 v[254:255], v[246:247], v[36:37], v[254:255] op_sel:[0,1,0]
	v_pk_fma_f32 v[252:253], v[240:241], v[38:39], v[252:253] op_sel_hi:[1,0,1]
	v_pk_fma_f32 v[254:255], v[248:249], v[38:39], v[254:255] op_sel_hi:[1,0,1]
	v_pk_fma_f32 v[252:253], v[242:243], v[38:39], v[252:253] op_sel:[0,1,0]
	v_pk_fma_f32 v[254:255], v[250:251], v[38:39], v[254:255] op_sel:[0,1,0]
	v_add_f32_dpp v52, v54, v53 row_ror:4 row_mask:0xf bank_mask:0xf
	v_cndmask_b32_e64 v61, v52, v60, s[64:65]
	v_cndmask_b32_e64 v62, v60, v52, s[64:65]
	v_add_f32_dpp v40, v140, v140 quad_perm:[1,0,3,2] row_mask:0xf bank_mask:0xf
	v_add_f32_dpp v41, v141, v141 quad_perm:[1,0,3,2] row_mask:0xf bank_mask:0xf
	v_add_f32_dpp v42, v142, v142 quad_perm:[1,0,3,2] row_mask:0xf bank_mask:0xf
	v_add_f32_dpp v43, v143, v143 quad_perm:[1,0,3,2] row_mask:0xf bank_mask:0xf
	v_cndmask_b32_e32 v40, v42, v40, vcc
	v_cndmask_b32_e32 v41, v43, v41, vcc
	v_add_f32_dpp v46, v44, v44 quad_perm:[2,3,0,1] row_mask:0xf bank_mask:0xf
	v_add_f32_dpp v47, v45, v45 quad_perm:[2,3,0,1] row_mask:0xf bank_mask:0xf
	v_cndmask_b32_e64 v44, v47, v46, s[4:5]
	s_waitcnt vmcnt(8)
	v_pk_mul_f32 v[140:141], v[236:237], v[32:33] op_sel_hi:[1,0]
	v_pk_mul_f32 v[142:143], v[244:245], v[32:33] op_sel_hi:[1,0]
	v_pk_fma_f32 v[140:141], v[238:239], v[32:33], v[140:141] op_sel:[0,1,0]
	v_pk_fma_f32 v[142:143], v[246:247], v[32:33], v[142:143] op_sel:[0,1,0]
	v_pk_fma_f32 v[140:141], v[240:241], v[34:35], v[140:141] op_sel_hi:[1,0,1]
	v_pk_fma_f32 v[142:143], v[248:249], v[34:35], v[142:143] op_sel_hi:[1,0,1]
	v_pk_fma_f32 v[140:141], v[242:243], v[34:35], v[140:141] op_sel:[0,1,0]
	v_pk_fma_f32 v[142:143], v[250:251], v[34:35], v[142:143] op_sel:[0,1,0]
	v_add_f32_dpp v60, v62, v61 row_ror:8 row_mask:0xf bank_mask:0xf
	v_add_f32_dpp v36, v252, v252 quad_perm:[1,0,3,2] row_mask:0xf bank_mask:0xf
	v_add_f32_dpp v37, v253, v253 quad_perm:[1,0,3,2] row_mask:0xf bank_mask:0xf
	v_add_f32_dpp v38, v254, v254 quad_perm:[1,0,3,2] row_mask:0xf bank_mask:0xf
	v_add_f32_dpp v39, v255, v255 quad_perm:[1,0,3,2] row_mask:0xf bank_mask:0xf
	v_cndmask_b32_e32 v36, v38, v36, vcc
	v_cndmask_b32_e32 v37, v39, v37, vcc
	v_add_f32_dpp v42, v40, v40 quad_perm:[2,3,0,1] row_mask:0xf bank_mask:0xf
	v_add_f32_dpp v43, v41, v41 quad_perm:[2,3,0,1] row_mask:0xf bank_mask:0xf
	v_cndmask_b32_e64 v40, v43, v42, s[4:5]
	v_cndmask_b32_e64 v45, v40, v44, s[6:7]
	v_cndmask_b32_e64 v46, v44, v40, s[6:7]
	s_waitcnt vmcnt(7)
; DI void attn_sample_item(const Params& p, int item, ldsp lds, int tid_) {
;     ...
;   SC_SCORE(kvA, 0)
;   SC_SCORE(kvB, 1)
	v_pk_mul_f32 v[252:253], v[236:237], v[28:29] op_sel_hi:[1,0]
	v_pk_mul_f32 v[254:255], v[244:245], v[28:29] op_sel_hi:[1,0]
	v_pk_fma_f32 v[252:253], v[238:239], v[28:29], v[252:253] op_sel:[0,1,0]
	v_pk_fma_f32 v[254:255], v[246:247], v[28:29], v[254:255] op_sel:[0,1,0]
	v_pk_fma_f32 v[252:253], v[240:241], v[30:31], v[252:253] op_sel_hi:[1,0,1]
	v_pk_fma_f32 v[254:255], v[248:249], v[30:31], v[254:255] op_sel_hi:[1,0,1]
	v_pk_fma_f32 v[252:253], v[242:243], v[30:31], v[252:253] op_sel:[0,1,0]
	v_pk_fma_f32 v[254:255], v[250:251], v[30:31], v[254:255] op_sel:[0,1,0]
	v_add_f32_dpp v44, v46, v45 row_ror:4 row_mask:0xf bank_mask:0xf
	v_add_f32_dpp v32, v140, v140 quad_perm:[1,0,3,2] row_mask:0xf bank_mask:0xf
	v_add_f32_dpp v33, v141, v141 quad_perm:[1,0,3,2] row_mask:0xf bank_mask:0xf
	v_add_f32_dpp v34, v142, v142 quad_perm:[1,0,3,2] row_mask:0xf bank_mask:0xf
	v_add_f32_dpp v35, v143, v143 quad_perm:[1,0,3,2] row_mask:0xf bank_mask:0xf
	v_cndmask_b32_e32 v32, v34, v32, vcc
	v_cndmask_b32_e32 v33, v35, v33, vcc
	v_add_f32_dpp v38, v36, v36 quad_perm:[2,3,0,1] row_mask:0xf bank_mask:0xf
	v_add_f32_dpp v39, v37, v37 quad_perm:[2,3,0,1] row_mask:0xf bank_mask:0xf
	v_cndmask_b32_e64 v36, v39, v38, s[4:5]
	s_waitcnt vmcnt(6)
	v_pk_mul_f32 v[140:141], v[236:237], v[24:25] op_sel_hi:[1,0]
	v_pk_mul_f32 v[142:143], v[244:245], v[24:25] op_sel_hi:[1,0]
	v_pk_fma_f32 v[140:141], v[238:239], v[24:25], v[140:141] op_sel:[0,1,0]
	v_pk_fma_f32 v[142:143], v[246:247], v[24:25], v[142:143] op_sel:[0,1,0]
	v_pk_fma_f32 v[140:141], v[240:241], v[26:27], v[140:141] op_sel_hi:[1,0,1]
	v_pk_fma_f32 v[142:143], v[248:249], v[26:27], v[142:143] op_sel_hi:[1,0,1]
	v_pk_fma_f32 v[140:141], v[242:243], v[26:27], v[140:141] op_sel:[0,1,0]
	v_pk_fma_f32 v[142:143], v[250:251], v[26:27], v[142:143] op_sel:[0,1,0]
	v_add_f32_dpp v28, v252, v252 quad_perm:[1,0,3,2] row_mask:0xf bank_mask:0xf
	v_add_f32_dpp v29, v253, v253 quad_perm:[1,0,3,2] row_mask:0xf bank_mask:0xf
	v_add_f32_dpp v30, v254, v254 quad_perm:[1,0,3,2] row_mask:0xf bank_mask:0xf
	v_add_f32_dpp v31, v255, v255 quad_perm:[1,0,3,2] row_mask:0xf bank_mask:0xf
	v_cndmask_b32_e32 v28, v30, v28, vcc
	v_cndmask_b32_e32 v29, v31, v29, vcc
	v_add_f32_dpp v34, v32, v32 quad_perm:[2,3,0,1] row_mask:0xf bank_mask:0xf
	v_add_f32_dpp v35, v33, v33 quad_perm:[2,3,0,1] row_mask:0xf bank_mask:0xf
	v_cndmask_b32_e64 v32, v35, v34, s[4:5]
	v_cndmask_b32_e64 v37, v32, v36, s[6:7]
	v_cndmask_b32_e64 v38, v36, v32, s[6:7]
	s_waitcnt vmcnt(5)
	v_pk_mul_f32 v[252:253], v[236:237], v[20:21] op_sel_hi:[1,0]
	v_pk_mul_f32 v[254:255], v[244:245], v[20:21] op_sel_hi:[1,0]
	v_pk_fma_f32 v[252:253], v[238:239], v[20:21], v[252:253] op_sel:[0,1,0]
	v_pk_fma_f32 v[254:255], v[246:247], v[20:21], v[254:255] op_sel:[0,1,0]
	v_pk_fma_f32 v[252:253], v[240:241], v[22:23], v[252:253] op_sel_hi:[1,0,1]
	v_pk_fma_f32 v[254:255], v[248:249], v[22:23], v[254:255] op_sel_hi:[1,0,1]
	v_pk_fma_f32 v[252:253], v[242:243], v[22:23], v[252:253] op_sel:[0,1,0]
	v_pk_fma_f32 v[254:255], v[250:251], v[22:23], v[254:255] op_sel:[0,1,0]
	v_add_f32_dpp v36, v38, v37 row_ror:4 row_mask:0xf bank_mask:0xf
	v_cndmask_b32_e64 v45, v36, v44, s[64:65]
	v_cndmask_b32_e64 v46, v44, v36, s[64:65]
	v_add_f32_dpp v24, v140, v140 quad_perm:[1,0,3,2] row_mask:0xf bank_mask:0xf
	v_add_f32_dpp v25, v141, v141 quad_perm:[1,0,3,2] row_mask:0xf bank_mask:0xf
	v_add_f32_dpp v26, v142, v142 quad_perm:[1,0,3,2] row_mask:0xf bank_mask:0xf
	v_add_f32_dpp v27, v143, v143 quad_perm:[1,0,3,2] row_mask:0xf bank_mask:0xf
	v_cndmask_b32_e32 v24, v26, v24, vcc
	v_cndmask_b32_e32 v25, v27, v25, vcc
	v_add_f32_dpp v30, v28, v28 quad_perm:[2,3,0,1] row_mask:0xf bank_mask:0xf
	v_add_f32_dpp v31, v29, v29 quad_perm:[2,3,0,1] row_mask:0xf bank_mask:0xf
	v_cndmask_b32_e64 v28, v31, v30, s[4:5]
	s_waitcnt vmcnt(4)
	v_pk_mul_f32 v[140:141], v[236:237], v[16:17] op_sel_hi:[1,0]
	v_pk_mul_f32 v[142:143], v[244:245], v[16:17] op_sel_hi:[1,0]
	v_pk_fma_f32 v[140:141], v[238:239], v[16:17], v[140:141] op_sel:[0,1,0]
	v_pk_fma_f32 v[142:143], v[246:247], v[16:17], v[142:143] op_sel:[0,1,0]
	v_pk_fma_f32 v[140:141], v[240:241], v[18:19], v[140:141] op_sel_hi:[1,0,1]
	v_pk_fma_f32 v[142:143], v[248:249], v[18:19], v[142:143] op_sel_hi:[1,0,1]
	v_pk_fma_f32 v[140:141], v[242:243], v[18:19], v[140:141] op_sel:[0,1,0]
	v_pk_fma_f32 v[142:143], v[250:251], v[18:19], v[142:143] op_sel:[0,1,0]
	v_add_f32_dpp v44, v46, v45 row_ror:8 row_mask:0xf bank_mask:0xf
	v_add_f32_dpp v20, v252, v252 quad_perm:[1,0,3,2] row_mask:0xf bank_mask:0xf
	v_add_f32_dpp v21, v253, v253 quad_perm:[1,0,3,2] row_mask:0xf bank_mask:0xf
	v_add_f32_dpp v22, v254, v254 quad_perm:[1,0,3,2] row_mask:0xf bank_mask:0xf
	v_add_f32_dpp v23, v255, v255 quad_perm:[1,0,3,2] row_mask:0xf bank_mask:0xf
	v_cndmask_b32_e32 v20, v22, v20, vcc
	v_cndmask_b32_e32 v21, v23, v21, vcc
	v_add_f32_dpp v26, v24, v24 quad_perm:[2,3,0,1] row_mask:0xf bank_mask:0xf
	v_add_f32_dpp v27, v25, v25 quad_perm:[2,3,0,1] row_mask:0xf bank_mask:0xf
	v_cndmask_b32_e64 v24, v27, v26, s[4:5]
	v_cndmask_b32_e64 v29, v24, v28, s[6:7]
	v_cndmask_b32_e64 v30, v28, v24, s[6:7]
	s_waitcnt vmcnt(3)
; DI void attn_sample_item(const Params& p, int item, ldsp lds, int tid_) {
;     ...
;   SC_SCORE(kvA, 0)
;   SC_SCORE(kvB, 1)
	v_pk_mul_f32 v[252:253], v[236:237], v[12:13] op_sel_hi:[1,0]
	v_pk_mul_f32 v[254:255], v[244:245], v[12:13] op_sel_hi:[1,0]
	v_pk_fma_f32 v[252:253], v[238:239], v[12:13], v[252:253] op_sel:[0,1,0]
	v_pk_fma_f32 v[254:255], v[246:247], v[12:13], v[254:255] op_sel:[0,1,0]
	v_pk_fma_f32 v[252:253], v[240:241], v[14:15], v[252:253] op_sel_hi:[1,0,1]
	v_pk_fma_f32 v[254:255], v[248:249], v[14:15], v[254:255] op_sel_hi:[1,0,1]
	v_pk_fma_f32 v[252:253], v[242:243], v[14:15], v[252:253] op_sel:[0,1,0]
	v_pk_fma_f32 v[254:255], v[250:251], v[14:15], v[254:255] op_sel:[0,1,0]
	v_permlane16_swap_b32_e32 v60, v44
	v_add_f32_e32 v60, v60, v44
	v_add_f32_dpp v28, v30, v29 row_ror:4 row_mask:0xf bank_mask:0xf
	v_add_f32_dpp v16, v140, v140 quad_perm:[1,0,3,2] row_mask:0xf bank_mask:0xf
	v_add_f32_dpp v17, v141, v141 quad_perm:[1,0,3,2] row_mask:0xf bank_mask:0xf
	v_add_f32_dpp v18, v142, v142 quad_perm:[1,0,3,2] row_mask:0xf bank_mask:0xf
	v_add_f32_dpp v19, v143, v143 quad_perm:[1,0,3,2] row_mask:0xf bank_mask:0xf
	v_cndmask_b32_e32 v16, v18, v16, vcc
	v_cndmask_b32_e32 v17, v19, v17, vcc
	v_add_f32_dpp v22, v20, v20 quad_perm:[2,3,0,1] row_mask:0xf bank_mask:0xf
	v_add_f32_dpp v23, v21, v21 quad_perm:[2,3,0,1] row_mask:0xf bank_mask:0xf
	v_cndmask_b32_e64 v20, v23, v22, s[4:5]
	s_waitcnt vmcnt(2)
	v_pk_mul_f32 v[140:141], v[236:237], v[8:9] op_sel_hi:[1,0]
	v_pk_mul_f32 v[142:143], v[244:245], v[8:9] op_sel_hi:[1,0]
	v_pk_fma_f32 v[140:141], v[238:239], v[8:9], v[140:141] op_sel:[0,1,0]
	v_pk_fma_f32 v[142:143], v[246:247], v[8:9], v[142:143] op_sel:[0,1,0]
	v_pk_fma_f32 v[140:141], v[240:241], v[10:11], v[140:141] op_sel_hi:[1,0,1]
	v_pk_fma_f32 v[142:143], v[248:249], v[10:11], v[142:143] op_sel_hi:[1,0,1]
	v_pk_fma_f32 v[140:141], v[242:243], v[10:11], v[140:141] op_sel:[0,1,0]
	v_pk_fma_f32 v[142:143], v[250:251], v[10:11], v[142:143] op_sel:[0,1,0]
	v_add_f32_dpp v12, v252, v252 quad_perm:[1,0,3,2] row_mask:0xf bank_mask:0xf
	v_add_f32_dpp v13, v253, v253 quad_perm:[1,0,3,2] row_mask:0xf bank_mask:0xf
	v_add_f32_dpp v14, v254, v254 quad_perm:[1,0,3,2] row_mask:0xf bank_mask:0xf
	v_add_f32_dpp v15, v255, v255 quad_perm:[1,0,3,2] row_mask:0xf bank_mask:0xf
	v_cndmask_b32_e32 v12, v14, v12, vcc
	v_cndmask_b32_e32 v13, v15, v13, vcc
	v_add_f32_dpp v18, v16, v16 quad_perm:[2,3,0,1] row_mask:0xf bank_mask:0xf
	v_add_f32_dpp v19, v17, v17 quad_perm:[2,3,0,1] row_mask:0xf bank_mask:0xf
	v_cndmask_b32_e64 v16, v19, v18, s[4:5]
	v_cndmask_b32_e64 v21, v16, v20, s[6:7]
	v_cndmask_b32_e64 v22, v20, v16, s[6:7]
	s_waitcnt vmcnt(1)
	v_pk_mul_f32 v[252:253], v[236:237], v[4:5] op_sel_hi:[1,0]
	v_pk_mul_f32 v[254:255], v[244:245], v[4:5] op_sel_hi:[1,0]
	v_pk_fma_f32 v[252:253], v[238:239], v[4:5], v[252:253] op_sel:[0,1,0]
	v_pk_fma_f32 v[254:255], v[246:247], v[4:5], v[254:255] op_sel:[0,1,0]
	v_pk_fma_f32 v[252:253], v[240:241], v[6:7], v[252:253] op_sel_hi:[1,0,1]
	v_pk_fma_f32 v[254:255], v[248:249], v[6:7], v[254:255] op_sel_hi:[1,0,1]
	v_pk_fma_f32 v[252:253], v[242:243], v[6:7], v[252:253] op_sel:[0,1,0]
	v_pk_fma_f32 v[254:255], v[250:251], v[6:7], v[254:255] op_sel:[0,1,0]
	v_add_f32_dpp v20, v22, v21 row_ror:4 row_mask:0xf bank_mask:0xf
	v_cndmask_b32_e64 v29, v20, v28, s[64:65]
	v_cndmask_b32_e64 v30, v28, v20, s[64:65]
	v_add_f32_dpp v8, v140, v140 quad_perm:[1,0,3,2] row_mask:0xf bank_mask:0xf
	v_add_f32_dpp v9, v141, v141 quad_perm:[1,0,3,2] row_mask:0xf bank_mask:0xf
	v_add_f32_dpp v10, v142, v142 quad_perm:[1,0,3,2] row_mask:0xf bank_mask:0xf
	v_add_f32_dpp v11, v143, v143 quad_perm:[1,0,3,2] row_mask:0xf bank_mask:0xf
	v_cndmask_b32_e32 v8, v10, v8, vcc
	v_cndmask_b32_e32 v9, v11, v9, vcc
	v_add_f32_dpp v14, v12, v12 quad_perm:[2,3,0,1] row_mask:0xf bank_mask:0xf
	v_add_f32_dpp v15, v13, v13 quad_perm:[2,3,0,1] row_mask:0xf bank_mask:0xf
	v_cndmask_b32_e64 v12, v15, v14, s[4:5]
	s_waitcnt vmcnt(0)
; DI void lbar() { asm volatile("s_waitcnt lgkmcnt(0)" ::: "memory"); __builtin_amdgcn_s_barrier(); asm volatile("" ::: "memory"); }
; DI float wave_sum(float v) { for (int o = 32; o >= 1; o >>= 1) v += __shfl_xor(v, o); return v; }
; DI void attn_sample_item(const Params& p, int item, ldsp lds, int tid_) {
;     ...
;   SC_SCORE(kvA, 0)
;   SC_SCORE(kvB, 1)
;     ...
;   for (int j = 0; j < 16; ++j) vvA[j] = __builtin_nontemporal_load((const f32x4*)(cv + (size_t)(wid * 32 + j) * 1024 + lane * 4));
;   lbar();
;   if (wid < 4) {
;     float v[4]; float mx = -1e30f;
; #pragma unroll
;     for (int j = 0; j < 4; ++j) { v[j] = SC[wid * 256 + j * 64 + lane]; mx = fmaxf(mx, v[j]); }
;     for (int o = 32; o >= 1; o >>= 1) mx = fmaxf(mx, __shfl_xor(mx, o));
;     float s = 0.f;
; #pragma unroll
;     for (int j = 0; j < 4; ++j) { v[j] = __expf(v[j] - mx); s += v[j]; }
;     s = wave_sum(s); const float inv = 1.f / s;
; #pragma unroll
;     for (int j = 0; j < 4; ++j) SC[wid * 256 + j * 64 + lane] = v[j] * inv;
;   }
; #pragma unroll
;   for (int j = 0; j < 16; ++j) vvB[j] = __builtin_nontemporal_load((const f32x4*)(cv + (size_t)(wid * 32 + 16 + j) * 1024 + lane * 4));
	v_pk_mul_f32 v[140:141], v[236:237], v[0:1] op_sel_hi:[1,0]
	v_pk_mul_f32 v[142:143], v[244:245], v[0:1] op_sel_hi:[1,0]
	v_pk_fma_f32 v[140:141], v[238:239], v[0:1], v[140:141] op_sel:[0,1,0]
	v_pk_fma_f32 v[142:143], v[246:247], v[0:1], v[142:143] op_sel:[0,1,0]
	v_pk_fma_f32 v[140:141], v[240:241], v[2:3], v[140:141] op_sel_hi:[1,0,1]
	v_pk_fma_f32 v[142:143], v[248:249], v[2:3], v[142:143] op_sel_hi:[1,0,1]
	v_pk_fma_f32 v[140:141], v[242:243], v[2:3], v[140:141] op_sel:[0,1,0]
	v_pk_fma_f32 v[142:143], v[250:251], v[2:3], v[142:143] op_sel:[0,1,0]
	v_add_f32_dpp v28, v30, v29 row_ror:8 row_mask:0xf bank_mask:0xf
	v_add_f32_dpp v4, v252, v252 quad_perm:[1,0,3,2] row_mask:0xf bank_mask:0xf
	v_add_f32_dpp v5, v253, v253 quad_perm:[1,0,3,2] row_mask:0xf bank_mask:0xf
	v_add_f32_dpp v6, v254, v254 quad_perm:[1,0,3,2] row_mask:0xf bank_mask:0xf
	v_add_f32_dpp v7, v255, v255 quad_perm:[1,0,3,2] row_mask:0xf bank_mask:0xf
	v_cndmask_b32_e32 v4, v6, v4, vcc
	v_cndmask_b32_e32 v5, v7, v5, vcc
	v_add_f32_dpp v10, v8, v8 quad_perm:[2,3,0,1] row_mask:0xf bank_mask:0xf
	v_add_f32_dpp v11, v9, v9 quad_perm:[2,3,0,1] row_mask:0xf bank_mask:0xf
	v_cndmask_b32_e64 v8, v11, v10, s[4:5]
	v_cndmask_b32_e64 v13, v8, v12, s[6:7]
	v_cndmask_b32_e64 v14, v12, v8, s[6:7]
	s_nop 1
	v_add_f32_dpp v12, v14, v13 row_ror:4 row_mask:0xf bank_mask:0xf
	v_add_f32_dpp v0, v140, v140 quad_perm:[1,0,3,2] row_mask:0xf bank_mask:0xf
	v_add_f32_dpp v1, v141, v141 quad_perm:[1,0,3,2] row_mask:0xf bank_mask:0xf
	v_add_f32_dpp v2, v142, v142 quad_perm:[1,0,3,2] row_mask:0xf bank_mask:0xf
	v_add_f32_dpp v3, v143, v143 quad_perm:[1,0,3,2] row_mask:0xf bank_mask:0xf
	v_cndmask_b32_e32 v0, v2, v0, vcc
	v_cndmask_b32_e32 v1, v3, v1, vcc
	v_add_f32_dpp v6, v4, v4 quad_perm:[2,3,0,1] row_mask:0xf bank_mask:0xf
	v_add_f32_dpp v7, v5, v5 quad_perm:[2,3,0,1] row_mask:0xf bank_mask:0xf
	v_cndmask_b32_e64 v4, v7, v6, s[4:5]
	v_add_f32_dpp v2, v0, v0 quad_perm:[2,3,0,1] row_mask:0xf bank_mask:0xf
	v_add_f32_dpp v3, v1, v1 quad_perm:[2,3,0,1] row_mask:0xf bank_mask:0xf
	v_cndmask_b32_e64 v0, v3, v2, s[4:5]
	v_cndmask_b32_e64 v5, v0, v4, s[6:7]
	v_cndmask_b32_e64 v6, v4, v0, s[6:7]
	s_nop 1
	v_add_f32_dpp v4, v6, v5 row_ror:4 row_mask:0xf bank_mask:0xf
	v_cndmask_b32_e64 v13, v4, v12, s[64:65]
	v_cndmask_b32_e64 v14, v12, v4, s[64:65]
	s_nop 1
	v_add_f32_dpp v12, v14, v13 row_ror:8 row_mask:0xf bank_mask:0xf
	s_nop 1
	v_permlane16_swap_b32_e32 v28, v12
	v_add_f32_e32 v28, v28, v12
	s_nop 1
	v_permlane32_swap_b32_e32 v60, v28
	v_add_f32_e32 v60, v60, v28
	ds_write_b32 v235, v60 offset:64
	v_add_u32_e32 v100, v158, v144
	global_load_dwordx4 v[100:103], v100, s[66:67] nt
	v_add_u32_e32 v92, v162, v144
	global_load_dwordx4 v[92:95], v92, s[66:67] nt
	v_add_u32_e32 v112, v164, v144
	global_load_dwordx4 v[112:115], v112, s[66:67] nt
	v_add_u32_e32 v108, v168, v144
	global_load_dwordx4 v[108:111], v108, s[66:67] nt
	v_add_u32_e32 v120, v172, v144
	global_load_dwordx4 v[120:123], v120, s[66:67] nt
	v_add_u32_e32 v116, v176, v144
	global_load_dwordx4 v[116:119], v116, s[66:67] nt
	v_add_u32_e32 v124, v180, v144
	global_load_dwordx4 v[124:127], v124, s[66:67] nt
	v_add_u32_e32 v104, v184, v144
	global_load_dwordx4 v[104:107], v104, s[66:67] nt
	v_add_u32_e32 v68, v188, v144
	global_load_dwordx4 v[68:71], v68, s[66:67] nt
	v_add_u32_e32 v64, v192, v144
	global_load_dwordx4 v[64:67], v64, s[66:67] nt
	v_add_u32_e32 v80, v196, v144
	global_load_dwordx4 v[80:83], v80, s[66:67] nt
	v_add_u32_e32 v76, v200, v144
	global_load_dwordx4 v[76:79], v76, s[66:67] nt
	v_add_u32_e32 v88, v202, v144
	global_load_dwordx4 v[88:91], v88, s[66:67] nt
	v_add_u32_e32 v84, v204, v144
	global_load_dwordx4 v[84:87], v84, s[66:67] nt
	v_add_u32_e32 v96, v206, v144
	global_load_dwordx4 v[96:99], v96, s[66:67] nt
	v_add_u32_e32 v72, v208, v144
	global_load_dwordx4 v[72:75], v72, s[66:67] nt
	v_add_u32_e32 v40, v146, v144
	global_load_dwordx4 v[40:43], v40, s[66:67] nt
	v_add_u32_e32 v36, v148, v144
	global_load_dwordx4 v[36:39], v36, s[66:67] nt
	v_add_u32_e32 v48, v150, v144
	global_load_dwordx4 v[48:51], v48, s[66:67] nt
	v_add_u32_e32 v44, v152, v144
	global_load_dwordx4 v[44:47], v44, s[66:67] nt
	v_add_u32_e32 v56, v154, v144
	global_load_dwordx4 v[56:59], v56, s[66:67] nt
	v_add_u32_e32 v52, v156, v144
	global_load_dwordx4 v[52:55], v52, s[66:67] nt
	v_add_u32_e32 v60, v160, v144
	global_load_dwordx4 v[60:63], v60, s[66:67] nt
	v_add_u32_e32 v32, v166, v144
	global_load_dwordx4 v[32:35], v32, s[66:67] nt
	v_add_u32_e32 v12, v170, v144
	global_load_dwordx4 v[12:15], v12, s[66:67] nt
	v_add_u32_e32 v4, v174, v144
	global_load_dwordx4 v[4:7], v4, s[66:67] nt
	v_add_u32_e32 v20, v178, v144
	global_load_dwordx4 v[20:23], v20, s[66:67] nt
	v_add_u32_e32 v8, v182, v144
	global_load_dwordx4 v[8:11], v8, s[66:67] nt
	v_add_u32_e32 v24, v186, v144
	global_load_dwordx4 v[24:27], v24, s[66:67] nt
	v_add_u32_e32 v16, v190, v144
	global_load_dwordx4 v[16:19], v16, s[66:67] nt
	v_add_u32_e32 v28, v194, v144
	global_load_dwordx4 v[28:31], v28, s[66:67] nt
	v_add_u32_e32 v0, v198, v144
	global_load_dwordx4 v[0:3], v0, s[66:67] nt
	v_lshlrev_b32_e32 v240, 2, v223
	s_waitcnt lgkmcnt(0)
	s_barrier
	v_cmp_gt_i32_e32 vcc, 4, v210
	s_and_saveexec_b64 s[4:5], vcc
	s_cbranch_execz .LBB0_1675

; DI float wave_sum(float v) { for (int o = 32; o >= 1; o >>= 1) v += __shfl_xor(v, o); return v; }
; DI void attn_sample_item(const Params& p, int item, ldsp lds, int tid_) {
;     ...
;   if (wid < 4) {
;     float v[4]; float mx = -1e30f;
; #pragma unroll
;     for (int j = 0; j < 4; ++j) { v[j] = SC[wid * 256 + j * 64 + lane]; mx = fmaxf(mx, v[j]); }
;     for (int o = 32; o >= 1; o >>= 1) mx = fmaxf(mx, __shfl_xor(mx, o));
;     float s = 0.f;
; #pragma unroll
;     for (int j = 0; j < 4; ++j) { v[j] = __expf(v[j] - mx); s += v[j]; }
;     s = wave_sum(s); const float inv = 1.f / s;
; #pragma unroll
;     for (int j = 0; j < 4; ++j) SC[wid * 256 + j * 64 + lane] = v[j] * inv;
;   }
	v_lshlrev_b32_e32 v241, 10, v210
	v_add3_u32 v244, 16, v241, v240
	ds_read2st64_b32 v[240:241], v244 offset1:1
	ds_read2st64_b32 v[242:243], v244 offset0:2 offset1:3
	s_waitcnt lgkmcnt(1)
	v_max3_f32 v245, v240, s35, v241
	s_waitcnt lgkmcnt(0)
	v_max3_f32 v245, v245, v242, v243
	ds_bpermute_b32 v246, v133, v245
	s_waitcnt lgkmcnt(0)
	v_max_f32_e32 v246, v246, v246
	v_max_f32_e32 v245, v245, v246
	ds_bpermute_b32 v246, v132, v245
	s_waitcnt lgkmcnt(0)
	v_max_f32_e32 v246, v246, v246
	v_max_f32_e32 v245, v245, v246
	ds_bpermute_b32 v246, v131, v245
	s_waitcnt lgkmcnt(0)
	v_max_f32_e32 v246, v246, v246
	v_max_f32_e32 v245, v245, v246
	ds_bpermute_b32 v246, v130, v245
	s_waitcnt lgkmcnt(0)
	v_max_f32_e32 v246, v246, v246
	v_max_f32_e32 v245, v245, v246
	ds_bpermute_b32 v246, v129, v245
	s_waitcnt lgkmcnt(0)
	v_max_f32_e32 v246, v246, v246
	v_max_f32_e32 v245, v245, v246
	ds_bpermute_b32 v246, v128, v245
	s_waitcnt lgkmcnt(0)
	v_max_f32_e32 v246, v246, v246
	v_max_f32_e32 v245, v245, v246
	v_sub_f32_e32 v240, v240, v245
	v_sub_f32_e32 v241, v241, v245
	v_mul_f32_e32 v240, 0x3fb8aa3b, v240
	v_sub_f32_e32 v242, v242, v245
	v_mul_f32_e32 v241, 0x3fb8aa3b, v241
	v_exp_f32_e32 v240, v240
	v_sub_f32_e32 v243, v243, v245
	v_mul_f32_e32 v242, 0x3fb8aa3b, v242
	v_exp_f32_e32 v241, v241
	v_mul_f32_e32 v243, 0x3fb8aa3b, v243
	v_exp_f32_e32 v242, v242
	v_exp_f32_e32 v243, v243
	v_add_f32_e32 v245, 0, v240
	v_add_f32_e32 v245, v241, v245
	v_add_f32_e32 v245, v242, v245
	v_add_f32_e32 v245, v243, v245
	ds_bpermute_b32 v246, v133, v245
	s_waitcnt lgkmcnt(0)
	v_add_f32_e32 v245, v245, v246
	ds_bpermute_b32 v246, v132, v245
	s_waitcnt lgkmcnt(0)
	v_add_f32_e32 v245, v245, v246
	ds_bpermute_b32 v246, v131, v245
	s_waitcnt lgkmcnt(0)
	v_add_f32_e32 v245, v245, v246
	ds_bpermute_b32 v246, v130, v245
	s_waitcnt lgkmcnt(0)
	v_add_f32_e32 v245, v245, v246
	ds_bpermute_b32 v246, v129, v245
	s_waitcnt lgkmcnt(0)
	v_add_f32_e32 v245, v245, v246
	ds_bpermute_b32 v246, v128, v245
	s_waitcnt lgkmcnt(0)
	v_add_f32_e32 v245, v245, v246
	v_div_scale_f32 v246, s[6:7], v245, v245, 1.0
	v_rcp_f32_e32 v247, v246
	v_div_scale_f32 v248, vcc, 1.0, v245, 1.0
	v_fma_f32 v249, -v246, v247, 1.0
	v_fmac_f32_e32 v247, v249, v247
	v_mul_f32_e32 v249, v248, v247
	v_fma_f32 v250, -v246, v249, v248
	v_fmac_f32_e32 v249, v250, v247
	v_fma_f32 v246, -v246, v249, v248
	v_div_fmas_f32 v246, v246, v247, v249
	v_div_fixup_f32 v245, v246, v245, 1.0
	v_mul_f32_e32 v240, v240, v245
	v_mul_f32_e32 v241, v241, v245
	v_mul_f32_e32 v242, v242, v245
	v_mul_f32_e32 v243, v243, v245
	ds_write2st64_b32 v244, v240, v241 offset1:1
	ds_write2st64_b32 v244, v242, v243 offset0:2 offset1:3
	s_branch .LBB0_1675
